# nt also on modulation w_mod loads, combine partial-output loads and transposer bf16 stores
# speedup vs baseline: 1.0164x; 1.0049x over previous
.LBB0_74:
.LBB0_75:
	s_load_dwordx2 s[0:1], s[92:93], 0x28
	s_load_dwordx2 s[2:3], s[92:93], 0x30
	s_load_dwordx2 s[4:5], s[92:93], 0x18
	s_load_dwordx2 s[6:7], s[92:93], 0x20
	v_lshlrev_b32_e32 v1, 2, v154
	s_waitcnt lgkmcnt(0)
	s_add_u32 s12, s4, 0x0
	s_addc_u32 s13, s5, 0
	global_load_dword v32, v1, s[12:13]
	s_add_u32 s12, s4, 0x800
	s_addc_u32 s13, s5, 0
	global_load_dword v33, v1, s[12:13]
	s_add_u32 s12, s4, 0x1000
	s_addc_u32 s13, s5, 0
	global_load_dword v34, v1, s[12:13]
	s_add_u32 s12, s4, 0x1800
	s_addc_u32 s13, s5, 0
	global_load_dword v35, v1, s[12:13]
	s_add_u32 s12, s4, 0x2000
	s_addc_u32 s13, s5, 0
	global_load_dword v36, v1, s[12:13]
	s_add_u32 s12, s4, 0x2800
	s_addc_u32 s13, s5, 0
	global_load_dword v37, v1, s[12:13]
	s_add_u32 s12, s4, 0x3000
	s_addc_u32 s13, s5, 0
	global_load_dword v38, v1, s[12:13]
	s_add_u32 s12, s4, 0x3800
	s_addc_u32 s13, s5, 0
	global_load_dword v39, v1, s[12:13]
	s_add_u32 s12, s4, 0x4000
	s_addc_u32 s13, s5, 0
	global_load_dword v40, v1, s[12:13]
	s_add_u32 s12, s4, 0x4800
	s_addc_u32 s13, s5, 0
	global_load_dword v41, v1, s[12:13]
	s_add_u32 s12, s4, 0x5000
	s_addc_u32 s13, s5, 0
	global_load_dword v42, v1, s[12:13]
	s_add_u32 s12, s4, 0x5800
	s_addc_u32 s13, s5, 0
	global_load_dword v43, v1, s[12:13]
	s_add_u32 s12, s4, 0x6000
	s_addc_u32 s13, s5, 0
	global_load_dword v44, v1, s[12:13]
	s_add_u32 s12, s4, 0x6800
	s_addc_u32 s13, s5, 0
	global_load_dword v45, v1, s[12:13]
	s_add_u32 s12, s4, 0x7000
	s_addc_u32 s13, s5, 0
	global_load_dword v46, v1, s[12:13]
	s_add_u32 s12, s4, 0x7800
	s_addc_u32 s13, s5, 0
	global_load_dword v47, v1, s[12:13]
	s_add_u32 s12, s6, 0x0
	s_addc_u32 s13, s7, 0
	global_load_dword v48, v1, s[12:13]
	s_add_u32 s12, s6, 0x800
	s_addc_u32 s13, s7, 0
	global_load_dword v49, v1, s[12:13]
	s_add_u32 s12, s6, 0x1000
	s_addc_u32 s13, s7, 0
	global_load_dword v50, v1, s[12:13]
	s_add_u32 s12, s6, 0x1800
	s_addc_u32 s13, s7, 0
	global_load_dword v51, v1, s[12:13]
	v_mov_b32_e32 v2, 0xbfb8aa3b
	s_waitcnt vmcnt(0)
	v_mul_f32_e32 v3, v2, v32
	v_exp_f32_e32 v3, v3
	s_nop 0
	v_add_f32_e32 v3, 1.0, v3
	v_rcp_f32_e32 v3, v3
	s_nop 0
	v_mul_f32_e32 v3, v3, v32
	ds_write_b32 v1, v3 offset:0
	v_mul_f32_e32 v3, v2, v33
	v_exp_f32_e32 v3, v3
	s_nop 0
	v_add_f32_e32 v3, 1.0, v3
	v_rcp_f32_e32 v3, v3
	s_nop 0
	v_mul_f32_e32 v3, v3, v33
	ds_write_b32 v1, v3 offset:2048
	v_mul_f32_e32 v3, v2, v34
	v_exp_f32_e32 v3, v3
	s_nop 0
	v_add_f32_e32 v3, 1.0, v3
	v_rcp_f32_e32 v3, v3
	s_nop 0
	v_mul_f32_e32 v3, v3, v34
	ds_write_b32 v1, v3 offset:4096
	v_mul_f32_e32 v3, v2, v35
	v_exp_f32_e32 v3, v3
	s_nop 0
	v_add_f32_e32 v3, 1.0, v3
	v_rcp_f32_e32 v3, v3
	s_nop 0
	v_mul_f32_e32 v3, v3, v35
	ds_write_b32 v1, v3 offset:6144
	v_mul_f32_e32 v3, v2, v36
	v_exp_f32_e32 v3, v3
	s_nop 0
	v_add_f32_e32 v3, 1.0, v3
	v_rcp_f32_e32 v3, v3
	s_nop 0
	v_mul_f32_e32 v3, v3, v36
	ds_write_b32 v1, v3 offset:8192
	v_mul_f32_e32 v3, v2, v37
	v_exp_f32_e32 v3, v3
	s_nop 0
	v_add_f32_e32 v3, 1.0, v3
	v_rcp_f32_e32 v3, v3
	s_nop 0
	v_mul_f32_e32 v3, v3, v37
	ds_write_b32 v1, v3 offset:10240
	v_mul_f32_e32 v3, v2, v38
	v_exp_f32_e32 v3, v3
	s_nop 0
	v_add_f32_e32 v3, 1.0, v3
	v_rcp_f32_e32 v3, v3
	s_nop 0
	v_mul_f32_e32 v3, v3, v38
	ds_write_b32 v1, v3 offset:12288
	v_mul_f32_e32 v3, v2, v39
	v_exp_f32_e32 v3, v3
	s_nop 0
	v_add_f32_e32 v3, 1.0, v3
	v_rcp_f32_e32 v3, v3
	s_nop 0
	v_mul_f32_e32 v3, v3, v39
	ds_write_b32 v1, v3 offset:14336
	v_mul_f32_e32 v3, v2, v40
	v_exp_f32_e32 v3, v3
	s_nop 0
	v_add_f32_e32 v3, 1.0, v3
	v_rcp_f32_e32 v3, v3
	s_nop 0
	v_mul_f32_e32 v3, v3, v40
	ds_write_b32 v1, v3 offset:16384
	v_mul_f32_e32 v3, v2, v41
	v_exp_f32_e32 v3, v3
	s_nop 0
	v_add_f32_e32 v3, 1.0, v3
	v_rcp_f32_e32 v3, v3
	s_nop 0
	v_mul_f32_e32 v3, v3, v41
	ds_write_b32 v1, v3 offset:18432
	v_mul_f32_e32 v3, v2, v42
	v_exp_f32_e32 v3, v3
	s_nop 0
	v_add_f32_e32 v3, 1.0, v3
	v_rcp_f32_e32 v3, v3
	s_nop 0
	v_mul_f32_e32 v3, v3, v42
	ds_write_b32 v1, v3 offset:20480
	v_mul_f32_e32 v3, v2, v43
	v_exp_f32_e32 v3, v3
	s_nop 0
	v_add_f32_e32 v3, 1.0, v3
	v_rcp_f32_e32 v3, v3
	s_nop 0
	v_mul_f32_e32 v3, v3, v43
	ds_write_b32 v1, v3 offset:22528
	v_mul_f32_e32 v3, v2, v44
	v_exp_f32_e32 v3, v3
	s_nop 0
	v_add_f32_e32 v3, 1.0, v3
	v_rcp_f32_e32 v3, v3
	s_nop 0
	v_mul_f32_e32 v3, v3, v44
	ds_write_b32 v1, v3 offset:24576
	v_mul_f32_e32 v3, v2, v45
	v_exp_f32_e32 v3, v3
	s_nop 0
	v_add_f32_e32 v3, 1.0, v3
	v_rcp_f32_e32 v3, v3
	s_nop 0
	v_mul_f32_e32 v3, v3, v45
	ds_write_b32 v1, v3 offset:26624
	v_mul_f32_e32 v3, v2, v46
	v_exp_f32_e32 v3, v3
	s_nop 0
	v_add_f32_e32 v3, 1.0, v3
	v_rcp_f32_e32 v3, v3
	s_nop 0
	v_mul_f32_e32 v3, v3, v46
	ds_write_b32 v1, v3 offset:28672
	v_mul_f32_e32 v3, v2, v47
	v_exp_f32_e32 v3, v3
	s_nop 0
	v_add_f32_e32 v3, 1.0, v3
	v_rcp_f32_e32 v3, v3
	s_nop 0
	v_mul_f32_e32 v3, v3, v47
	ds_write_b32 v1, v3 offset:30720
	v_mul_f32_e32 v3, v2, v48
	v_exp_f32_e32 v3, v3
	s_nop 0
	v_add_f32_e32 v3, 1.0, v3
	v_rcp_f32_e32 v3, v3
	s_nop 0
	v_mul_f32_e32 v3, v3, v48
	ds_write_b32 v1, v3 offset:32768
	v_mul_f32_e32 v3, v2, v49
	v_exp_f32_e32 v3, v3
	s_nop 0
	v_add_f32_e32 v3, 1.0, v3
	v_rcp_f32_e32 v3, v3
	s_nop 0
	v_mul_f32_e32 v3, v3, v49
	ds_write_b32 v1, v3 offset:34816
	v_mul_f32_e32 v3, v2, v50
	v_exp_f32_e32 v3, v3
	s_nop 0
	v_add_f32_e32 v3, 1.0, v3
	v_rcp_f32_e32 v3, v3
	s_nop 0
	v_mul_f32_e32 v3, v3, v50
	ds_write_b32 v1, v3 offset:36864
	v_mul_f32_e32 v3, v2, v51
	v_exp_f32_e32 v3, v3
	s_nop 0
	v_add_f32_e32 v3, 1.0, v3
	v_rcp_f32_e32 v3, v3
	s_nop 0
	v_mul_f32_e32 v3, v3, v51
	ds_write_b32 v1, v3 offset:38912
	s_waitcnt lgkmcnt(0)
	s_barrier
	s_lshr_b32 s8, s96, 7
	s_and_b32 s9, s96, 127
	s_mul_i32 s9, s9, 96
	v_and_b32_e32 v1, 63, v154
	v_cmp_lt_u32_e32 vcc, 23, v1
	s_nop 1
	v_cndmask_b32_e64 v2, 0, 1, vcc
	v_mul_u32_u24_e32 v3, 24, v2
	v_sub_u32_e32 v3, v1, v3
	v_lshrrev_b32_e32 v4, 6, v154
	v_lshl_add_u32 v10, v4, 8, v2
	v_lshlrev_b32_e32 v10, 2, v10
	v_mul_u32_u24_e32 v11, 0xc000, v2
	v_lshl_add_u32 v11, v3, 4, v11
	v_readfirstlane_b32 s12, v4
	s_lshl_b32 s12, s12, 8
	s_lshl_b32 s13, s8, 11
	s_add_u32 s12, s12, s13
	s_mul_hi_u32 s14, s12, 0xc000
	s_mul_i32 s12, s12, 0xc000
	s_lshl_b32 s13, s9, 2
	s_add_u32 s12, s12, s13
	s_addc_u32 s14, s14, 0
	s_add_u32 s10, s0, s12
	s_addc_u32 s11, s1, s14
	v_mov_b32_e32 v12, 0
	v_mov_b32_e32 v13, 0
	v_mov_b32_e32 v14, 0
	v_mov_b32_e32 v15, 0
	v_mov_b32_e32 v16, 0
	v_mov_b32_e32 v17, 0
	v_mov_b32_e32 v18, 0
	v_mov_b32_e32 v19, 0
	v_mov_b32_e32 v20, 0
	v_mov_b32_e32 v21, 0
	v_mov_b32_e32 v22, 0
	v_mov_b32_e32 v23, 0
	v_mov_b32_e32 v24, 0
	v_mov_b32_e32 v25, 0
	v_mov_b32_e32 v26, 0
	v_mov_b32_e32 v27, 0
	v_mov_b32_e32 v28, 0
	v_mov_b32_e32 v29, 0
	v_mov_b32_e32 v30, 0
	v_mov_b32_e32 v31, 0
	s_mov_b64 s[20:21], exec
	s_mov_b32 exec_lo, -1
	s_mov_b32 exec_hi, 0xffff
	global_load_dwordx4 v[32:35], v11, s[10:11] nt
	s_add_u32 s10, s10, 0x18000
	s_addc_u32 s11, s11, 0
	global_load_dwordx4 v[36:39], v11, s[10:11] nt
	s_add_u32 s10, s10, 0x18000
	s_addc_u32 s11, s11, 0
	global_load_dwordx4 v[40:43], v11, s[10:11] nt
	s_add_u32 s10, s10, 0x18000
	s_addc_u32 s11, s11, 0
	global_load_dwordx4 v[44:47], v11, s[10:11] nt
	s_add_u32 s10, s10, 0x18000
	s_addc_u32 s11, s11, 0
	global_load_dwordx4 v[48:51], v11, s[10:11] nt
	s_add_u32 s10, s10, 0x18000
	s_addc_u32 s11, s11, 0
	global_load_dwordx4 v[52:55], v11, s[10:11] nt
	s_add_u32 s10, s10, 0x18000
	s_addc_u32 s11, s11, 0
	global_load_dwordx4 v[56:59], v11, s[10:11] nt
	s_add_u32 s10, s10, 0x18000
	s_addc_u32 s11, s11, 0
	global_load_dwordx4 v[60:63], v11, s[10:11] nt
	s_add_u32 s10, s10, 0x18000
	s_addc_u32 s11, s11, 0
	global_load_dwordx4 v[64:67], v11, s[10:11] nt
	s_add_u32 s10, s10, 0x18000
	s_addc_u32 s11, s11, 0
	global_load_dwordx4 v[68:71], v11, s[10:11] nt
	s_add_u32 s10, s10, 0x18000
	s_addc_u32 s11, s11, 0
	global_load_dwordx4 v[72:75], v11, s[10:11] nt
	s_add_u32 s10, s10, 0x18000
	s_addc_u32 s11, s11, 0
	global_load_dwordx4 v[76:79], v11, s[10:11] nt
	s_add_u32 s10, s10, 0x18000
	s_addc_u32 s11, s11, 0
	global_load_dwordx4 v[80:83], v11, s[10:11] nt
	s_add_u32 s10, s10, 0x18000
	s_addc_u32 s11, s11, 0
	global_load_dwordx4 v[84:87], v11, s[10:11] nt
	s_add_u32 s10, s10, 0x18000
	s_addc_u32 s11, s11, 0
	global_load_dwordx4 v[88:91], v11, s[10:11] nt
	s_add_u32 s10, s10, 0x18000
	s_addc_u32 s11, s11, 0
	global_load_dwordx4 v[92:95], v11, s[10:11] nt
	s_add_u32 s10, s10, 0x18000
	s_addc_u32 s11, s11, 0
	ds_read_b32 v96, v10 offset:0
	ds_read_b32 v97, v10 offset:8192
	ds_read_b32 v98, v10 offset:16384
	ds_read_b32 v99, v10 offset:24576
	ds_read_b32 v100, v10 offset:32768
	s_waitcnt vmcnt(15) lgkmcnt(0)
	v_fmac_f32_e32 v12, v96, v32
	v_fmac_f32_e32 v13, v96, v33
	v_fmac_f32_e32 v14, v96, v34
	v_fmac_f32_e32 v15, v96, v35
	v_fmac_f32_e32 v16, v97, v32
	v_fmac_f32_e32 v17, v97, v33
	v_fmac_f32_e32 v18, v97, v34
	v_fmac_f32_e32 v19, v97, v35
	v_fmac_f32_e32 v20, v98, v32
	v_fmac_f32_e32 v21, v98, v33
	v_fmac_f32_e32 v22, v98, v34
	v_fmac_f32_e32 v23, v98, v35
	v_fmac_f32_e32 v24, v99, v32
	v_fmac_f32_e32 v25, v99, v33
	v_fmac_f32_e32 v26, v99, v34
	v_fmac_f32_e32 v27, v99, v35
	v_fmac_f32_e32 v28, v100, v32
	v_fmac_f32_e32 v29, v100, v33
	v_fmac_f32_e32 v30, v100, v34
	v_fmac_f32_e32 v31, v100, v35
	global_load_dwordx4 v[32:35], v11, s[10:11] nt
	s_add_u32 s10, s10, 0x18000
	s_addc_u32 s11, s11, 0
	ds_read_b32 v96, v10 offset:8
	ds_read_b32 v97, v10 offset:8200
	ds_read_b32 v98, v10 offset:16392
	ds_read_b32 v99, v10 offset:24584
	ds_read_b32 v100, v10 offset:32776
	s_waitcnt vmcnt(15) lgkmcnt(0)
	v_fmac_f32_e32 v12, v96, v36
	v_fmac_f32_e32 v13, v96, v37
	v_fmac_f32_e32 v14, v96, v38
	v_fmac_f32_e32 v15, v96, v39
	v_fmac_f32_e32 v16, v97, v36
	v_fmac_f32_e32 v17, v97, v37
	v_fmac_f32_e32 v18, v97, v38
	v_fmac_f32_e32 v19, v97, v39
	v_fmac_f32_e32 v20, v98, v36
	v_fmac_f32_e32 v21, v98, v37
	v_fmac_f32_e32 v22, v98, v38
	v_fmac_f32_e32 v23, v98, v39
	v_fmac_f32_e32 v24, v99, v36
	v_fmac_f32_e32 v25, v99, v37
	v_fmac_f32_e32 v26, v99, v38
	v_fmac_f32_e32 v27, v99, v39
	v_fmac_f32_e32 v28, v100, v36
	v_fmac_f32_e32 v29, v100, v37
	v_fmac_f32_e32 v30, v100, v38
	v_fmac_f32_e32 v31, v100, v39
	global_load_dwordx4 v[36:39], v11, s[10:11] nt
	s_add_u32 s10, s10, 0x18000
	s_addc_u32 s11, s11, 0
	ds_read_b32 v96, v10 offset:16
	ds_read_b32 v97, v10 offset:8208
	ds_read_b32 v98, v10 offset:16400
	ds_read_b32 v99, v10 offset:24592
	ds_read_b32 v100, v10 offset:32784
	s_waitcnt vmcnt(15) lgkmcnt(0)
	v_fmac_f32_e32 v12, v96, v40
	v_fmac_f32_e32 v13, v96, v41
	v_fmac_f32_e32 v14, v96, v42
	v_fmac_f32_e32 v15, v96, v43
	v_fmac_f32_e32 v16, v97, v40
	v_fmac_f32_e32 v17, v97, v41
	v_fmac_f32_e32 v18, v97, v42
	v_fmac_f32_e32 v19, v97, v43
	v_fmac_f32_e32 v20, v98, v40
	v_fmac_f32_e32 v21, v98, v41
	v_fmac_f32_e32 v22, v98, v42
	v_fmac_f32_e32 v23, v98, v43
	v_fmac_f32_e32 v24, v99, v40
	v_fmac_f32_e32 v25, v99, v41
	v_fmac_f32_e32 v26, v99, v42
	v_fmac_f32_e32 v27, v99, v43
	v_fmac_f32_e32 v28, v100, v40
	v_fmac_f32_e32 v29, v100, v41
	v_fmac_f32_e32 v30, v100, v42
	v_fmac_f32_e32 v31, v100, v43
	global_load_dwordx4 v[40:43], v11, s[10:11] nt
	s_add_u32 s10, s10, 0x18000
	s_addc_u32 s11, s11, 0
	ds_read_b32 v96, v10 offset:24
	ds_read_b32 v97, v10 offset:8216
	ds_read_b32 v98, v10 offset:16408
	ds_read_b32 v99, v10 offset:24600
	ds_read_b32 v100, v10 offset:32792
	s_waitcnt vmcnt(15) lgkmcnt(0)
	v_fmac_f32_e32 v12, v96, v44
	v_fmac_f32_e32 v13, v96, v45
	v_fmac_f32_e32 v14, v96, v46
	v_fmac_f32_e32 v15, v96, v47
	v_fmac_f32_e32 v16, v97, v44
	v_fmac_f32_e32 v17, v97, v45
	v_fmac_f32_e32 v18, v97, v46
	v_fmac_f32_e32 v19, v97, v47
	v_fmac_f32_e32 v20, v98, v44
	v_fmac_f32_e32 v21, v98, v45
	v_fmac_f32_e32 v22, v98, v46
	v_fmac_f32_e32 v23, v98, v47
	v_fmac_f32_e32 v24, v99, v44
	v_fmac_f32_e32 v25, v99, v45
	v_fmac_f32_e32 v26, v99, v46
	v_fmac_f32_e32 v27, v99, v47
	v_fmac_f32_e32 v28, v100, v44
	v_fmac_f32_e32 v29, v100, v45
	v_fmac_f32_e32 v30, v100, v46
	v_fmac_f32_e32 v31, v100, v47
	global_load_dwordx4 v[44:47], v11, s[10:11] nt
	s_add_u32 s10, s10, 0x18000
	s_addc_u32 s11, s11, 0
	ds_read_b32 v96, v10 offset:32
	ds_read_b32 v97, v10 offset:8224
	ds_read_b32 v98, v10 offset:16416
	ds_read_b32 v99, v10 offset:24608
	ds_read_b32 v100, v10 offset:32800
	s_waitcnt vmcnt(15) lgkmcnt(0)
	v_fmac_f32_e32 v12, v96, v48
	v_fmac_f32_e32 v13, v96, v49
	v_fmac_f32_e32 v14, v96, v50
	v_fmac_f32_e32 v15, v96, v51
	v_fmac_f32_e32 v16, v97, v48
	v_fmac_f32_e32 v17, v97, v49
	v_fmac_f32_e32 v18, v97, v50
	v_fmac_f32_e32 v19, v97, v51
	v_fmac_f32_e32 v20, v98, v48
	v_fmac_f32_e32 v21, v98, v49
	v_fmac_f32_e32 v22, v98, v50
	v_fmac_f32_e32 v23, v98, v51
	v_fmac_f32_e32 v24, v99, v48
	v_fmac_f32_e32 v25, v99, v49
	v_fmac_f32_e32 v26, v99, v50
	v_fmac_f32_e32 v27, v99, v51
	v_fmac_f32_e32 v28, v100, v48
	v_fmac_f32_e32 v29, v100, v49
	v_fmac_f32_e32 v30, v100, v50
	v_fmac_f32_e32 v31, v100, v51
	global_load_dwordx4 v[48:51], v11, s[10:11] nt
	s_add_u32 s10, s10, 0x18000
	s_addc_u32 s11, s11, 0
	ds_read_b32 v96, v10 offset:40
	ds_read_b32 v97, v10 offset:8232
	ds_read_b32 v98, v10 offset:16424
	ds_read_b32 v99, v10 offset:24616
	ds_read_b32 v100, v10 offset:32808
	s_waitcnt vmcnt(15) lgkmcnt(0)
	v_fmac_f32_e32 v12, v96, v52
	v_fmac_f32_e32 v13, v96, v53
	v_fmac_f32_e32 v14, v96, v54
	v_fmac_f32_e32 v15, v96, v55
	v_fmac_f32_e32 v16, v97, v52
	v_fmac_f32_e32 v17, v97, v53
	v_fmac_f32_e32 v18, v97, v54
	v_fmac_f32_e32 v19, v97, v55
	v_fmac_f32_e32 v20, v98, v52
	v_fmac_f32_e32 v21, v98, v53
	v_fmac_f32_e32 v22, v98, v54
	v_fmac_f32_e32 v23, v98, v55
	v_fmac_f32_e32 v24, v99, v52
	v_fmac_f32_e32 v25, v99, v53
	v_fmac_f32_e32 v26, v99, v54
	v_fmac_f32_e32 v27, v99, v55
	v_fmac_f32_e32 v28, v100, v52
	v_fmac_f32_e32 v29, v100, v53
	v_fmac_f32_e32 v30, v100, v54
	v_fmac_f32_e32 v31, v100, v55
	global_load_dwordx4 v[52:55], v11, s[10:11] nt
	s_add_u32 s10, s10, 0x18000
	s_addc_u32 s11, s11, 0
	ds_read_b32 v96, v10 offset:48
	ds_read_b32 v97, v10 offset:8240
	ds_read_b32 v98, v10 offset:16432
	ds_read_b32 v99, v10 offset:24624
	ds_read_b32 v100, v10 offset:32816
	s_waitcnt vmcnt(15) lgkmcnt(0)
	v_fmac_f32_e32 v12, v96, v56
	v_fmac_f32_e32 v13, v96, v57
	v_fmac_f32_e32 v14, v96, v58
	v_fmac_f32_e32 v15, v96, v59
	v_fmac_f32_e32 v16, v97, v56
	v_fmac_f32_e32 v17, v97, v57
	v_fmac_f32_e32 v18, v97, v58
	v_fmac_f32_e32 v19, v97, v59
	v_fmac_f32_e32 v20, v98, v56
	v_fmac_f32_e32 v21, v98, v57
	v_fmac_f32_e32 v22, v98, v58
	v_fmac_f32_e32 v23, v98, v59
	v_fmac_f32_e32 v24, v99, v56
	v_fmac_f32_e32 v25, v99, v57
	v_fmac_f32_e32 v26, v99, v58
	v_fmac_f32_e32 v27, v99, v59
	v_fmac_f32_e32 v28, v100, v56
	v_fmac_f32_e32 v29, v100, v57
	v_fmac_f32_e32 v30, v100, v58
	v_fmac_f32_e32 v31, v100, v59
	global_load_dwordx4 v[56:59], v11, s[10:11] nt
	s_add_u32 s10, s10, 0x18000
	s_addc_u32 s11, s11, 0
	ds_read_b32 v96, v10 offset:56
	ds_read_b32 v97, v10 offset:8248
	ds_read_b32 v98, v10 offset:16440
	ds_read_b32 v99, v10 offset:24632
	ds_read_b32 v100, v10 offset:32824
	s_waitcnt vmcnt(15) lgkmcnt(0)
	v_fmac_f32_e32 v12, v96, v60
	v_fmac_f32_e32 v13, v96, v61
	v_fmac_f32_e32 v14, v96, v62
	v_fmac_f32_e32 v15, v96, v63
	v_fmac_f32_e32 v16, v97, v60
	v_fmac_f32_e32 v17, v97, v61
	v_fmac_f32_e32 v18, v97, v62
	v_fmac_f32_e32 v19, v97, v63
	v_fmac_f32_e32 v20, v98, v60
	v_fmac_f32_e32 v21, v98, v61
	v_fmac_f32_e32 v22, v98, v62
	v_fmac_f32_e32 v23, v98, v63
	v_fmac_f32_e32 v24, v99, v60
	v_fmac_f32_e32 v25, v99, v61
	v_fmac_f32_e32 v26, v99, v62
	v_fmac_f32_e32 v27, v99, v63
	v_fmac_f32_e32 v28, v100, v60
	v_fmac_f32_e32 v29, v100, v61
	v_fmac_f32_e32 v30, v100, v62
	v_fmac_f32_e32 v31, v100, v63
	global_load_dwordx4 v[60:63], v11, s[10:11] nt
	s_add_u32 s10, s10, 0x18000
	s_addc_u32 s11, s11, 0
	ds_read_b32 v96, v10 offset:64
	ds_read_b32 v97, v10 offset:8256
	ds_read_b32 v98, v10 offset:16448
	ds_read_b32 v99, v10 offset:24640
	ds_read_b32 v100, v10 offset:32832
	s_waitcnt vmcnt(15) lgkmcnt(0)
	v_fmac_f32_e32 v12, v96, v64
	v_fmac_f32_e32 v13, v96, v65
	v_fmac_f32_e32 v14, v96, v66
	v_fmac_f32_e32 v15, v96, v67
	v_fmac_f32_e32 v16, v97, v64
	v_fmac_f32_e32 v17, v97, v65
	v_fmac_f32_e32 v18, v97, v66
	v_fmac_f32_e32 v19, v97, v67
	v_fmac_f32_e32 v20, v98, v64
	v_fmac_f32_e32 v21, v98, v65
	v_fmac_f32_e32 v22, v98, v66
	v_fmac_f32_e32 v23, v98, v67
	v_fmac_f32_e32 v24, v99, v64
	v_fmac_f32_e32 v25, v99, v65
	v_fmac_f32_e32 v26, v99, v66
	v_fmac_f32_e32 v27, v99, v67
	v_fmac_f32_e32 v28, v100, v64
	v_fmac_f32_e32 v29, v100, v65
	v_fmac_f32_e32 v30, v100, v66
	v_fmac_f32_e32 v31, v100, v67
	global_load_dwordx4 v[64:67], v11, s[10:11] nt
	s_add_u32 s10, s10, 0x18000
	s_addc_u32 s11, s11, 0
	ds_read_b32 v96, v10 offset:72
	ds_read_b32 v97, v10 offset:8264
	ds_read_b32 v98, v10 offset:16456
	ds_read_b32 v99, v10 offset:24648
	ds_read_b32 v100, v10 offset:32840
	s_waitcnt vmcnt(15) lgkmcnt(0)
	v_fmac_f32_e32 v12, v96, v68
	v_fmac_f32_e32 v13, v96, v69
	v_fmac_f32_e32 v14, v96, v70
	v_fmac_f32_e32 v15, v96, v71
	v_fmac_f32_e32 v16, v97, v68
	v_fmac_f32_e32 v17, v97, v69
	v_fmac_f32_e32 v18, v97, v70
	v_fmac_f32_e32 v19, v97, v71
	v_fmac_f32_e32 v20, v98, v68
	v_fmac_f32_e32 v21, v98, v69
	v_fmac_f32_e32 v22, v98, v70
	v_fmac_f32_e32 v23, v98, v71
	v_fmac_f32_e32 v24, v99, v68
	v_fmac_f32_e32 v25, v99, v69
	v_fmac_f32_e32 v26, v99, v70
	v_fmac_f32_e32 v27, v99, v71
	v_fmac_f32_e32 v28, v100, v68
	v_fmac_f32_e32 v29, v100, v69
	v_fmac_f32_e32 v30, v100, v70
	v_fmac_f32_e32 v31, v100, v71
	global_load_dwordx4 v[68:71], v11, s[10:11] nt
	s_add_u32 s10, s10, 0x18000
	s_addc_u32 s11, s11, 0
	ds_read_b32 v96, v10 offset:80
	ds_read_b32 v97, v10 offset:8272
	ds_read_b32 v98, v10 offset:16464
	ds_read_b32 v99, v10 offset:24656
	ds_read_b32 v100, v10 offset:32848
	s_waitcnt vmcnt(15) lgkmcnt(0)
	v_fmac_f32_e32 v12, v96, v72
	v_fmac_f32_e32 v13, v96, v73
	v_fmac_f32_e32 v14, v96, v74
	v_fmac_f32_e32 v15, v96, v75
	v_fmac_f32_e32 v16, v97, v72
	v_fmac_f32_e32 v17, v97, v73
	v_fmac_f32_e32 v18, v97, v74
	v_fmac_f32_e32 v19, v97, v75
	v_fmac_f32_e32 v20, v98, v72
	v_fmac_f32_e32 v21, v98, v73
	v_fmac_f32_e32 v22, v98, v74
	v_fmac_f32_e32 v23, v98, v75
	v_fmac_f32_e32 v24, v99, v72
	v_fmac_f32_e32 v25, v99, v73
	v_fmac_f32_e32 v26, v99, v74
	v_fmac_f32_e32 v27, v99, v75
	v_fmac_f32_e32 v28, v100, v72
	v_fmac_f32_e32 v29, v100, v73
	v_fmac_f32_e32 v30, v100, v74
	v_fmac_f32_e32 v31, v100, v75
	global_load_dwordx4 v[72:75], v11, s[10:11] nt
	s_add_u32 s10, s10, 0x18000
	s_addc_u32 s11, s11, 0
	ds_read_b32 v96, v10 offset:88
	ds_read_b32 v97, v10 offset:8280
	ds_read_b32 v98, v10 offset:16472
	ds_read_b32 v99, v10 offset:24664
	ds_read_b32 v100, v10 offset:32856
	s_waitcnt vmcnt(15) lgkmcnt(0)
	v_fmac_f32_e32 v12, v96, v76
	v_fmac_f32_e32 v13, v96, v77
	v_fmac_f32_e32 v14, v96, v78
	v_fmac_f32_e32 v15, v96, v79
	v_fmac_f32_e32 v16, v97, v76
	v_fmac_f32_e32 v17, v97, v77
	v_fmac_f32_e32 v18, v97, v78
	v_fmac_f32_e32 v19, v97, v79
	v_fmac_f32_e32 v20, v98, v76
	v_fmac_f32_e32 v21, v98, v77
	v_fmac_f32_e32 v22, v98, v78
	v_fmac_f32_e32 v23, v98, v79
	v_fmac_f32_e32 v24, v99, v76
	v_fmac_f32_e32 v25, v99, v77
	v_fmac_f32_e32 v26, v99, v78
	v_fmac_f32_e32 v27, v99, v79
	v_fmac_f32_e32 v28, v100, v76
	v_fmac_f32_e32 v29, v100, v77
	v_fmac_f32_e32 v30, v100, v78
	v_fmac_f32_e32 v31, v100, v79
	global_load_dwordx4 v[76:79], v11, s[10:11] nt
	s_add_u32 s10, s10, 0x18000
	s_addc_u32 s11, s11, 0
	ds_read_b32 v96, v10 offset:96
	ds_read_b32 v97, v10 offset:8288
	ds_read_b32 v98, v10 offset:16480
	ds_read_b32 v99, v10 offset:24672
	ds_read_b32 v100, v10 offset:32864
	s_waitcnt vmcnt(15) lgkmcnt(0)
	v_fmac_f32_e32 v12, v96, v80
	v_fmac_f32_e32 v13, v96, v81
	v_fmac_f32_e32 v14, v96, v82
	v_fmac_f32_e32 v15, v96, v83
	v_fmac_f32_e32 v16, v97, v80
	v_fmac_f32_e32 v17, v97, v81
	v_fmac_f32_e32 v18, v97, v82
	v_fmac_f32_e32 v19, v97, v83
	v_fmac_f32_e32 v20, v98, v80
	v_fmac_f32_e32 v21, v98, v81
	v_fmac_f32_e32 v22, v98, v82
	v_fmac_f32_e32 v23, v98, v83
	v_fmac_f32_e32 v24, v99, v80
	v_fmac_f32_e32 v25, v99, v81
	v_fmac_f32_e32 v26, v99, v82
	v_fmac_f32_e32 v27, v99, v83
	v_fmac_f32_e32 v28, v100, v80
	v_fmac_f32_e32 v29, v100, v81
	v_fmac_f32_e32 v30, v100, v82
	v_fmac_f32_e32 v31, v100, v83
	global_load_dwordx4 v[80:83], v11, s[10:11] nt
	s_add_u32 s10, s10, 0x18000
	s_addc_u32 s11, s11, 0
	ds_read_b32 v96, v10 offset:104
	ds_read_b32 v97, v10 offset:8296
	ds_read_b32 v98, v10 offset:16488
	ds_read_b32 v99, v10 offset:24680
	ds_read_b32 v100, v10 offset:32872
	s_waitcnt vmcnt(15) lgkmcnt(0)
	v_fmac_f32_e32 v12, v96, v84
	v_fmac_f32_e32 v13, v96, v85
	v_fmac_f32_e32 v14, v96, v86
	v_fmac_f32_e32 v15, v96, v87
	v_fmac_f32_e32 v16, v97, v84
	v_fmac_f32_e32 v17, v97, v85
	v_fmac_f32_e32 v18, v97, v86
	v_fmac_f32_e32 v19, v97, v87
	v_fmac_f32_e32 v20, v98, v84
	v_fmac_f32_e32 v21, v98, v85
	v_fmac_f32_e32 v22, v98, v86
	v_fmac_f32_e32 v23, v98, v87
	v_fmac_f32_e32 v24, v99, v84
	v_fmac_f32_e32 v25, v99, v85
	v_fmac_f32_e32 v26, v99, v86
	v_fmac_f32_e32 v27, v99, v87
	v_fmac_f32_e32 v28, v100, v84
	v_fmac_f32_e32 v29, v100, v85
	v_fmac_f32_e32 v30, v100, v86
	v_fmac_f32_e32 v31, v100, v87
	global_load_dwordx4 v[84:87], v11, s[10:11] nt
	s_add_u32 s10, s10, 0x18000
	s_addc_u32 s11, s11, 0
	ds_read_b32 v96, v10 offset:112
	ds_read_b32 v97, v10 offset:8304
	ds_read_b32 v98, v10 offset:16496
	ds_read_b32 v99, v10 offset:24688
	ds_read_b32 v100, v10 offset:32880
	s_waitcnt vmcnt(15) lgkmcnt(0)
	v_fmac_f32_e32 v12, v96, v88
	v_fmac_f32_e32 v13, v96, v89
	v_fmac_f32_e32 v14, v96, v90
	v_fmac_f32_e32 v15, v96, v91
	v_fmac_f32_e32 v16, v97, v88
	v_fmac_f32_e32 v17, v97, v89
	v_fmac_f32_e32 v18, v97, v90
	v_fmac_f32_e32 v19, v97, v91
	v_fmac_f32_e32 v20, v98, v88
	v_fmac_f32_e32 v21, v98, v89
	v_fmac_f32_e32 v22, v98, v90
	v_fmac_f32_e32 v23, v98, v91
	v_fmac_f32_e32 v24, v99, v88
	v_fmac_f32_e32 v25, v99, v89
	v_fmac_f32_e32 v26, v99, v90
	v_fmac_f32_e32 v27, v99, v91
	v_fmac_f32_e32 v28, v100, v88
	v_fmac_f32_e32 v29, v100, v89
	v_fmac_f32_e32 v30, v100, v90
	v_fmac_f32_e32 v31, v100, v91
	global_load_dwordx4 v[88:91], v11, s[10:11] nt
	s_add_u32 s10, s10, 0x18000
	s_addc_u32 s11, s11, 0
	ds_read_b32 v96, v10 offset:120
	ds_read_b32 v97, v10 offset:8312
	ds_read_b32 v98, v10 offset:16504
	ds_read_b32 v99, v10 offset:24696
	ds_read_b32 v100, v10 offset:32888
	s_waitcnt vmcnt(15) lgkmcnt(0)
	v_fmac_f32_e32 v12, v96, v92
	v_fmac_f32_e32 v13, v96, v93
	v_fmac_f32_e32 v14, v96, v94
	v_fmac_f32_e32 v15, v96, v95
	v_fmac_f32_e32 v16, v97, v92
	v_fmac_f32_e32 v17, v97, v93
	v_fmac_f32_e32 v18, v97, v94
	v_fmac_f32_e32 v19, v97, v95
	v_fmac_f32_e32 v20, v98, v92
	v_fmac_f32_e32 v21, v98, v93
	v_fmac_f32_e32 v22, v98, v94
	v_fmac_f32_e32 v23, v98, v95
	v_fmac_f32_e32 v24, v99, v92
	v_fmac_f32_e32 v25, v99, v93
	v_fmac_f32_e32 v26, v99, v94
	v_fmac_f32_e32 v27, v99, v95
	v_fmac_f32_e32 v28, v100, v92
	v_fmac_f32_e32 v29, v100, v93
	v_fmac_f32_e32 v30, v100, v94
	v_fmac_f32_e32 v31, v100, v95
	global_load_dwordx4 v[92:95], v11, s[10:11] nt
	s_add_u32 s10, s10, 0x18000
	s_addc_u32 s11, s11, 0
	ds_read_b32 v96, v10 offset:128
	ds_read_b32 v97, v10 offset:8320
	ds_read_b32 v98, v10 offset:16512
	ds_read_b32 v99, v10 offset:24704
	ds_read_b32 v100, v10 offset:32896
	s_waitcnt vmcnt(15) lgkmcnt(0)
	v_fmac_f32_e32 v12, v96, v32
	v_fmac_f32_e32 v13, v96, v33
	v_fmac_f32_e32 v14, v96, v34
	v_fmac_f32_e32 v15, v96, v35
	v_fmac_f32_e32 v16, v97, v32
	v_fmac_f32_e32 v17, v97, v33
	v_fmac_f32_e32 v18, v97, v34
	v_fmac_f32_e32 v19, v97, v35
	v_fmac_f32_e32 v20, v98, v32
	v_fmac_f32_e32 v21, v98, v33
	v_fmac_f32_e32 v22, v98, v34
	v_fmac_f32_e32 v23, v98, v35
	v_fmac_f32_e32 v24, v99, v32
	v_fmac_f32_e32 v25, v99, v33
	v_fmac_f32_e32 v26, v99, v34
	v_fmac_f32_e32 v27, v99, v35
	v_fmac_f32_e32 v28, v100, v32
	v_fmac_f32_e32 v29, v100, v33
	v_fmac_f32_e32 v30, v100, v34
	v_fmac_f32_e32 v31, v100, v35
	global_load_dwordx4 v[32:35], v11, s[10:11] nt
	s_add_u32 s10, s10, 0x18000
	s_addc_u32 s11, s11, 0
	ds_read_b32 v96, v10 offset:136
	ds_read_b32 v97, v10 offset:8328
	ds_read_b32 v98, v10 offset:16520
	ds_read_b32 v99, v10 offset:24712
	ds_read_b32 v100, v10 offset:32904
	s_waitcnt vmcnt(15) lgkmcnt(0)
	v_fmac_f32_e32 v12, v96, v36
	v_fmac_f32_e32 v13, v96, v37
	v_fmac_f32_e32 v14, v96, v38
	v_fmac_f32_e32 v15, v96, v39
	v_fmac_f32_e32 v16, v97, v36
	v_fmac_f32_e32 v17, v97, v37
	v_fmac_f32_e32 v18, v97, v38
	v_fmac_f32_e32 v19, v97, v39
	v_fmac_f32_e32 v20, v98, v36
	v_fmac_f32_e32 v21, v98, v37
	v_fmac_f32_e32 v22, v98, v38
	v_fmac_f32_e32 v23, v98, v39
	v_fmac_f32_e32 v24, v99, v36
	v_fmac_f32_e32 v25, v99, v37
	v_fmac_f32_e32 v26, v99, v38
	v_fmac_f32_e32 v27, v99, v39
	v_fmac_f32_e32 v28, v100, v36
	v_fmac_f32_e32 v29, v100, v37
	v_fmac_f32_e32 v30, v100, v38
	v_fmac_f32_e32 v31, v100, v39
	global_load_dwordx4 v[36:39], v11, s[10:11] nt
	s_add_u32 s10, s10, 0x18000
	s_addc_u32 s11, s11, 0
	ds_read_b32 v96, v10 offset:144
	ds_read_b32 v97, v10 offset:8336
	ds_read_b32 v98, v10 offset:16528
	ds_read_b32 v99, v10 offset:24720
	ds_read_b32 v100, v10 offset:32912
	s_waitcnt vmcnt(15) lgkmcnt(0)
	v_fmac_f32_e32 v12, v96, v40
	v_fmac_f32_e32 v13, v96, v41
	v_fmac_f32_e32 v14, v96, v42
	v_fmac_f32_e32 v15, v96, v43
	v_fmac_f32_e32 v16, v97, v40
	v_fmac_f32_e32 v17, v97, v41
	v_fmac_f32_e32 v18, v97, v42
	v_fmac_f32_e32 v19, v97, v43
	v_fmac_f32_e32 v20, v98, v40
	v_fmac_f32_e32 v21, v98, v41
	v_fmac_f32_e32 v22, v98, v42
	v_fmac_f32_e32 v23, v98, v43
	v_fmac_f32_e32 v24, v99, v40
	v_fmac_f32_e32 v25, v99, v41
	v_fmac_f32_e32 v26, v99, v42
	v_fmac_f32_e32 v27, v99, v43
	v_fmac_f32_e32 v28, v100, v40
	v_fmac_f32_e32 v29, v100, v41
	v_fmac_f32_e32 v30, v100, v42
	v_fmac_f32_e32 v31, v100, v43
	global_load_dwordx4 v[40:43], v11, s[10:11] nt
	s_add_u32 s10, s10, 0x18000
	s_addc_u32 s11, s11, 0
	ds_read_b32 v96, v10 offset:152
	ds_read_b32 v97, v10 offset:8344
	ds_read_b32 v98, v10 offset:16536
	ds_read_b32 v99, v10 offset:24728
	ds_read_b32 v100, v10 offset:32920
	s_waitcnt vmcnt(15) lgkmcnt(0)
	v_fmac_f32_e32 v12, v96, v44
	v_fmac_f32_e32 v13, v96, v45
	v_fmac_f32_e32 v14, v96, v46
	v_fmac_f32_e32 v15, v96, v47
	v_fmac_f32_e32 v16, v97, v44
	v_fmac_f32_e32 v17, v97, v45
	v_fmac_f32_e32 v18, v97, v46
	v_fmac_f32_e32 v19, v97, v47
	v_fmac_f32_e32 v20, v98, v44
	v_fmac_f32_e32 v21, v98, v45
	v_fmac_f32_e32 v22, v98, v46
	v_fmac_f32_e32 v23, v98, v47
	v_fmac_f32_e32 v24, v99, v44
	v_fmac_f32_e32 v25, v99, v45
	v_fmac_f32_e32 v26, v99, v46
	v_fmac_f32_e32 v27, v99, v47
	v_fmac_f32_e32 v28, v100, v44
	v_fmac_f32_e32 v29, v100, v45
	v_fmac_f32_e32 v30, v100, v46
	v_fmac_f32_e32 v31, v100, v47
	global_load_dwordx4 v[44:47], v11, s[10:11] nt
	s_add_u32 s10, s10, 0x18000
	s_addc_u32 s11, s11, 0
	ds_read_b32 v96, v10 offset:160
	ds_read_b32 v97, v10 offset:8352
	ds_read_b32 v98, v10 offset:16544
	ds_read_b32 v99, v10 offset:24736
	ds_read_b32 v100, v10 offset:32928
	s_waitcnt vmcnt(15) lgkmcnt(0)
	v_fmac_f32_e32 v12, v96, v48
	v_fmac_f32_e32 v13, v96, v49
	v_fmac_f32_e32 v14, v96, v50
	v_fmac_f32_e32 v15, v96, v51
	v_fmac_f32_e32 v16, v97, v48
	v_fmac_f32_e32 v17, v97, v49
	v_fmac_f32_e32 v18, v97, v50
	v_fmac_f32_e32 v19, v97, v51
	v_fmac_f32_e32 v20, v98, v48
	v_fmac_f32_e32 v21, v98, v49
	v_fmac_f32_e32 v22, v98, v50
	v_fmac_f32_e32 v23, v98, v51
	v_fmac_f32_e32 v24, v99, v48
	v_fmac_f32_e32 v25, v99, v49
	v_fmac_f32_e32 v26, v99, v50
	v_fmac_f32_e32 v27, v99, v51
	v_fmac_f32_e32 v28, v100, v48
	v_fmac_f32_e32 v29, v100, v49
	v_fmac_f32_e32 v30, v100, v50
	v_fmac_f32_e32 v31, v100, v51
	global_load_dwordx4 v[48:51], v11, s[10:11] nt
	s_add_u32 s10, s10, 0x18000
	s_addc_u32 s11, s11, 0
	ds_read_b32 v96, v10 offset:168
	ds_read_b32 v97, v10 offset:8360
	ds_read_b32 v98, v10 offset:16552
	ds_read_b32 v99, v10 offset:24744
	ds_read_b32 v100, v10 offset:32936
	s_waitcnt vmcnt(15) lgkmcnt(0)
	v_fmac_f32_e32 v12, v96, v52
	v_fmac_f32_e32 v13, v96, v53
	v_fmac_f32_e32 v14, v96, v54
	v_fmac_f32_e32 v15, v96, v55
	v_fmac_f32_e32 v16, v97, v52
	v_fmac_f32_e32 v17, v97, v53
	v_fmac_f32_e32 v18, v97, v54
	v_fmac_f32_e32 v19, v97, v55
	v_fmac_f32_e32 v20, v98, v52
	v_fmac_f32_e32 v21, v98, v53
	v_fmac_f32_e32 v22, v98, v54
	v_fmac_f32_e32 v23, v98, v55
	v_fmac_f32_e32 v24, v99, v52
	v_fmac_f32_e32 v25, v99, v53
	v_fmac_f32_e32 v26, v99, v54
	v_fmac_f32_e32 v27, v99, v55
	v_fmac_f32_e32 v28, v100, v52
	v_fmac_f32_e32 v29, v100, v53
	v_fmac_f32_e32 v30, v100, v54
	v_fmac_f32_e32 v31, v100, v55
	global_load_dwordx4 v[52:55], v11, s[10:11] nt
	s_add_u32 s10, s10, 0x18000
	s_addc_u32 s11, s11, 0
	ds_read_b32 v96, v10 offset:176
	ds_read_b32 v97, v10 offset:8368
	ds_read_b32 v98, v10 offset:16560
	ds_read_b32 v99, v10 offset:24752
	ds_read_b32 v100, v10 offset:32944
	s_waitcnt vmcnt(15) lgkmcnt(0)
	v_fmac_f32_e32 v12, v96, v56
	v_fmac_f32_e32 v13, v96, v57
	v_fmac_f32_e32 v14, v96, v58
	v_fmac_f32_e32 v15, v96, v59
	v_fmac_f32_e32 v16, v97, v56
	v_fmac_f32_e32 v17, v97, v57
	v_fmac_f32_e32 v18, v97, v58
	v_fmac_f32_e32 v19, v97, v59
	v_fmac_f32_e32 v20, v98, v56
	v_fmac_f32_e32 v21, v98, v57
	v_fmac_f32_e32 v22, v98, v58
	v_fmac_f32_e32 v23, v98, v59
	v_fmac_f32_e32 v24, v99, v56
	v_fmac_f32_e32 v25, v99, v57
	v_fmac_f32_e32 v26, v99, v58
	v_fmac_f32_e32 v27, v99, v59
	v_fmac_f32_e32 v28, v100, v56
	v_fmac_f32_e32 v29, v100, v57
	v_fmac_f32_e32 v30, v100, v58
	v_fmac_f32_e32 v31, v100, v59
	global_load_dwordx4 v[56:59], v11, s[10:11] nt
	s_add_u32 s10, s10, 0x18000
	s_addc_u32 s11, s11, 0
	ds_read_b32 v96, v10 offset:184
	ds_read_b32 v97, v10 offset:8376
	ds_read_b32 v98, v10 offset:16568
	ds_read_b32 v99, v10 offset:24760
	ds_read_b32 v100, v10 offset:32952
	s_waitcnt vmcnt(15) lgkmcnt(0)
	v_fmac_f32_e32 v12, v96, v60
	v_fmac_f32_e32 v13, v96, v61
	v_fmac_f32_e32 v14, v96, v62
	v_fmac_f32_e32 v15, v96, v63
	v_fmac_f32_e32 v16, v97, v60
	v_fmac_f32_e32 v17, v97, v61
	v_fmac_f32_e32 v18, v97, v62
	v_fmac_f32_e32 v19, v97, v63
	v_fmac_f32_e32 v20, v98, v60
	v_fmac_f32_e32 v21, v98, v61
	v_fmac_f32_e32 v22, v98, v62
	v_fmac_f32_e32 v23, v98, v63
	v_fmac_f32_e32 v24, v99, v60
	v_fmac_f32_e32 v25, v99, v61
	v_fmac_f32_e32 v26, v99, v62
	v_fmac_f32_e32 v27, v99, v63
	v_fmac_f32_e32 v28, v100, v60
	v_fmac_f32_e32 v29, v100, v61
	v_fmac_f32_e32 v30, v100, v62
	v_fmac_f32_e32 v31, v100, v63
	global_load_dwordx4 v[60:63], v11, s[10:11] nt
	s_add_u32 s10, s10, 0x18000
	s_addc_u32 s11, s11, 0
	ds_read_b32 v96, v10 offset:192
	ds_read_b32 v97, v10 offset:8384
	ds_read_b32 v98, v10 offset:16576
	ds_read_b32 v99, v10 offset:24768
	ds_read_b32 v100, v10 offset:32960
	s_waitcnt vmcnt(15) lgkmcnt(0)
	v_fmac_f32_e32 v12, v96, v64
	v_fmac_f32_e32 v13, v96, v65
	v_fmac_f32_e32 v14, v96, v66
	v_fmac_f32_e32 v15, v96, v67
	v_fmac_f32_e32 v16, v97, v64
	v_fmac_f32_e32 v17, v97, v65
	v_fmac_f32_e32 v18, v97, v66
	v_fmac_f32_e32 v19, v97, v67
	v_fmac_f32_e32 v20, v98, v64
	v_fmac_f32_e32 v21, v98, v65
	v_fmac_f32_e32 v22, v98, v66
	v_fmac_f32_e32 v23, v98, v67
	v_fmac_f32_e32 v24, v99, v64
	v_fmac_f32_e32 v25, v99, v65
	v_fmac_f32_e32 v26, v99, v66
	v_fmac_f32_e32 v27, v99, v67
	v_fmac_f32_e32 v28, v100, v64
	v_fmac_f32_e32 v29, v100, v65
	v_fmac_f32_e32 v30, v100, v66
	v_fmac_f32_e32 v31, v100, v67
	global_load_dwordx4 v[64:67], v11, s[10:11] nt
	s_add_u32 s10, s10, 0x18000
	s_addc_u32 s11, s11, 0
	ds_read_b32 v96, v10 offset:200
	ds_read_b32 v97, v10 offset:8392
	ds_read_b32 v98, v10 offset:16584
	ds_read_b32 v99, v10 offset:24776
	ds_read_b32 v100, v10 offset:32968
	s_waitcnt vmcnt(15) lgkmcnt(0)
	v_fmac_f32_e32 v12, v96, v68
	v_fmac_f32_e32 v13, v96, v69
	v_fmac_f32_e32 v14, v96, v70
	v_fmac_f32_e32 v15, v96, v71
	v_fmac_f32_e32 v16, v97, v68
	v_fmac_f32_e32 v17, v97, v69
	v_fmac_f32_e32 v18, v97, v70
	v_fmac_f32_e32 v19, v97, v71
	v_fmac_f32_e32 v20, v98, v68
	v_fmac_f32_e32 v21, v98, v69
	v_fmac_f32_e32 v22, v98, v70
	v_fmac_f32_e32 v23, v98, v71
	v_fmac_f32_e32 v24, v99, v68
	v_fmac_f32_e32 v25, v99, v69
	v_fmac_f32_e32 v26, v99, v70
	v_fmac_f32_e32 v27, v99, v71
	v_fmac_f32_e32 v28, v100, v68
	v_fmac_f32_e32 v29, v100, v69
	v_fmac_f32_e32 v30, v100, v70
	v_fmac_f32_e32 v31, v100, v71
	global_load_dwordx4 v[68:71], v11, s[10:11] nt
	s_add_u32 s10, s10, 0x18000
	s_addc_u32 s11, s11, 0
	ds_read_b32 v96, v10 offset:208
	ds_read_b32 v97, v10 offset:8400
	ds_read_b32 v98, v10 offset:16592
	ds_read_b32 v99, v10 offset:24784
	ds_read_b32 v100, v10 offset:32976
	s_waitcnt vmcnt(15) lgkmcnt(0)
	v_fmac_f32_e32 v12, v96, v72
	v_fmac_f32_e32 v13, v96, v73
	v_fmac_f32_e32 v14, v96, v74
	v_fmac_f32_e32 v15, v96, v75
	v_fmac_f32_e32 v16, v97, v72
	v_fmac_f32_e32 v17, v97, v73
	v_fmac_f32_e32 v18, v97, v74
	v_fmac_f32_e32 v19, v97, v75
	v_fmac_f32_e32 v20, v98, v72
	v_fmac_f32_e32 v21, v98, v73
	v_fmac_f32_e32 v22, v98, v74
	v_fmac_f32_e32 v23, v98, v75
	v_fmac_f32_e32 v24, v99, v72
	v_fmac_f32_e32 v25, v99, v73
	v_fmac_f32_e32 v26, v99, v74
	v_fmac_f32_e32 v27, v99, v75
	v_fmac_f32_e32 v28, v100, v72
	v_fmac_f32_e32 v29, v100, v73
	v_fmac_f32_e32 v30, v100, v74
	v_fmac_f32_e32 v31, v100, v75
	global_load_dwordx4 v[72:75], v11, s[10:11] nt
	s_add_u32 s10, s10, 0x18000
	s_addc_u32 s11, s11, 0
	ds_read_b32 v96, v10 offset:216
	ds_read_b32 v97, v10 offset:8408
	ds_read_b32 v98, v10 offset:16600
	ds_read_b32 v99, v10 offset:24792
	ds_read_b32 v100, v10 offset:32984
	s_waitcnt vmcnt(15) lgkmcnt(0)
	v_fmac_f32_e32 v12, v96, v76
	v_fmac_f32_e32 v13, v96, v77
	v_fmac_f32_e32 v14, v96, v78
	v_fmac_f32_e32 v15, v96, v79
	v_fmac_f32_e32 v16, v97, v76
	v_fmac_f32_e32 v17, v97, v77
	v_fmac_f32_e32 v18, v97, v78
	v_fmac_f32_e32 v19, v97, v79
	v_fmac_f32_e32 v20, v98, v76
	v_fmac_f32_e32 v21, v98, v77
	v_fmac_f32_e32 v22, v98, v78
	v_fmac_f32_e32 v23, v98, v79
	v_fmac_f32_e32 v24, v99, v76
	v_fmac_f32_e32 v25, v99, v77
	v_fmac_f32_e32 v26, v99, v78
	v_fmac_f32_e32 v27, v99, v79
	v_fmac_f32_e32 v28, v100, v76
	v_fmac_f32_e32 v29, v100, v77
	v_fmac_f32_e32 v30, v100, v78
	v_fmac_f32_e32 v31, v100, v79
	global_load_dwordx4 v[76:79], v11, s[10:11] nt
	s_add_u32 s10, s10, 0x18000
	s_addc_u32 s11, s11, 0
	ds_read_b32 v96, v10 offset:224
	ds_read_b32 v97, v10 offset:8416
	ds_read_b32 v98, v10 offset:16608
	ds_read_b32 v99, v10 offset:24800
	ds_read_b32 v100, v10 offset:32992
	s_waitcnt vmcnt(15) lgkmcnt(0)
	v_fmac_f32_e32 v12, v96, v80
	v_fmac_f32_e32 v13, v96, v81
	v_fmac_f32_e32 v14, v96, v82
	v_fmac_f32_e32 v15, v96, v83
	v_fmac_f32_e32 v16, v97, v80
	v_fmac_f32_e32 v17, v97, v81
	v_fmac_f32_e32 v18, v97, v82
	v_fmac_f32_e32 v19, v97, v83
	v_fmac_f32_e32 v20, v98, v80
	v_fmac_f32_e32 v21, v98, v81
	v_fmac_f32_e32 v22, v98, v82
	v_fmac_f32_e32 v23, v98, v83
	v_fmac_f32_e32 v24, v99, v80
	v_fmac_f32_e32 v25, v99, v81
	v_fmac_f32_e32 v26, v99, v82
	v_fmac_f32_e32 v27, v99, v83
	v_fmac_f32_e32 v28, v100, v80
	v_fmac_f32_e32 v29, v100, v81
	v_fmac_f32_e32 v30, v100, v82
	v_fmac_f32_e32 v31, v100, v83
	global_load_dwordx4 v[80:83], v11, s[10:11] nt
	s_add_u32 s10, s10, 0x18000
	s_addc_u32 s11, s11, 0
	ds_read_b32 v96, v10 offset:232
	ds_read_b32 v97, v10 offset:8424
	ds_read_b32 v98, v10 offset:16616
	ds_read_b32 v99, v10 offset:24808
	ds_read_b32 v100, v10 offset:33000
	s_waitcnt vmcnt(15) lgkmcnt(0)
	v_fmac_f32_e32 v12, v96, v84
	v_fmac_f32_e32 v13, v96, v85
	v_fmac_f32_e32 v14, v96, v86
	v_fmac_f32_e32 v15, v96, v87
	v_fmac_f32_e32 v16, v97, v84
	v_fmac_f32_e32 v17, v97, v85
	v_fmac_f32_e32 v18, v97, v86
	v_fmac_f32_e32 v19, v97, v87
	v_fmac_f32_e32 v20, v98, v84
	v_fmac_f32_e32 v21, v98, v85
	v_fmac_f32_e32 v22, v98, v86
	v_fmac_f32_e32 v23, v98, v87
	v_fmac_f32_e32 v24, v99, v84
	v_fmac_f32_e32 v25, v99, v85
	v_fmac_f32_e32 v26, v99, v86
	v_fmac_f32_e32 v27, v99, v87
	v_fmac_f32_e32 v28, v100, v84
	v_fmac_f32_e32 v29, v100, v85
	v_fmac_f32_e32 v30, v100, v86
	v_fmac_f32_e32 v31, v100, v87
	global_load_dwordx4 v[84:87], v11, s[10:11] nt
	s_add_u32 s10, s10, 0x18000
	s_addc_u32 s11, s11, 0
	ds_read_b32 v96, v10 offset:240
	ds_read_b32 v97, v10 offset:8432
	ds_read_b32 v98, v10 offset:16624
	ds_read_b32 v99, v10 offset:24816
	ds_read_b32 v100, v10 offset:33008
	s_waitcnt vmcnt(15) lgkmcnt(0)
	v_fmac_f32_e32 v12, v96, v88
	v_fmac_f32_e32 v13, v96, v89
	v_fmac_f32_e32 v14, v96, v90
	v_fmac_f32_e32 v15, v96, v91
	v_fmac_f32_e32 v16, v97, v88
	v_fmac_f32_e32 v17, v97, v89
	v_fmac_f32_e32 v18, v97, v90
	v_fmac_f32_e32 v19, v97, v91
	v_fmac_f32_e32 v20, v98, v88
	v_fmac_f32_e32 v21, v98, v89
	v_fmac_f32_e32 v22, v98, v90
	v_fmac_f32_e32 v23, v98, v91
	v_fmac_f32_e32 v24, v99, v88
	v_fmac_f32_e32 v25, v99, v89
	v_fmac_f32_e32 v26, v99, v90
	v_fmac_f32_e32 v27, v99, v91
	v_fmac_f32_e32 v28, v100, v88
	v_fmac_f32_e32 v29, v100, v89
	v_fmac_f32_e32 v30, v100, v90
	v_fmac_f32_e32 v31, v100, v91
	global_load_dwordx4 v[88:91], v11, s[10:11] nt
	s_add_u32 s10, s10, 0x18000
	s_addc_u32 s11, s11, 0
	ds_read_b32 v96, v10 offset:248
	ds_read_b32 v97, v10 offset:8440
	ds_read_b32 v98, v10 offset:16632
	ds_read_b32 v99, v10 offset:24824
	ds_read_b32 v100, v10 offset:33016
	s_waitcnt vmcnt(15) lgkmcnt(0)
	v_fmac_f32_e32 v12, v96, v92
	v_fmac_f32_e32 v13, v96, v93
	v_fmac_f32_e32 v14, v96, v94
	v_fmac_f32_e32 v15, v96, v95
	v_fmac_f32_e32 v16, v97, v92
	v_fmac_f32_e32 v17, v97, v93
	v_fmac_f32_e32 v18, v97, v94
	v_fmac_f32_e32 v19, v97, v95
	v_fmac_f32_e32 v20, v98, v92
	v_fmac_f32_e32 v21, v98, v93
	v_fmac_f32_e32 v22, v98, v94
	v_fmac_f32_e32 v23, v98, v95
	v_fmac_f32_e32 v24, v99, v92
	v_fmac_f32_e32 v25, v99, v93
	v_fmac_f32_e32 v26, v99, v94
	v_fmac_f32_e32 v27, v99, v95
	v_fmac_f32_e32 v28, v100, v92
	v_fmac_f32_e32 v29, v100, v93
	v_fmac_f32_e32 v30, v100, v94
	v_fmac_f32_e32 v31, v100, v95
	global_load_dwordx4 v[92:95], v11, s[10:11] nt
	s_add_u32 s10, s10, 0x18000
	s_addc_u32 s11, s11, 0
	ds_read_b32 v96, v10 offset:256
	ds_read_b32 v97, v10 offset:8448
	ds_read_b32 v98, v10 offset:16640
	ds_read_b32 v99, v10 offset:24832
	ds_read_b32 v100, v10 offset:33024
	s_waitcnt vmcnt(15) lgkmcnt(0)
	v_fmac_f32_e32 v12, v96, v32
	v_fmac_f32_e32 v13, v96, v33
	v_fmac_f32_e32 v14, v96, v34
	v_fmac_f32_e32 v15, v96, v35
	v_fmac_f32_e32 v16, v97, v32
	v_fmac_f32_e32 v17, v97, v33
	v_fmac_f32_e32 v18, v97, v34
	v_fmac_f32_e32 v19, v97, v35
	v_fmac_f32_e32 v20, v98, v32
	v_fmac_f32_e32 v21, v98, v33
	v_fmac_f32_e32 v22, v98, v34
	v_fmac_f32_e32 v23, v98, v35
	v_fmac_f32_e32 v24, v99, v32
	v_fmac_f32_e32 v25, v99, v33
	v_fmac_f32_e32 v26, v99, v34
	v_fmac_f32_e32 v27, v99, v35
	v_fmac_f32_e32 v28, v100, v32
	v_fmac_f32_e32 v29, v100, v33
	v_fmac_f32_e32 v30, v100, v34
	v_fmac_f32_e32 v31, v100, v35
	global_load_dwordx4 v[32:35], v11, s[10:11] nt
	s_add_u32 s10, s10, 0x18000
	s_addc_u32 s11, s11, 0
	ds_read_b32 v96, v10 offset:264
	ds_read_b32 v97, v10 offset:8456
	ds_read_b32 v98, v10 offset:16648
	ds_read_b32 v99, v10 offset:24840
	ds_read_b32 v100, v10 offset:33032
	s_waitcnt vmcnt(15) lgkmcnt(0)
	v_fmac_f32_e32 v12, v96, v36
	v_fmac_f32_e32 v13, v96, v37
	v_fmac_f32_e32 v14, v96, v38
	v_fmac_f32_e32 v15, v96, v39
	v_fmac_f32_e32 v16, v97, v36
	v_fmac_f32_e32 v17, v97, v37
	v_fmac_f32_e32 v18, v97, v38
	v_fmac_f32_e32 v19, v97, v39
	v_fmac_f32_e32 v20, v98, v36
	v_fmac_f32_e32 v21, v98, v37
	v_fmac_f32_e32 v22, v98, v38
	v_fmac_f32_e32 v23, v98, v39
	v_fmac_f32_e32 v24, v99, v36
	v_fmac_f32_e32 v25, v99, v37
	v_fmac_f32_e32 v26, v99, v38
	v_fmac_f32_e32 v27, v99, v39
	v_fmac_f32_e32 v28, v100, v36
	v_fmac_f32_e32 v29, v100, v37
	v_fmac_f32_e32 v30, v100, v38
	v_fmac_f32_e32 v31, v100, v39
	global_load_dwordx4 v[36:39], v11, s[10:11] nt
	s_add_u32 s10, s10, 0x18000
	s_addc_u32 s11, s11, 0
	ds_read_b32 v96, v10 offset:272
	ds_read_b32 v97, v10 offset:8464
	ds_read_b32 v98, v10 offset:16656
	ds_read_b32 v99, v10 offset:24848
	ds_read_b32 v100, v10 offset:33040
	s_waitcnt vmcnt(15) lgkmcnt(0)
	v_fmac_f32_e32 v12, v96, v40
	v_fmac_f32_e32 v13, v96, v41
	v_fmac_f32_e32 v14, v96, v42
	v_fmac_f32_e32 v15, v96, v43
	v_fmac_f32_e32 v16, v97, v40
	v_fmac_f32_e32 v17, v97, v41
	v_fmac_f32_e32 v18, v97, v42
	v_fmac_f32_e32 v19, v97, v43
	v_fmac_f32_e32 v20, v98, v40
	v_fmac_f32_e32 v21, v98, v41
	v_fmac_f32_e32 v22, v98, v42
	v_fmac_f32_e32 v23, v98, v43
	v_fmac_f32_e32 v24, v99, v40
	v_fmac_f32_e32 v25, v99, v41
	v_fmac_f32_e32 v26, v99, v42
	v_fmac_f32_e32 v27, v99, v43
	v_fmac_f32_e32 v28, v100, v40
	v_fmac_f32_e32 v29, v100, v41
	v_fmac_f32_e32 v30, v100, v42
	v_fmac_f32_e32 v31, v100, v43
	global_load_dwordx4 v[40:43], v11, s[10:11] nt
	s_add_u32 s10, s10, 0x18000
	s_addc_u32 s11, s11, 0
	ds_read_b32 v96, v10 offset:280
	ds_read_b32 v97, v10 offset:8472
	ds_read_b32 v98, v10 offset:16664
	ds_read_b32 v99, v10 offset:24856
	ds_read_b32 v100, v10 offset:33048
	s_waitcnt vmcnt(15) lgkmcnt(0)
	v_fmac_f32_e32 v12, v96, v44
	v_fmac_f32_e32 v13, v96, v45
	v_fmac_f32_e32 v14, v96, v46
	v_fmac_f32_e32 v15, v96, v47
	v_fmac_f32_e32 v16, v97, v44
	v_fmac_f32_e32 v17, v97, v45
	v_fmac_f32_e32 v18, v97, v46
	v_fmac_f32_e32 v19, v97, v47
	v_fmac_f32_e32 v20, v98, v44
	v_fmac_f32_e32 v21, v98, v45
	v_fmac_f32_e32 v22, v98, v46
	v_fmac_f32_e32 v23, v98, v47
	v_fmac_f32_e32 v24, v99, v44
	v_fmac_f32_e32 v25, v99, v45
	v_fmac_f32_e32 v26, v99, v46
	v_fmac_f32_e32 v27, v99, v47
	v_fmac_f32_e32 v28, v100, v44
	v_fmac_f32_e32 v29, v100, v45
	v_fmac_f32_e32 v30, v100, v46
	v_fmac_f32_e32 v31, v100, v47
	global_load_dwordx4 v[44:47], v11, s[10:11] nt
	s_add_u32 s10, s10, 0x18000
	s_addc_u32 s11, s11, 0
	ds_read_b32 v96, v10 offset:288
	ds_read_b32 v97, v10 offset:8480
	ds_read_b32 v98, v10 offset:16672
	ds_read_b32 v99, v10 offset:24864
	ds_read_b32 v100, v10 offset:33056
	s_waitcnt vmcnt(15) lgkmcnt(0)
	v_fmac_f32_e32 v12, v96, v48
	v_fmac_f32_e32 v13, v96, v49
	v_fmac_f32_e32 v14, v96, v50
	v_fmac_f32_e32 v15, v96, v51
	v_fmac_f32_e32 v16, v97, v48
	v_fmac_f32_e32 v17, v97, v49
	v_fmac_f32_e32 v18, v97, v50
	v_fmac_f32_e32 v19, v97, v51
	v_fmac_f32_e32 v20, v98, v48
	v_fmac_f32_e32 v21, v98, v49
	v_fmac_f32_e32 v22, v98, v50
	v_fmac_f32_e32 v23, v98, v51
	v_fmac_f32_e32 v24, v99, v48
	v_fmac_f32_e32 v25, v99, v49
	v_fmac_f32_e32 v26, v99, v50
	v_fmac_f32_e32 v27, v99, v51
	v_fmac_f32_e32 v28, v100, v48
	v_fmac_f32_e32 v29, v100, v49
	v_fmac_f32_e32 v30, v100, v50
	v_fmac_f32_e32 v31, v100, v51
	global_load_dwordx4 v[48:51], v11, s[10:11] nt
	s_add_u32 s10, s10, 0x18000
	s_addc_u32 s11, s11, 0
	ds_read_b32 v96, v10 offset:296
	ds_read_b32 v97, v10 offset:8488
	ds_read_b32 v98, v10 offset:16680
	ds_read_b32 v99, v10 offset:24872
	ds_read_b32 v100, v10 offset:33064
	s_waitcnt vmcnt(15) lgkmcnt(0)
	v_fmac_f32_e32 v12, v96, v52
	v_fmac_f32_e32 v13, v96, v53
	v_fmac_f32_e32 v14, v96, v54
	v_fmac_f32_e32 v15, v96, v55
	v_fmac_f32_e32 v16, v97, v52
	v_fmac_f32_e32 v17, v97, v53
	v_fmac_f32_e32 v18, v97, v54
	v_fmac_f32_e32 v19, v97, v55
	v_fmac_f32_e32 v20, v98, v52
	v_fmac_f32_e32 v21, v98, v53
	v_fmac_f32_e32 v22, v98, v54
	v_fmac_f32_e32 v23, v98, v55
	v_fmac_f32_e32 v24, v99, v52
	v_fmac_f32_e32 v25, v99, v53
	v_fmac_f32_e32 v26, v99, v54
	v_fmac_f32_e32 v27, v99, v55
	v_fmac_f32_e32 v28, v100, v52
	v_fmac_f32_e32 v29, v100, v53
	v_fmac_f32_e32 v30, v100, v54
	v_fmac_f32_e32 v31, v100, v55
	global_load_dwordx4 v[52:55], v11, s[10:11] nt
	s_add_u32 s10, s10, 0x18000
	s_addc_u32 s11, s11, 0
	ds_read_b32 v96, v10 offset:304
	ds_read_b32 v97, v10 offset:8496
	ds_read_b32 v98, v10 offset:16688
	ds_read_b32 v99, v10 offset:24880
	ds_read_b32 v100, v10 offset:33072
	s_waitcnt vmcnt(15) lgkmcnt(0)
	v_fmac_f32_e32 v12, v96, v56
	v_fmac_f32_e32 v13, v96, v57
	v_fmac_f32_e32 v14, v96, v58
	v_fmac_f32_e32 v15, v96, v59
	v_fmac_f32_e32 v16, v97, v56
	v_fmac_f32_e32 v17, v97, v57
	v_fmac_f32_e32 v18, v97, v58
	v_fmac_f32_e32 v19, v97, v59
	v_fmac_f32_e32 v20, v98, v56
	v_fmac_f32_e32 v21, v98, v57
	v_fmac_f32_e32 v22, v98, v58
	v_fmac_f32_e32 v23, v98, v59
	v_fmac_f32_e32 v24, v99, v56
	v_fmac_f32_e32 v25, v99, v57
	v_fmac_f32_e32 v26, v99, v58
	v_fmac_f32_e32 v27, v99, v59
	v_fmac_f32_e32 v28, v100, v56
	v_fmac_f32_e32 v29, v100, v57
	v_fmac_f32_e32 v30, v100, v58
	v_fmac_f32_e32 v31, v100, v59
	global_load_dwordx4 v[56:59], v11, s[10:11] nt
	s_add_u32 s10, s10, 0x18000
	s_addc_u32 s11, s11, 0
	ds_read_b32 v96, v10 offset:312
	ds_read_b32 v97, v10 offset:8504
	ds_read_b32 v98, v10 offset:16696
	ds_read_b32 v99, v10 offset:24888
	ds_read_b32 v100, v10 offset:33080
	s_waitcnt vmcnt(15) lgkmcnt(0)
	v_fmac_f32_e32 v12, v96, v60
	v_fmac_f32_e32 v13, v96, v61
	v_fmac_f32_e32 v14, v96, v62
	v_fmac_f32_e32 v15, v96, v63
	v_fmac_f32_e32 v16, v97, v60
	v_fmac_f32_e32 v17, v97, v61
	v_fmac_f32_e32 v18, v97, v62
	v_fmac_f32_e32 v19, v97, v63
	v_fmac_f32_e32 v20, v98, v60
	v_fmac_f32_e32 v21, v98, v61
	v_fmac_f32_e32 v22, v98, v62
	v_fmac_f32_e32 v23, v98, v63
	v_fmac_f32_e32 v24, v99, v60
	v_fmac_f32_e32 v25, v99, v61
	v_fmac_f32_e32 v26, v99, v62
	v_fmac_f32_e32 v27, v99, v63
	v_fmac_f32_e32 v28, v100, v60
	v_fmac_f32_e32 v29, v100, v61
	v_fmac_f32_e32 v30, v100, v62
	v_fmac_f32_e32 v31, v100, v63
	global_load_dwordx4 v[60:63], v11, s[10:11] nt
	s_add_u32 s10, s10, 0x18000
	s_addc_u32 s11, s11, 0
	ds_read_b32 v96, v10 offset:320
	ds_read_b32 v97, v10 offset:8512
	ds_read_b32 v98, v10 offset:16704
	ds_read_b32 v99, v10 offset:24896
	ds_read_b32 v100, v10 offset:33088
	s_waitcnt vmcnt(15) lgkmcnt(0)
	v_fmac_f32_e32 v12, v96, v64
	v_fmac_f32_e32 v13, v96, v65
	v_fmac_f32_e32 v14, v96, v66
	v_fmac_f32_e32 v15, v96, v67
	v_fmac_f32_e32 v16, v97, v64
	v_fmac_f32_e32 v17, v97, v65
	v_fmac_f32_e32 v18, v97, v66
	v_fmac_f32_e32 v19, v97, v67
	v_fmac_f32_e32 v20, v98, v64
	v_fmac_f32_e32 v21, v98, v65
	v_fmac_f32_e32 v22, v98, v66
	v_fmac_f32_e32 v23, v98, v67
	v_fmac_f32_e32 v24, v99, v64
	v_fmac_f32_e32 v25, v99, v65
	v_fmac_f32_e32 v26, v99, v66
	v_fmac_f32_e32 v27, v99, v67
	v_fmac_f32_e32 v28, v100, v64
	v_fmac_f32_e32 v29, v100, v65
	v_fmac_f32_e32 v30, v100, v66
	v_fmac_f32_e32 v31, v100, v67
	global_load_dwordx4 v[64:67], v11, s[10:11] nt
	s_add_u32 s10, s10, 0x18000
	s_addc_u32 s11, s11, 0
	ds_read_b32 v96, v10 offset:328
	ds_read_b32 v97, v10 offset:8520
	ds_read_b32 v98, v10 offset:16712
	ds_read_b32 v99, v10 offset:24904
	ds_read_b32 v100, v10 offset:33096
	s_waitcnt vmcnt(15) lgkmcnt(0)
	v_fmac_f32_e32 v12, v96, v68
	v_fmac_f32_e32 v13, v96, v69
	v_fmac_f32_e32 v14, v96, v70
	v_fmac_f32_e32 v15, v96, v71
	v_fmac_f32_e32 v16, v97, v68
	v_fmac_f32_e32 v17, v97, v69
	v_fmac_f32_e32 v18, v97, v70
	v_fmac_f32_e32 v19, v97, v71
	v_fmac_f32_e32 v20, v98, v68
	v_fmac_f32_e32 v21, v98, v69
	v_fmac_f32_e32 v22, v98, v70
	v_fmac_f32_e32 v23, v98, v71
	v_fmac_f32_e32 v24, v99, v68
	v_fmac_f32_e32 v25, v99, v69
	v_fmac_f32_e32 v26, v99, v70
	v_fmac_f32_e32 v27, v99, v71
	v_fmac_f32_e32 v28, v100, v68
	v_fmac_f32_e32 v29, v100, v69
	v_fmac_f32_e32 v30, v100, v70
	v_fmac_f32_e32 v31, v100, v71
	global_load_dwordx4 v[68:71], v11, s[10:11] nt
	s_add_u32 s10, s10, 0x18000
	s_addc_u32 s11, s11, 0
	ds_read_b32 v96, v10 offset:336
	ds_read_b32 v97, v10 offset:8528
	ds_read_b32 v98, v10 offset:16720
	ds_read_b32 v99, v10 offset:24912
	ds_read_b32 v100, v10 offset:33104
	s_waitcnt vmcnt(15) lgkmcnt(0)
	v_fmac_f32_e32 v12, v96, v72
	v_fmac_f32_e32 v13, v96, v73
	v_fmac_f32_e32 v14, v96, v74
	v_fmac_f32_e32 v15, v96, v75
	v_fmac_f32_e32 v16, v97, v72
	v_fmac_f32_e32 v17, v97, v73
	v_fmac_f32_e32 v18, v97, v74
	v_fmac_f32_e32 v19, v97, v75
	v_fmac_f32_e32 v20, v98, v72
	v_fmac_f32_e32 v21, v98, v73
	v_fmac_f32_e32 v22, v98, v74
	v_fmac_f32_e32 v23, v98, v75
	v_fmac_f32_e32 v24, v99, v72
	v_fmac_f32_e32 v25, v99, v73
	v_fmac_f32_e32 v26, v99, v74
	v_fmac_f32_e32 v27, v99, v75
	v_fmac_f32_e32 v28, v100, v72
	v_fmac_f32_e32 v29, v100, v73
	v_fmac_f32_e32 v30, v100, v74
	v_fmac_f32_e32 v31, v100, v75
	global_load_dwordx4 v[72:75], v11, s[10:11] nt
	s_add_u32 s10, s10, 0x18000
	s_addc_u32 s11, s11, 0
	ds_read_b32 v96, v10 offset:344
	ds_read_b32 v97, v10 offset:8536
	ds_read_b32 v98, v10 offset:16728
	ds_read_b32 v99, v10 offset:24920
	ds_read_b32 v100, v10 offset:33112
	s_waitcnt vmcnt(15) lgkmcnt(0)
	v_fmac_f32_e32 v12, v96, v76
	v_fmac_f32_e32 v13, v96, v77
	v_fmac_f32_e32 v14, v96, v78
	v_fmac_f32_e32 v15, v96, v79
	v_fmac_f32_e32 v16, v97, v76
	v_fmac_f32_e32 v17, v97, v77
	v_fmac_f32_e32 v18, v97, v78
	v_fmac_f32_e32 v19, v97, v79
	v_fmac_f32_e32 v20, v98, v76
	v_fmac_f32_e32 v21, v98, v77
	v_fmac_f32_e32 v22, v98, v78
	v_fmac_f32_e32 v23, v98, v79
	v_fmac_f32_e32 v24, v99, v76
	v_fmac_f32_e32 v25, v99, v77
	v_fmac_f32_e32 v26, v99, v78
	v_fmac_f32_e32 v27, v99, v79
	v_fmac_f32_e32 v28, v100, v76
	v_fmac_f32_e32 v29, v100, v77
	v_fmac_f32_e32 v30, v100, v78
	v_fmac_f32_e32 v31, v100, v79
	global_load_dwordx4 v[76:79], v11, s[10:11] nt
	s_add_u32 s10, s10, 0x18000
	s_addc_u32 s11, s11, 0
	ds_read_b32 v96, v10 offset:352
	ds_read_b32 v97, v10 offset:8544
	ds_read_b32 v98, v10 offset:16736
	ds_read_b32 v99, v10 offset:24928
	ds_read_b32 v100, v10 offset:33120
	s_waitcnt vmcnt(15) lgkmcnt(0)
	v_fmac_f32_e32 v12, v96, v80
	v_fmac_f32_e32 v13, v96, v81
	v_fmac_f32_e32 v14, v96, v82
	v_fmac_f32_e32 v15, v96, v83
	v_fmac_f32_e32 v16, v97, v80
	v_fmac_f32_e32 v17, v97, v81
	v_fmac_f32_e32 v18, v97, v82
	v_fmac_f32_e32 v19, v97, v83
	v_fmac_f32_e32 v20, v98, v80
	v_fmac_f32_e32 v21, v98, v81
	v_fmac_f32_e32 v22, v98, v82
	v_fmac_f32_e32 v23, v98, v83
	v_fmac_f32_e32 v24, v99, v80
	v_fmac_f32_e32 v25, v99, v81
	v_fmac_f32_e32 v26, v99, v82
	v_fmac_f32_e32 v27, v99, v83
	v_fmac_f32_e32 v28, v100, v80
	v_fmac_f32_e32 v29, v100, v81
	v_fmac_f32_e32 v30, v100, v82
	v_fmac_f32_e32 v31, v100, v83
	global_load_dwordx4 v[80:83], v11, s[10:11] nt
	s_add_u32 s10, s10, 0x18000
	s_addc_u32 s11, s11, 0
	ds_read_b32 v96, v10 offset:360
	ds_read_b32 v97, v10 offset:8552
	ds_read_b32 v98, v10 offset:16744
	ds_read_b32 v99, v10 offset:24936
	ds_read_b32 v100, v10 offset:33128
	s_waitcnt vmcnt(15) lgkmcnt(0)
	v_fmac_f32_e32 v12, v96, v84
	v_fmac_f32_e32 v13, v96, v85
	v_fmac_f32_e32 v14, v96, v86
	v_fmac_f32_e32 v15, v96, v87
	v_fmac_f32_e32 v16, v97, v84
	v_fmac_f32_e32 v17, v97, v85
	v_fmac_f32_e32 v18, v97, v86
	v_fmac_f32_e32 v19, v97, v87
	v_fmac_f32_e32 v20, v98, v84
	v_fmac_f32_e32 v21, v98, v85
	v_fmac_f32_e32 v22, v98, v86
	v_fmac_f32_e32 v23, v98, v87
	v_fmac_f32_e32 v24, v99, v84
	v_fmac_f32_e32 v25, v99, v85
	v_fmac_f32_e32 v26, v99, v86
	v_fmac_f32_e32 v27, v99, v87
	v_fmac_f32_e32 v28, v100, v84
	v_fmac_f32_e32 v29, v100, v85
	v_fmac_f32_e32 v30, v100, v86
	v_fmac_f32_e32 v31, v100, v87
	global_load_dwordx4 v[84:87], v11, s[10:11] nt
	s_add_u32 s10, s10, 0x18000
	s_addc_u32 s11, s11, 0
	ds_read_b32 v96, v10 offset:368
	ds_read_b32 v97, v10 offset:8560
	ds_read_b32 v98, v10 offset:16752
	ds_read_b32 v99, v10 offset:24944
	ds_read_b32 v100, v10 offset:33136
	s_waitcnt vmcnt(15) lgkmcnt(0)
	v_fmac_f32_e32 v12, v96, v88
	v_fmac_f32_e32 v13, v96, v89
	v_fmac_f32_e32 v14, v96, v90
	v_fmac_f32_e32 v15, v96, v91
	v_fmac_f32_e32 v16, v97, v88
	v_fmac_f32_e32 v17, v97, v89
	v_fmac_f32_e32 v18, v97, v90
	v_fmac_f32_e32 v19, v97, v91
	v_fmac_f32_e32 v20, v98, v88
	v_fmac_f32_e32 v21, v98, v89
	v_fmac_f32_e32 v22, v98, v90
	v_fmac_f32_e32 v23, v98, v91
	v_fmac_f32_e32 v24, v99, v88
	v_fmac_f32_e32 v25, v99, v89
	v_fmac_f32_e32 v26, v99, v90
	v_fmac_f32_e32 v27, v99, v91
	v_fmac_f32_e32 v28, v100, v88
	v_fmac_f32_e32 v29, v100, v89
	v_fmac_f32_e32 v30, v100, v90
	v_fmac_f32_e32 v31, v100, v91
	global_load_dwordx4 v[88:91], v11, s[10:11] nt
	s_add_u32 s10, s10, 0x18000
	s_addc_u32 s11, s11, 0
	ds_read_b32 v96, v10 offset:376
	ds_read_b32 v97, v10 offset:8568
	ds_read_b32 v98, v10 offset:16760
	ds_read_b32 v99, v10 offset:24952
	ds_read_b32 v100, v10 offset:33144
	s_waitcnt vmcnt(15) lgkmcnt(0)
	v_fmac_f32_e32 v12, v96, v92
	v_fmac_f32_e32 v13, v96, v93
	v_fmac_f32_e32 v14, v96, v94
	v_fmac_f32_e32 v15, v96, v95
	v_fmac_f32_e32 v16, v97, v92
	v_fmac_f32_e32 v17, v97, v93
	v_fmac_f32_e32 v18, v97, v94
	v_fmac_f32_e32 v19, v97, v95
	v_fmac_f32_e32 v20, v98, v92
	v_fmac_f32_e32 v21, v98, v93
	v_fmac_f32_e32 v22, v98, v94
	v_fmac_f32_e32 v23, v98, v95
	v_fmac_f32_e32 v24, v99, v92
	v_fmac_f32_e32 v25, v99, v93
	v_fmac_f32_e32 v26, v99, v94
	v_fmac_f32_e32 v27, v99, v95
	v_fmac_f32_e32 v28, v100, v92
	v_fmac_f32_e32 v29, v100, v93
	v_fmac_f32_e32 v30, v100, v94
	v_fmac_f32_e32 v31, v100, v95
	global_load_dwordx4 v[92:95], v11, s[10:11] nt
	s_add_u32 s10, s10, 0x18000
	s_addc_u32 s11, s11, 0
	ds_read_b32 v96, v10 offset:384
	ds_read_b32 v97, v10 offset:8576
	ds_read_b32 v98, v10 offset:16768
	ds_read_b32 v99, v10 offset:24960
	ds_read_b32 v100, v10 offset:33152
	s_waitcnt vmcnt(15) lgkmcnt(0)
	v_fmac_f32_e32 v12, v96, v32
	v_fmac_f32_e32 v13, v96, v33
	v_fmac_f32_e32 v14, v96, v34
	v_fmac_f32_e32 v15, v96, v35
	v_fmac_f32_e32 v16, v97, v32
	v_fmac_f32_e32 v17, v97, v33
	v_fmac_f32_e32 v18, v97, v34
	v_fmac_f32_e32 v19, v97, v35
	v_fmac_f32_e32 v20, v98, v32
	v_fmac_f32_e32 v21, v98, v33
	v_fmac_f32_e32 v22, v98, v34
	v_fmac_f32_e32 v23, v98, v35
	v_fmac_f32_e32 v24, v99, v32
	v_fmac_f32_e32 v25, v99, v33
	v_fmac_f32_e32 v26, v99, v34
	v_fmac_f32_e32 v27, v99, v35
	v_fmac_f32_e32 v28, v100, v32
	v_fmac_f32_e32 v29, v100, v33
	v_fmac_f32_e32 v30, v100, v34
	v_fmac_f32_e32 v31, v100, v35
	global_load_dwordx4 v[32:35], v11, s[10:11] nt
	s_add_u32 s10, s10, 0x18000
	s_addc_u32 s11, s11, 0
	ds_read_b32 v96, v10 offset:392
	ds_read_b32 v97, v10 offset:8584
	ds_read_b32 v98, v10 offset:16776
	ds_read_b32 v99, v10 offset:24968
	ds_read_b32 v100, v10 offset:33160
	s_waitcnt vmcnt(15) lgkmcnt(0)
	v_fmac_f32_e32 v12, v96, v36
	v_fmac_f32_e32 v13, v96, v37
	v_fmac_f32_e32 v14, v96, v38
	v_fmac_f32_e32 v15, v96, v39
	v_fmac_f32_e32 v16, v97, v36
	v_fmac_f32_e32 v17, v97, v37
	v_fmac_f32_e32 v18, v97, v38
	v_fmac_f32_e32 v19, v97, v39
	v_fmac_f32_e32 v20, v98, v36
	v_fmac_f32_e32 v21, v98, v37
	v_fmac_f32_e32 v22, v98, v38
	v_fmac_f32_e32 v23, v98, v39
	v_fmac_f32_e32 v24, v99, v36
	v_fmac_f32_e32 v25, v99, v37
	v_fmac_f32_e32 v26, v99, v38
	v_fmac_f32_e32 v27, v99, v39
	v_fmac_f32_e32 v28, v100, v36
	v_fmac_f32_e32 v29, v100, v37
	v_fmac_f32_e32 v30, v100, v38
	v_fmac_f32_e32 v31, v100, v39
	global_load_dwordx4 v[36:39], v11, s[10:11] nt
	s_add_u32 s10, s10, 0x18000
	s_addc_u32 s11, s11, 0
	ds_read_b32 v96, v10 offset:400
	ds_read_b32 v97, v10 offset:8592
	ds_read_b32 v98, v10 offset:16784
	ds_read_b32 v99, v10 offset:24976
	ds_read_b32 v100, v10 offset:33168
	s_waitcnt vmcnt(15) lgkmcnt(0)
	v_fmac_f32_e32 v12, v96, v40
	v_fmac_f32_e32 v13, v96, v41
	v_fmac_f32_e32 v14, v96, v42
	v_fmac_f32_e32 v15, v96, v43
	v_fmac_f32_e32 v16, v97, v40
	v_fmac_f32_e32 v17, v97, v41
	v_fmac_f32_e32 v18, v97, v42
	v_fmac_f32_e32 v19, v97, v43
	v_fmac_f32_e32 v20, v98, v40
	v_fmac_f32_e32 v21, v98, v41
	v_fmac_f32_e32 v22, v98, v42
	v_fmac_f32_e32 v23, v98, v43
	v_fmac_f32_e32 v24, v99, v40
	v_fmac_f32_e32 v25, v99, v41
	v_fmac_f32_e32 v26, v99, v42
	v_fmac_f32_e32 v27, v99, v43
	v_fmac_f32_e32 v28, v100, v40
	v_fmac_f32_e32 v29, v100, v41
	v_fmac_f32_e32 v30, v100, v42
	v_fmac_f32_e32 v31, v100, v43
	global_load_dwordx4 v[40:43], v11, s[10:11] nt
	s_add_u32 s10, s10, 0x18000
	s_addc_u32 s11, s11, 0
	ds_read_b32 v96, v10 offset:408
	ds_read_b32 v97, v10 offset:8600
	ds_read_b32 v98, v10 offset:16792
	ds_read_b32 v99, v10 offset:24984
	ds_read_b32 v100, v10 offset:33176
	s_waitcnt vmcnt(15) lgkmcnt(0)
	v_fmac_f32_e32 v12, v96, v44
	v_fmac_f32_e32 v13, v96, v45
	v_fmac_f32_e32 v14, v96, v46
	v_fmac_f32_e32 v15, v96, v47
	v_fmac_f32_e32 v16, v97, v44
	v_fmac_f32_e32 v17, v97, v45
	v_fmac_f32_e32 v18, v97, v46
	v_fmac_f32_e32 v19, v97, v47
	v_fmac_f32_e32 v20, v98, v44
	v_fmac_f32_e32 v21, v98, v45
	v_fmac_f32_e32 v22, v98, v46
	v_fmac_f32_e32 v23, v98, v47
	v_fmac_f32_e32 v24, v99, v44
	v_fmac_f32_e32 v25, v99, v45
	v_fmac_f32_e32 v26, v99, v46
	v_fmac_f32_e32 v27, v99, v47
	v_fmac_f32_e32 v28, v100, v44
	v_fmac_f32_e32 v29, v100, v45
	v_fmac_f32_e32 v30, v100, v46
	v_fmac_f32_e32 v31, v100, v47
	global_load_dwordx4 v[44:47], v11, s[10:11] nt
	s_add_u32 s10, s10, 0x18000
	s_addc_u32 s11, s11, 0
	ds_read_b32 v96, v10 offset:416
	ds_read_b32 v97, v10 offset:8608
	ds_read_b32 v98, v10 offset:16800
	ds_read_b32 v99, v10 offset:24992
	ds_read_b32 v100, v10 offset:33184
	s_waitcnt vmcnt(15) lgkmcnt(0)
	v_fmac_f32_e32 v12, v96, v48
	v_fmac_f32_e32 v13, v96, v49
	v_fmac_f32_e32 v14, v96, v50
	v_fmac_f32_e32 v15, v96, v51
	v_fmac_f32_e32 v16, v97, v48
	v_fmac_f32_e32 v17, v97, v49
	v_fmac_f32_e32 v18, v97, v50
	v_fmac_f32_e32 v19, v97, v51
	v_fmac_f32_e32 v20, v98, v48
	v_fmac_f32_e32 v21, v98, v49
	v_fmac_f32_e32 v22, v98, v50
	v_fmac_f32_e32 v23, v98, v51
	v_fmac_f32_e32 v24, v99, v48
	v_fmac_f32_e32 v25, v99, v49
	v_fmac_f32_e32 v26, v99, v50
	v_fmac_f32_e32 v27, v99, v51
	v_fmac_f32_e32 v28, v100, v48
	v_fmac_f32_e32 v29, v100, v49
	v_fmac_f32_e32 v30, v100, v50
	v_fmac_f32_e32 v31, v100, v51
	global_load_dwordx4 v[48:51], v11, s[10:11] nt
	s_add_u32 s10, s10, 0x18000
	s_addc_u32 s11, s11, 0
	ds_read_b32 v96, v10 offset:424
	ds_read_b32 v97, v10 offset:8616
	ds_read_b32 v98, v10 offset:16808
	ds_read_b32 v99, v10 offset:25000
	ds_read_b32 v100, v10 offset:33192
	s_waitcnt vmcnt(15) lgkmcnt(0)
	v_fmac_f32_e32 v12, v96, v52
	v_fmac_f32_e32 v13, v96, v53
	v_fmac_f32_e32 v14, v96, v54
	v_fmac_f32_e32 v15, v96, v55
	v_fmac_f32_e32 v16, v97, v52
	v_fmac_f32_e32 v17, v97, v53
	v_fmac_f32_e32 v18, v97, v54
	v_fmac_f32_e32 v19, v97, v55
	v_fmac_f32_e32 v20, v98, v52
	v_fmac_f32_e32 v21, v98, v53
	v_fmac_f32_e32 v22, v98, v54
	v_fmac_f32_e32 v23, v98, v55
	v_fmac_f32_e32 v24, v99, v52
	v_fmac_f32_e32 v25, v99, v53
	v_fmac_f32_e32 v26, v99, v54
	v_fmac_f32_e32 v27, v99, v55
	v_fmac_f32_e32 v28, v100, v52
	v_fmac_f32_e32 v29, v100, v53
	v_fmac_f32_e32 v30, v100, v54
	v_fmac_f32_e32 v31, v100, v55
	global_load_dwordx4 v[52:55], v11, s[10:11] nt
	s_add_u32 s10, s10, 0x18000
	s_addc_u32 s11, s11, 0
	ds_read_b32 v96, v10 offset:432
	ds_read_b32 v97, v10 offset:8624
	ds_read_b32 v98, v10 offset:16816
	ds_read_b32 v99, v10 offset:25008
	ds_read_b32 v100, v10 offset:33200
	s_waitcnt vmcnt(15) lgkmcnt(0)
	v_fmac_f32_e32 v12, v96, v56
	v_fmac_f32_e32 v13, v96, v57
	v_fmac_f32_e32 v14, v96, v58
	v_fmac_f32_e32 v15, v96, v59
	v_fmac_f32_e32 v16, v97, v56
	v_fmac_f32_e32 v17, v97, v57
	v_fmac_f32_e32 v18, v97, v58
	v_fmac_f32_e32 v19, v97, v59
	v_fmac_f32_e32 v20, v98, v56
	v_fmac_f32_e32 v21, v98, v57
	v_fmac_f32_e32 v22, v98, v58
	v_fmac_f32_e32 v23, v98, v59
	v_fmac_f32_e32 v24, v99, v56
	v_fmac_f32_e32 v25, v99, v57
	v_fmac_f32_e32 v26, v99, v58
	v_fmac_f32_e32 v27, v99, v59
	v_fmac_f32_e32 v28, v100, v56
	v_fmac_f32_e32 v29, v100, v57
	v_fmac_f32_e32 v30, v100, v58
	v_fmac_f32_e32 v31, v100, v59
	global_load_dwordx4 v[56:59], v11, s[10:11] nt
	s_add_u32 s10, s10, 0x18000
	s_addc_u32 s11, s11, 0
	ds_read_b32 v96, v10 offset:440
	ds_read_b32 v97, v10 offset:8632
	ds_read_b32 v98, v10 offset:16824
	ds_read_b32 v99, v10 offset:25016
	ds_read_b32 v100, v10 offset:33208
	s_waitcnt vmcnt(15) lgkmcnt(0)
	v_fmac_f32_e32 v12, v96, v60
	v_fmac_f32_e32 v13, v96, v61
	v_fmac_f32_e32 v14, v96, v62
	v_fmac_f32_e32 v15, v96, v63
	v_fmac_f32_e32 v16, v97, v60
	v_fmac_f32_e32 v17, v97, v61
	v_fmac_f32_e32 v18, v97, v62
	v_fmac_f32_e32 v19, v97, v63
	v_fmac_f32_e32 v20, v98, v60
	v_fmac_f32_e32 v21, v98, v61
	v_fmac_f32_e32 v22, v98, v62
	v_fmac_f32_e32 v23, v98, v63
	v_fmac_f32_e32 v24, v99, v60
	v_fmac_f32_e32 v25, v99, v61
	v_fmac_f32_e32 v26, v99, v62
	v_fmac_f32_e32 v27, v99, v63
	v_fmac_f32_e32 v28, v100, v60
	v_fmac_f32_e32 v29, v100, v61
	v_fmac_f32_e32 v30, v100, v62
	v_fmac_f32_e32 v31, v100, v63
	global_load_dwordx4 v[60:63], v11, s[10:11] nt
	s_add_u32 s10, s10, 0x18000
	s_addc_u32 s11, s11, 0
	ds_read_b32 v96, v10 offset:448
	ds_read_b32 v97, v10 offset:8640
	ds_read_b32 v98, v10 offset:16832
	ds_read_b32 v99, v10 offset:25024
	ds_read_b32 v100, v10 offset:33216
	s_waitcnt vmcnt(15) lgkmcnt(0)
	v_fmac_f32_e32 v12, v96, v64
	v_fmac_f32_e32 v13, v96, v65
	v_fmac_f32_e32 v14, v96, v66
	v_fmac_f32_e32 v15, v96, v67
	v_fmac_f32_e32 v16, v97, v64
	v_fmac_f32_e32 v17, v97, v65
	v_fmac_f32_e32 v18, v97, v66
	v_fmac_f32_e32 v19, v97, v67
	v_fmac_f32_e32 v20, v98, v64
	v_fmac_f32_e32 v21, v98, v65
	v_fmac_f32_e32 v22, v98, v66
	v_fmac_f32_e32 v23, v98, v67
	v_fmac_f32_e32 v24, v99, v64
	v_fmac_f32_e32 v25, v99, v65
	v_fmac_f32_e32 v26, v99, v66
	v_fmac_f32_e32 v27, v99, v67
	v_fmac_f32_e32 v28, v100, v64
	v_fmac_f32_e32 v29, v100, v65
	v_fmac_f32_e32 v30, v100, v66
	v_fmac_f32_e32 v31, v100, v67
	global_load_dwordx4 v[64:67], v11, s[10:11] nt
	s_add_u32 s10, s10, 0x18000
	s_addc_u32 s11, s11, 0
	ds_read_b32 v96, v10 offset:456
	ds_read_b32 v97, v10 offset:8648
	ds_read_b32 v98, v10 offset:16840
	ds_read_b32 v99, v10 offset:25032
	ds_read_b32 v100, v10 offset:33224
	s_waitcnt vmcnt(15) lgkmcnt(0)
	v_fmac_f32_e32 v12, v96, v68
	v_fmac_f32_e32 v13, v96, v69
	v_fmac_f32_e32 v14, v96, v70
	v_fmac_f32_e32 v15, v96, v71
	v_fmac_f32_e32 v16, v97, v68
	v_fmac_f32_e32 v17, v97, v69
	v_fmac_f32_e32 v18, v97, v70
	v_fmac_f32_e32 v19, v97, v71
	v_fmac_f32_e32 v20, v98, v68
	v_fmac_f32_e32 v21, v98, v69
	v_fmac_f32_e32 v22, v98, v70
	v_fmac_f32_e32 v23, v98, v71
	v_fmac_f32_e32 v24, v99, v68
	v_fmac_f32_e32 v25, v99, v69
	v_fmac_f32_e32 v26, v99, v70
	v_fmac_f32_e32 v27, v99, v71
	v_fmac_f32_e32 v28, v100, v68
	v_fmac_f32_e32 v29, v100, v69
	v_fmac_f32_e32 v30, v100, v70
	v_fmac_f32_e32 v31, v100, v71
	global_load_dwordx4 v[68:71], v11, s[10:11] nt
	s_add_u32 s10, s10, 0x18000
	s_addc_u32 s11, s11, 0
	ds_read_b32 v96, v10 offset:464
	ds_read_b32 v97, v10 offset:8656
	ds_read_b32 v98, v10 offset:16848
	ds_read_b32 v99, v10 offset:25040
	ds_read_b32 v100, v10 offset:33232
	s_waitcnt vmcnt(15) lgkmcnt(0)
	v_fmac_f32_e32 v12, v96, v72
	v_fmac_f32_e32 v13, v96, v73
	v_fmac_f32_e32 v14, v96, v74
	v_fmac_f32_e32 v15, v96, v75
	v_fmac_f32_e32 v16, v97, v72
	v_fmac_f32_e32 v17, v97, v73
	v_fmac_f32_e32 v18, v97, v74
	v_fmac_f32_e32 v19, v97, v75
	v_fmac_f32_e32 v20, v98, v72
	v_fmac_f32_e32 v21, v98, v73
	v_fmac_f32_e32 v22, v98, v74
	v_fmac_f32_e32 v23, v98, v75
	v_fmac_f32_e32 v24, v99, v72
	v_fmac_f32_e32 v25, v99, v73
	v_fmac_f32_e32 v26, v99, v74
	v_fmac_f32_e32 v27, v99, v75
	v_fmac_f32_e32 v28, v100, v72
	v_fmac_f32_e32 v29, v100, v73
	v_fmac_f32_e32 v30, v100, v74
	v_fmac_f32_e32 v31, v100, v75
	global_load_dwordx4 v[72:75], v11, s[10:11] nt
	s_add_u32 s10, s10, 0x18000
	s_addc_u32 s11, s11, 0
	ds_read_b32 v96, v10 offset:472
	ds_read_b32 v97, v10 offset:8664
	ds_read_b32 v98, v10 offset:16856
	ds_read_b32 v99, v10 offset:25048
	ds_read_b32 v100, v10 offset:33240
	s_waitcnt vmcnt(15) lgkmcnt(0)
	v_fmac_f32_e32 v12, v96, v76
	v_fmac_f32_e32 v13, v96, v77
	v_fmac_f32_e32 v14, v96, v78
	v_fmac_f32_e32 v15, v96, v79
	v_fmac_f32_e32 v16, v97, v76
	v_fmac_f32_e32 v17, v97, v77
	v_fmac_f32_e32 v18, v97, v78
	v_fmac_f32_e32 v19, v97, v79
	v_fmac_f32_e32 v20, v98, v76
	v_fmac_f32_e32 v21, v98, v77
	v_fmac_f32_e32 v22, v98, v78
	v_fmac_f32_e32 v23, v98, v79
	v_fmac_f32_e32 v24, v99, v76
	v_fmac_f32_e32 v25, v99, v77
	v_fmac_f32_e32 v26, v99, v78
	v_fmac_f32_e32 v27, v99, v79
	v_fmac_f32_e32 v28, v100, v76
	v_fmac_f32_e32 v29, v100, v77
	v_fmac_f32_e32 v30, v100, v78
	v_fmac_f32_e32 v31, v100, v79
	global_load_dwordx4 v[76:79], v11, s[10:11] nt
	s_add_u32 s10, s10, 0x18000
	s_addc_u32 s11, s11, 0
	ds_read_b32 v96, v10 offset:480
	ds_read_b32 v97, v10 offset:8672
	ds_read_b32 v98, v10 offset:16864
	ds_read_b32 v99, v10 offset:25056
	ds_read_b32 v100, v10 offset:33248
	s_waitcnt vmcnt(15) lgkmcnt(0)
	v_fmac_f32_e32 v12, v96, v80
	v_fmac_f32_e32 v13, v96, v81
	v_fmac_f32_e32 v14, v96, v82
	v_fmac_f32_e32 v15, v96, v83
	v_fmac_f32_e32 v16, v97, v80
	v_fmac_f32_e32 v17, v97, v81
	v_fmac_f32_e32 v18, v97, v82
	v_fmac_f32_e32 v19, v97, v83
	v_fmac_f32_e32 v20, v98, v80
	v_fmac_f32_e32 v21, v98, v81
	v_fmac_f32_e32 v22, v98, v82
	v_fmac_f32_e32 v23, v98, v83
	v_fmac_f32_e32 v24, v99, v80
	v_fmac_f32_e32 v25, v99, v81
	v_fmac_f32_e32 v26, v99, v82
	v_fmac_f32_e32 v27, v99, v83
	v_fmac_f32_e32 v28, v100, v80
	v_fmac_f32_e32 v29, v100, v81
	v_fmac_f32_e32 v30, v100, v82
	v_fmac_f32_e32 v31, v100, v83
	global_load_dwordx4 v[80:83], v11, s[10:11] nt
	s_add_u32 s10, s10, 0x18000
	s_addc_u32 s11, s11, 0
	ds_read_b32 v96, v10 offset:488
	ds_read_b32 v97, v10 offset:8680
	ds_read_b32 v98, v10 offset:16872
	ds_read_b32 v99, v10 offset:25064
	ds_read_b32 v100, v10 offset:33256
	s_waitcnt vmcnt(15) lgkmcnt(0)
	v_fmac_f32_e32 v12, v96, v84
	v_fmac_f32_e32 v13, v96, v85
	v_fmac_f32_e32 v14, v96, v86
	v_fmac_f32_e32 v15, v96, v87
	v_fmac_f32_e32 v16, v97, v84
	v_fmac_f32_e32 v17, v97, v85
	v_fmac_f32_e32 v18, v97, v86
	v_fmac_f32_e32 v19, v97, v87
	v_fmac_f32_e32 v20, v98, v84
	v_fmac_f32_e32 v21, v98, v85
	v_fmac_f32_e32 v22, v98, v86
	v_fmac_f32_e32 v23, v98, v87
	v_fmac_f32_e32 v24, v99, v84
	v_fmac_f32_e32 v25, v99, v85
	v_fmac_f32_e32 v26, v99, v86
	v_fmac_f32_e32 v27, v99, v87
	v_fmac_f32_e32 v28, v100, v84
	v_fmac_f32_e32 v29, v100, v85
	v_fmac_f32_e32 v30, v100, v86
	v_fmac_f32_e32 v31, v100, v87
	global_load_dwordx4 v[84:87], v11, s[10:11] nt
	s_add_u32 s10, s10, 0x18000
	s_addc_u32 s11, s11, 0
	ds_read_b32 v96, v10 offset:496
	ds_read_b32 v97, v10 offset:8688
	ds_read_b32 v98, v10 offset:16880
	ds_read_b32 v99, v10 offset:25072
	ds_read_b32 v100, v10 offset:33264
	s_waitcnt vmcnt(15) lgkmcnt(0)
	v_fmac_f32_e32 v12, v96, v88
	v_fmac_f32_e32 v13, v96, v89
	v_fmac_f32_e32 v14, v96, v90
	v_fmac_f32_e32 v15, v96, v91
	v_fmac_f32_e32 v16, v97, v88
	v_fmac_f32_e32 v17, v97, v89
	v_fmac_f32_e32 v18, v97, v90
	v_fmac_f32_e32 v19, v97, v91
	v_fmac_f32_e32 v20, v98, v88
	v_fmac_f32_e32 v21, v98, v89
	v_fmac_f32_e32 v22, v98, v90
	v_fmac_f32_e32 v23, v98, v91
	v_fmac_f32_e32 v24, v99, v88
	v_fmac_f32_e32 v25, v99, v89
	v_fmac_f32_e32 v26, v99, v90
	v_fmac_f32_e32 v27, v99, v91
	v_fmac_f32_e32 v28, v100, v88
	v_fmac_f32_e32 v29, v100, v89
	v_fmac_f32_e32 v30, v100, v90
	v_fmac_f32_e32 v31, v100, v91
	global_load_dwordx4 v[88:91], v11, s[10:11] nt
	s_add_u32 s10, s10, 0x18000
	s_addc_u32 s11, s11, 0
	ds_read_b32 v96, v10 offset:504
	ds_read_b32 v97, v10 offset:8696
	ds_read_b32 v98, v10 offset:16888
	ds_read_b32 v99, v10 offset:25080
	ds_read_b32 v100, v10 offset:33272
	s_waitcnt vmcnt(15) lgkmcnt(0)
	v_fmac_f32_e32 v12, v96, v92
	v_fmac_f32_e32 v13, v96, v93
	v_fmac_f32_e32 v14, v96, v94
	v_fmac_f32_e32 v15, v96, v95
	v_fmac_f32_e32 v16, v97, v92
	v_fmac_f32_e32 v17, v97, v93
	v_fmac_f32_e32 v18, v97, v94
	v_fmac_f32_e32 v19, v97, v95
	v_fmac_f32_e32 v20, v98, v92
	v_fmac_f32_e32 v21, v98, v93
	v_fmac_f32_e32 v22, v98, v94
	v_fmac_f32_e32 v23, v98, v95
	v_fmac_f32_e32 v24, v99, v92
	v_fmac_f32_e32 v25, v99, v93
	v_fmac_f32_e32 v26, v99, v94
	v_fmac_f32_e32 v27, v99, v95
	v_fmac_f32_e32 v28, v100, v92
	v_fmac_f32_e32 v29, v100, v93
	v_fmac_f32_e32 v30, v100, v94
	v_fmac_f32_e32 v31, v100, v95
	global_load_dwordx4 v[92:95], v11, s[10:11] nt
	s_add_u32 s10, s10, 0x18000
	s_addc_u32 s11, s11, 0
	ds_read_b32 v96, v10 offset:512
	ds_read_b32 v97, v10 offset:8704
	ds_read_b32 v98, v10 offset:16896
	ds_read_b32 v99, v10 offset:25088
	ds_read_b32 v100, v10 offset:33280
	s_waitcnt vmcnt(15) lgkmcnt(0)
	v_fmac_f32_e32 v12, v96, v32
	v_fmac_f32_e32 v13, v96, v33
	v_fmac_f32_e32 v14, v96, v34
	v_fmac_f32_e32 v15, v96, v35
	v_fmac_f32_e32 v16, v97, v32
	v_fmac_f32_e32 v17, v97, v33
	v_fmac_f32_e32 v18, v97, v34
	v_fmac_f32_e32 v19, v97, v35
	v_fmac_f32_e32 v20, v98, v32
	v_fmac_f32_e32 v21, v98, v33
	v_fmac_f32_e32 v22, v98, v34
	v_fmac_f32_e32 v23, v98, v35
	v_fmac_f32_e32 v24, v99, v32
	v_fmac_f32_e32 v25, v99, v33
	v_fmac_f32_e32 v26, v99, v34
	v_fmac_f32_e32 v27, v99, v35
	v_fmac_f32_e32 v28, v100, v32
	v_fmac_f32_e32 v29, v100, v33
	v_fmac_f32_e32 v30, v100, v34
	v_fmac_f32_e32 v31, v100, v35
	global_load_dwordx4 v[32:35], v11, s[10:11] nt
	s_add_u32 s10, s10, 0x18000
	s_addc_u32 s11, s11, 0
	ds_read_b32 v96, v10 offset:520
	ds_read_b32 v97, v10 offset:8712
	ds_read_b32 v98, v10 offset:16904
	ds_read_b32 v99, v10 offset:25096
	ds_read_b32 v100, v10 offset:33288
	s_waitcnt vmcnt(15) lgkmcnt(0)
	v_fmac_f32_e32 v12, v96, v36
	v_fmac_f32_e32 v13, v96, v37
	v_fmac_f32_e32 v14, v96, v38
	v_fmac_f32_e32 v15, v96, v39
	v_fmac_f32_e32 v16, v97, v36
	v_fmac_f32_e32 v17, v97, v37
	v_fmac_f32_e32 v18, v97, v38
	v_fmac_f32_e32 v19, v97, v39
	v_fmac_f32_e32 v20, v98, v36
	v_fmac_f32_e32 v21, v98, v37
	v_fmac_f32_e32 v22, v98, v38
	v_fmac_f32_e32 v23, v98, v39
	v_fmac_f32_e32 v24, v99, v36
	v_fmac_f32_e32 v25, v99, v37
	v_fmac_f32_e32 v26, v99, v38
	v_fmac_f32_e32 v27, v99, v39
	v_fmac_f32_e32 v28, v100, v36
	v_fmac_f32_e32 v29, v100, v37
	v_fmac_f32_e32 v30, v100, v38
	v_fmac_f32_e32 v31, v100, v39
	global_load_dwordx4 v[36:39], v11, s[10:11] nt
	s_add_u32 s10, s10, 0x18000
	s_addc_u32 s11, s11, 0
	ds_read_b32 v96, v10 offset:528
	ds_read_b32 v97, v10 offset:8720
	ds_read_b32 v98, v10 offset:16912
	ds_read_b32 v99, v10 offset:25104
	ds_read_b32 v100, v10 offset:33296
	s_waitcnt vmcnt(15) lgkmcnt(0)
	v_fmac_f32_e32 v12, v96, v40
	v_fmac_f32_e32 v13, v96, v41
	v_fmac_f32_e32 v14, v96, v42
	v_fmac_f32_e32 v15, v96, v43
	v_fmac_f32_e32 v16, v97, v40
	v_fmac_f32_e32 v17, v97, v41
	v_fmac_f32_e32 v18, v97, v42
	v_fmac_f32_e32 v19, v97, v43
	v_fmac_f32_e32 v20, v98, v40
	v_fmac_f32_e32 v21, v98, v41
	v_fmac_f32_e32 v22, v98, v42
	v_fmac_f32_e32 v23, v98, v43
	v_fmac_f32_e32 v24, v99, v40
	v_fmac_f32_e32 v25, v99, v41
	v_fmac_f32_e32 v26, v99, v42
	v_fmac_f32_e32 v27, v99, v43
	v_fmac_f32_e32 v28, v100, v40
	v_fmac_f32_e32 v29, v100, v41
	v_fmac_f32_e32 v30, v100, v42
	v_fmac_f32_e32 v31, v100, v43
	global_load_dwordx4 v[40:43], v11, s[10:11] nt
	s_add_u32 s10, s10, 0x18000
	s_addc_u32 s11, s11, 0
	ds_read_b32 v96, v10 offset:536
	ds_read_b32 v97, v10 offset:8728
	ds_read_b32 v98, v10 offset:16920
	ds_read_b32 v99, v10 offset:25112
	ds_read_b32 v100, v10 offset:33304
	s_waitcnt vmcnt(15) lgkmcnt(0)
	v_fmac_f32_e32 v12, v96, v44
	v_fmac_f32_e32 v13, v96, v45
	v_fmac_f32_e32 v14, v96, v46
	v_fmac_f32_e32 v15, v96, v47
	v_fmac_f32_e32 v16, v97, v44
	v_fmac_f32_e32 v17, v97, v45
	v_fmac_f32_e32 v18, v97, v46
	v_fmac_f32_e32 v19, v97, v47
	v_fmac_f32_e32 v20, v98, v44
	v_fmac_f32_e32 v21, v98, v45
	v_fmac_f32_e32 v22, v98, v46
	v_fmac_f32_e32 v23, v98, v47
	v_fmac_f32_e32 v24, v99, v44
	v_fmac_f32_e32 v25, v99, v45
	v_fmac_f32_e32 v26, v99, v46
	v_fmac_f32_e32 v27, v99, v47
	v_fmac_f32_e32 v28, v100, v44
	v_fmac_f32_e32 v29, v100, v45
	v_fmac_f32_e32 v30, v100, v46
	v_fmac_f32_e32 v31, v100, v47
	global_load_dwordx4 v[44:47], v11, s[10:11] nt
	s_add_u32 s10, s10, 0x18000
	s_addc_u32 s11, s11, 0
	ds_read_b32 v96, v10 offset:544
	ds_read_b32 v97, v10 offset:8736
	ds_read_b32 v98, v10 offset:16928
	ds_read_b32 v99, v10 offset:25120
	ds_read_b32 v100, v10 offset:33312
	s_waitcnt vmcnt(15) lgkmcnt(0)
	v_fmac_f32_e32 v12, v96, v48
	v_fmac_f32_e32 v13, v96, v49
	v_fmac_f32_e32 v14, v96, v50
	v_fmac_f32_e32 v15, v96, v51
	v_fmac_f32_e32 v16, v97, v48
	v_fmac_f32_e32 v17, v97, v49
	v_fmac_f32_e32 v18, v97, v50
	v_fmac_f32_e32 v19, v97, v51
	v_fmac_f32_e32 v20, v98, v48
	v_fmac_f32_e32 v21, v98, v49
	v_fmac_f32_e32 v22, v98, v50
	v_fmac_f32_e32 v23, v98, v51
	v_fmac_f32_e32 v24, v99, v48
	v_fmac_f32_e32 v25, v99, v49
	v_fmac_f32_e32 v26, v99, v50
	v_fmac_f32_e32 v27, v99, v51
	v_fmac_f32_e32 v28, v100, v48
	v_fmac_f32_e32 v29, v100, v49
	v_fmac_f32_e32 v30, v100, v50
	v_fmac_f32_e32 v31, v100, v51
	global_load_dwordx4 v[48:51], v11, s[10:11] nt
	s_add_u32 s10, s10, 0x18000
	s_addc_u32 s11, s11, 0
	ds_read_b32 v96, v10 offset:552
	ds_read_b32 v97, v10 offset:8744
	ds_read_b32 v98, v10 offset:16936
	ds_read_b32 v99, v10 offset:25128
	ds_read_b32 v100, v10 offset:33320
	s_waitcnt vmcnt(15) lgkmcnt(0)
	v_fmac_f32_e32 v12, v96, v52
	v_fmac_f32_e32 v13, v96, v53
	v_fmac_f32_e32 v14, v96, v54
	v_fmac_f32_e32 v15, v96, v55
	v_fmac_f32_e32 v16, v97, v52
	v_fmac_f32_e32 v17, v97, v53
	v_fmac_f32_e32 v18, v97, v54
	v_fmac_f32_e32 v19, v97, v55
	v_fmac_f32_e32 v20, v98, v52
	v_fmac_f32_e32 v21, v98, v53
	v_fmac_f32_e32 v22, v98, v54
	v_fmac_f32_e32 v23, v98, v55
	v_fmac_f32_e32 v24, v99, v52
	v_fmac_f32_e32 v25, v99, v53
	v_fmac_f32_e32 v26, v99, v54
	v_fmac_f32_e32 v27, v99, v55
	v_fmac_f32_e32 v28, v100, v52
	v_fmac_f32_e32 v29, v100, v53
	v_fmac_f32_e32 v30, v100, v54
	v_fmac_f32_e32 v31, v100, v55
	global_load_dwordx4 v[52:55], v11, s[10:11] nt
	s_add_u32 s10, s10, 0x18000
	s_addc_u32 s11, s11, 0
	ds_read_b32 v96, v10 offset:560
	ds_read_b32 v97, v10 offset:8752
	ds_read_b32 v98, v10 offset:16944
	ds_read_b32 v99, v10 offset:25136
	ds_read_b32 v100, v10 offset:33328
	s_waitcnt vmcnt(15) lgkmcnt(0)
	v_fmac_f32_e32 v12, v96, v56
	v_fmac_f32_e32 v13, v96, v57
	v_fmac_f32_e32 v14, v96, v58
	v_fmac_f32_e32 v15, v96, v59
	v_fmac_f32_e32 v16, v97, v56
	v_fmac_f32_e32 v17, v97, v57
	v_fmac_f32_e32 v18, v97, v58
	v_fmac_f32_e32 v19, v97, v59
	v_fmac_f32_e32 v20, v98, v56
	v_fmac_f32_e32 v21, v98, v57
	v_fmac_f32_e32 v22, v98, v58
	v_fmac_f32_e32 v23, v98, v59
	v_fmac_f32_e32 v24, v99, v56
	v_fmac_f32_e32 v25, v99, v57
	v_fmac_f32_e32 v26, v99, v58
	v_fmac_f32_e32 v27, v99, v59
	v_fmac_f32_e32 v28, v100, v56
	v_fmac_f32_e32 v29, v100, v57
	v_fmac_f32_e32 v30, v100, v58
	v_fmac_f32_e32 v31, v100, v59
	global_load_dwordx4 v[56:59], v11, s[10:11] nt
	s_add_u32 s10, s10, 0x18000
	s_addc_u32 s11, s11, 0
	ds_read_b32 v96, v10 offset:568
	ds_read_b32 v97, v10 offset:8760
	ds_read_b32 v98, v10 offset:16952
	ds_read_b32 v99, v10 offset:25144
	ds_read_b32 v100, v10 offset:33336
	s_waitcnt vmcnt(15) lgkmcnt(0)
	v_fmac_f32_e32 v12, v96, v60
	v_fmac_f32_e32 v13, v96, v61
	v_fmac_f32_e32 v14, v96, v62
	v_fmac_f32_e32 v15, v96, v63
	v_fmac_f32_e32 v16, v97, v60
	v_fmac_f32_e32 v17, v97, v61
	v_fmac_f32_e32 v18, v97, v62
	v_fmac_f32_e32 v19, v97, v63
	v_fmac_f32_e32 v20, v98, v60
	v_fmac_f32_e32 v21, v98, v61
	v_fmac_f32_e32 v22, v98, v62
	v_fmac_f32_e32 v23, v98, v63
	v_fmac_f32_e32 v24, v99, v60
	v_fmac_f32_e32 v25, v99, v61
	v_fmac_f32_e32 v26, v99, v62
	v_fmac_f32_e32 v27, v99, v63
	v_fmac_f32_e32 v28, v100, v60
	v_fmac_f32_e32 v29, v100, v61
	v_fmac_f32_e32 v30, v100, v62
	v_fmac_f32_e32 v31, v100, v63
	global_load_dwordx4 v[60:63], v11, s[10:11] nt
	s_add_u32 s10, s10, 0x18000
	s_addc_u32 s11, s11, 0
	ds_read_b32 v96, v10 offset:576
	ds_read_b32 v97, v10 offset:8768
	ds_read_b32 v98, v10 offset:16960
	ds_read_b32 v99, v10 offset:25152
	ds_read_b32 v100, v10 offset:33344
	s_waitcnt vmcnt(15) lgkmcnt(0)
	v_fmac_f32_e32 v12, v96, v64
	v_fmac_f32_e32 v13, v96, v65
	v_fmac_f32_e32 v14, v96, v66
	v_fmac_f32_e32 v15, v96, v67
	v_fmac_f32_e32 v16, v97, v64
	v_fmac_f32_e32 v17, v97, v65
	v_fmac_f32_e32 v18, v97, v66
	v_fmac_f32_e32 v19, v97, v67
	v_fmac_f32_e32 v20, v98, v64
	v_fmac_f32_e32 v21, v98, v65
	v_fmac_f32_e32 v22, v98, v66
	v_fmac_f32_e32 v23, v98, v67
	v_fmac_f32_e32 v24, v99, v64
	v_fmac_f32_e32 v25, v99, v65
	v_fmac_f32_e32 v26, v99, v66
	v_fmac_f32_e32 v27, v99, v67
	v_fmac_f32_e32 v28, v100, v64
	v_fmac_f32_e32 v29, v100, v65
	v_fmac_f32_e32 v30, v100, v66
	v_fmac_f32_e32 v31, v100, v67
	global_load_dwordx4 v[64:67], v11, s[10:11] nt
	s_add_u32 s10, s10, 0x18000
	s_addc_u32 s11, s11, 0
	ds_read_b32 v96, v10 offset:584
	ds_read_b32 v97, v10 offset:8776
	ds_read_b32 v98, v10 offset:16968
	ds_read_b32 v99, v10 offset:25160
	ds_read_b32 v100, v10 offset:33352
	s_waitcnt vmcnt(15) lgkmcnt(0)
	v_fmac_f32_e32 v12, v96, v68
	v_fmac_f32_e32 v13, v96, v69
	v_fmac_f32_e32 v14, v96, v70
	v_fmac_f32_e32 v15, v96, v71
	v_fmac_f32_e32 v16, v97, v68
	v_fmac_f32_e32 v17, v97, v69
	v_fmac_f32_e32 v18, v97, v70
	v_fmac_f32_e32 v19, v97, v71
	v_fmac_f32_e32 v20, v98, v68
	v_fmac_f32_e32 v21, v98, v69
	v_fmac_f32_e32 v22, v98, v70
	v_fmac_f32_e32 v23, v98, v71
	v_fmac_f32_e32 v24, v99, v68
	v_fmac_f32_e32 v25, v99, v69
	v_fmac_f32_e32 v26, v99, v70
	v_fmac_f32_e32 v27, v99, v71
	v_fmac_f32_e32 v28, v100, v68
	v_fmac_f32_e32 v29, v100, v69
	v_fmac_f32_e32 v30, v100, v70
	v_fmac_f32_e32 v31, v100, v71
	global_load_dwordx4 v[68:71], v11, s[10:11] nt
	s_add_u32 s10, s10, 0x18000
	s_addc_u32 s11, s11, 0
	ds_read_b32 v96, v10 offset:592
	ds_read_b32 v97, v10 offset:8784
	ds_read_b32 v98, v10 offset:16976
	ds_read_b32 v99, v10 offset:25168
	ds_read_b32 v100, v10 offset:33360
	s_waitcnt vmcnt(15) lgkmcnt(0)
	v_fmac_f32_e32 v12, v96, v72
	v_fmac_f32_e32 v13, v96, v73
	v_fmac_f32_e32 v14, v96, v74
	v_fmac_f32_e32 v15, v96, v75
	v_fmac_f32_e32 v16, v97, v72
	v_fmac_f32_e32 v17, v97, v73
	v_fmac_f32_e32 v18, v97, v74
	v_fmac_f32_e32 v19, v97, v75
	v_fmac_f32_e32 v20, v98, v72
	v_fmac_f32_e32 v21, v98, v73
	v_fmac_f32_e32 v22, v98, v74
	v_fmac_f32_e32 v23, v98, v75
	v_fmac_f32_e32 v24, v99, v72
	v_fmac_f32_e32 v25, v99, v73
	v_fmac_f32_e32 v26, v99, v74
	v_fmac_f32_e32 v27, v99, v75
	v_fmac_f32_e32 v28, v100, v72
	v_fmac_f32_e32 v29, v100, v73
	v_fmac_f32_e32 v30, v100, v74
	v_fmac_f32_e32 v31, v100, v75
	global_load_dwordx4 v[72:75], v11, s[10:11] nt
	s_add_u32 s10, s10, 0x18000
	s_addc_u32 s11, s11, 0
	ds_read_b32 v96, v10 offset:600
	ds_read_b32 v97, v10 offset:8792
	ds_read_b32 v98, v10 offset:16984
	ds_read_b32 v99, v10 offset:25176
	ds_read_b32 v100, v10 offset:33368
	s_waitcnt vmcnt(15) lgkmcnt(0)
	v_fmac_f32_e32 v12, v96, v76
	v_fmac_f32_e32 v13, v96, v77
	v_fmac_f32_e32 v14, v96, v78
	v_fmac_f32_e32 v15, v96, v79
	v_fmac_f32_e32 v16, v97, v76
	v_fmac_f32_e32 v17, v97, v77
	v_fmac_f32_e32 v18, v97, v78
	v_fmac_f32_e32 v19, v97, v79
	v_fmac_f32_e32 v20, v98, v76
	v_fmac_f32_e32 v21, v98, v77
	v_fmac_f32_e32 v22, v98, v78
	v_fmac_f32_e32 v23, v98, v79
	v_fmac_f32_e32 v24, v99, v76
	v_fmac_f32_e32 v25, v99, v77
	v_fmac_f32_e32 v26, v99, v78
	v_fmac_f32_e32 v27, v99, v79
	v_fmac_f32_e32 v28, v100, v76
	v_fmac_f32_e32 v29, v100, v77
	v_fmac_f32_e32 v30, v100, v78
	v_fmac_f32_e32 v31, v100, v79
	global_load_dwordx4 v[76:79], v11, s[10:11] nt
	s_add_u32 s10, s10, 0x18000
	s_addc_u32 s11, s11, 0
	ds_read_b32 v96, v10 offset:608
	ds_read_b32 v97, v10 offset:8800
	ds_read_b32 v98, v10 offset:16992
	ds_read_b32 v99, v10 offset:25184
	ds_read_b32 v100, v10 offset:33376
	s_waitcnt vmcnt(15) lgkmcnt(0)
	v_fmac_f32_e32 v12, v96, v80
	v_fmac_f32_e32 v13, v96, v81
	v_fmac_f32_e32 v14, v96, v82
	v_fmac_f32_e32 v15, v96, v83
	v_fmac_f32_e32 v16, v97, v80
	v_fmac_f32_e32 v17, v97, v81
	v_fmac_f32_e32 v18, v97, v82
	v_fmac_f32_e32 v19, v97, v83
	v_fmac_f32_e32 v20, v98, v80
	v_fmac_f32_e32 v21, v98, v81
	v_fmac_f32_e32 v22, v98, v82
	v_fmac_f32_e32 v23, v98, v83
	v_fmac_f32_e32 v24, v99, v80
	v_fmac_f32_e32 v25, v99, v81
	v_fmac_f32_e32 v26, v99, v82
	v_fmac_f32_e32 v27, v99, v83
	v_fmac_f32_e32 v28, v100, v80
	v_fmac_f32_e32 v29, v100, v81
	v_fmac_f32_e32 v30, v100, v82
	v_fmac_f32_e32 v31, v100, v83
	global_load_dwordx4 v[80:83], v11, s[10:11] nt
	s_add_u32 s10, s10, 0x18000
	s_addc_u32 s11, s11, 0
	ds_read_b32 v96, v10 offset:616
	ds_read_b32 v97, v10 offset:8808
	ds_read_b32 v98, v10 offset:17000
	ds_read_b32 v99, v10 offset:25192
	ds_read_b32 v100, v10 offset:33384
	s_waitcnt vmcnt(15) lgkmcnt(0)
	v_fmac_f32_e32 v12, v96, v84
	v_fmac_f32_e32 v13, v96, v85
	v_fmac_f32_e32 v14, v96, v86
	v_fmac_f32_e32 v15, v96, v87
	v_fmac_f32_e32 v16, v97, v84
	v_fmac_f32_e32 v17, v97, v85
	v_fmac_f32_e32 v18, v97, v86
	v_fmac_f32_e32 v19, v97, v87
	v_fmac_f32_e32 v20, v98, v84
	v_fmac_f32_e32 v21, v98, v85
	v_fmac_f32_e32 v22, v98, v86
	v_fmac_f32_e32 v23, v98, v87
	v_fmac_f32_e32 v24, v99, v84
	v_fmac_f32_e32 v25, v99, v85
	v_fmac_f32_e32 v26, v99, v86
	v_fmac_f32_e32 v27, v99, v87
	v_fmac_f32_e32 v28, v100, v84
	v_fmac_f32_e32 v29, v100, v85
	v_fmac_f32_e32 v30, v100, v86
	v_fmac_f32_e32 v31, v100, v87
	global_load_dwordx4 v[84:87], v11, s[10:11] nt
	s_add_u32 s10, s10, 0x18000
	s_addc_u32 s11, s11, 0
	ds_read_b32 v96, v10 offset:624
	ds_read_b32 v97, v10 offset:8816
	ds_read_b32 v98, v10 offset:17008
	ds_read_b32 v99, v10 offset:25200
	ds_read_b32 v100, v10 offset:33392
	s_waitcnt vmcnt(15) lgkmcnt(0)
	v_fmac_f32_e32 v12, v96, v88
	v_fmac_f32_e32 v13, v96, v89
	v_fmac_f32_e32 v14, v96, v90
	v_fmac_f32_e32 v15, v96, v91
	v_fmac_f32_e32 v16, v97, v88
	v_fmac_f32_e32 v17, v97, v89
	v_fmac_f32_e32 v18, v97, v90
	v_fmac_f32_e32 v19, v97, v91
	v_fmac_f32_e32 v20, v98, v88
	v_fmac_f32_e32 v21, v98, v89
	v_fmac_f32_e32 v22, v98, v90
	v_fmac_f32_e32 v23, v98, v91
	v_fmac_f32_e32 v24, v99, v88
	v_fmac_f32_e32 v25, v99, v89
	v_fmac_f32_e32 v26, v99, v90
	v_fmac_f32_e32 v27, v99, v91
	v_fmac_f32_e32 v28, v100, v88
	v_fmac_f32_e32 v29, v100, v89
	v_fmac_f32_e32 v30, v100, v90
	v_fmac_f32_e32 v31, v100, v91
	global_load_dwordx4 v[88:91], v11, s[10:11] nt
	s_add_u32 s10, s10, 0x18000
	s_addc_u32 s11, s11, 0
	ds_read_b32 v96, v10 offset:632
	ds_read_b32 v97, v10 offset:8824
	ds_read_b32 v98, v10 offset:17016
	ds_read_b32 v99, v10 offset:25208
	ds_read_b32 v100, v10 offset:33400
	s_waitcnt vmcnt(15) lgkmcnt(0)
	v_fmac_f32_e32 v12, v96, v92
	v_fmac_f32_e32 v13, v96, v93
	v_fmac_f32_e32 v14, v96, v94
	v_fmac_f32_e32 v15, v96, v95
	v_fmac_f32_e32 v16, v97, v92
	v_fmac_f32_e32 v17, v97, v93
	v_fmac_f32_e32 v18, v97, v94
	v_fmac_f32_e32 v19, v97, v95
	v_fmac_f32_e32 v20, v98, v92
	v_fmac_f32_e32 v21, v98, v93
	v_fmac_f32_e32 v22, v98, v94
	v_fmac_f32_e32 v23, v98, v95
	v_fmac_f32_e32 v24, v99, v92
	v_fmac_f32_e32 v25, v99, v93
	v_fmac_f32_e32 v26, v99, v94
	v_fmac_f32_e32 v27, v99, v95
	v_fmac_f32_e32 v28, v100, v92
	v_fmac_f32_e32 v29, v100, v93
	v_fmac_f32_e32 v30, v100, v94
	v_fmac_f32_e32 v31, v100, v95
	global_load_dwordx4 v[92:95], v11, s[10:11] nt
	s_add_u32 s10, s10, 0x18000
	s_addc_u32 s11, s11, 0
	ds_read_b32 v96, v10 offset:640
	ds_read_b32 v97, v10 offset:8832
	ds_read_b32 v98, v10 offset:17024
	ds_read_b32 v99, v10 offset:25216
	ds_read_b32 v100, v10 offset:33408
	s_waitcnt vmcnt(15) lgkmcnt(0)
	v_fmac_f32_e32 v12, v96, v32
	v_fmac_f32_e32 v13, v96, v33
	v_fmac_f32_e32 v14, v96, v34
	v_fmac_f32_e32 v15, v96, v35
	v_fmac_f32_e32 v16, v97, v32
	v_fmac_f32_e32 v17, v97, v33
	v_fmac_f32_e32 v18, v97, v34
	v_fmac_f32_e32 v19, v97, v35
	v_fmac_f32_e32 v20, v98, v32
	v_fmac_f32_e32 v21, v98, v33
	v_fmac_f32_e32 v22, v98, v34
	v_fmac_f32_e32 v23, v98, v35
	v_fmac_f32_e32 v24, v99, v32
	v_fmac_f32_e32 v25, v99, v33
	v_fmac_f32_e32 v26, v99, v34
	v_fmac_f32_e32 v27, v99, v35
	v_fmac_f32_e32 v28, v100, v32
	v_fmac_f32_e32 v29, v100, v33
	v_fmac_f32_e32 v30, v100, v34
	v_fmac_f32_e32 v31, v100, v35
	global_load_dwordx4 v[32:35], v11, s[10:11] nt
	s_add_u32 s10, s10, 0x18000
	s_addc_u32 s11, s11, 0
	ds_read_b32 v96, v10 offset:648
	ds_read_b32 v97, v10 offset:8840
	ds_read_b32 v98, v10 offset:17032
	ds_read_b32 v99, v10 offset:25224
	ds_read_b32 v100, v10 offset:33416
	s_waitcnt vmcnt(15) lgkmcnt(0)
	v_fmac_f32_e32 v12, v96, v36
	v_fmac_f32_e32 v13, v96, v37
	v_fmac_f32_e32 v14, v96, v38
	v_fmac_f32_e32 v15, v96, v39
	v_fmac_f32_e32 v16, v97, v36
	v_fmac_f32_e32 v17, v97, v37
	v_fmac_f32_e32 v18, v97, v38
	v_fmac_f32_e32 v19, v97, v39
	v_fmac_f32_e32 v20, v98, v36
	v_fmac_f32_e32 v21, v98, v37
	v_fmac_f32_e32 v22, v98, v38
	v_fmac_f32_e32 v23, v98, v39
	v_fmac_f32_e32 v24, v99, v36
	v_fmac_f32_e32 v25, v99, v37
	v_fmac_f32_e32 v26, v99, v38
	v_fmac_f32_e32 v27, v99, v39
	v_fmac_f32_e32 v28, v100, v36
	v_fmac_f32_e32 v29, v100, v37
	v_fmac_f32_e32 v30, v100, v38
	v_fmac_f32_e32 v31, v100, v39
	global_load_dwordx4 v[36:39], v11, s[10:11] nt
	s_add_u32 s10, s10, 0x18000
	s_addc_u32 s11, s11, 0
	ds_read_b32 v96, v10 offset:656
	ds_read_b32 v97, v10 offset:8848
	ds_read_b32 v98, v10 offset:17040
	ds_read_b32 v99, v10 offset:25232
	ds_read_b32 v100, v10 offset:33424
	s_waitcnt vmcnt(15) lgkmcnt(0)
	v_fmac_f32_e32 v12, v96, v40
	v_fmac_f32_e32 v13, v96, v41
	v_fmac_f32_e32 v14, v96, v42
	v_fmac_f32_e32 v15, v96, v43
	v_fmac_f32_e32 v16, v97, v40
	v_fmac_f32_e32 v17, v97, v41
	v_fmac_f32_e32 v18, v97, v42
	v_fmac_f32_e32 v19, v97, v43
	v_fmac_f32_e32 v20, v98, v40
	v_fmac_f32_e32 v21, v98, v41
	v_fmac_f32_e32 v22, v98, v42
	v_fmac_f32_e32 v23, v98, v43
	v_fmac_f32_e32 v24, v99, v40
	v_fmac_f32_e32 v25, v99, v41
	v_fmac_f32_e32 v26, v99, v42
	v_fmac_f32_e32 v27, v99, v43
	v_fmac_f32_e32 v28, v100, v40
	v_fmac_f32_e32 v29, v100, v41
	v_fmac_f32_e32 v30, v100, v42
	v_fmac_f32_e32 v31, v100, v43
	global_load_dwordx4 v[40:43], v11, s[10:11] nt
	s_add_u32 s10, s10, 0x18000
	s_addc_u32 s11, s11, 0
	ds_read_b32 v96, v10 offset:664
	ds_read_b32 v97, v10 offset:8856
	ds_read_b32 v98, v10 offset:17048
	ds_read_b32 v99, v10 offset:25240
	ds_read_b32 v100, v10 offset:33432
	s_waitcnt vmcnt(15) lgkmcnt(0)
	v_fmac_f32_e32 v12, v96, v44
	v_fmac_f32_e32 v13, v96, v45
	v_fmac_f32_e32 v14, v96, v46
	v_fmac_f32_e32 v15, v96, v47
	v_fmac_f32_e32 v16, v97, v44
	v_fmac_f32_e32 v17, v97, v45
	v_fmac_f32_e32 v18, v97, v46
	v_fmac_f32_e32 v19, v97, v47
	v_fmac_f32_e32 v20, v98, v44
	v_fmac_f32_e32 v21, v98, v45
	v_fmac_f32_e32 v22, v98, v46
	v_fmac_f32_e32 v23, v98, v47
	v_fmac_f32_e32 v24, v99, v44
	v_fmac_f32_e32 v25, v99, v45
	v_fmac_f32_e32 v26, v99, v46
	v_fmac_f32_e32 v27, v99, v47
	v_fmac_f32_e32 v28, v100, v44
	v_fmac_f32_e32 v29, v100, v45
	v_fmac_f32_e32 v30, v100, v46
	v_fmac_f32_e32 v31, v100, v47
	global_load_dwordx4 v[44:47], v11, s[10:11] nt
	s_add_u32 s10, s10, 0x18000
	s_addc_u32 s11, s11, 0
	ds_read_b32 v96, v10 offset:672
	ds_read_b32 v97, v10 offset:8864
	ds_read_b32 v98, v10 offset:17056
	ds_read_b32 v99, v10 offset:25248
	ds_read_b32 v100, v10 offset:33440
	s_waitcnt vmcnt(15) lgkmcnt(0)
	v_fmac_f32_e32 v12, v96, v48
	v_fmac_f32_e32 v13, v96, v49
	v_fmac_f32_e32 v14, v96, v50
	v_fmac_f32_e32 v15, v96, v51
	v_fmac_f32_e32 v16, v97, v48
	v_fmac_f32_e32 v17, v97, v49
	v_fmac_f32_e32 v18, v97, v50
	v_fmac_f32_e32 v19, v97, v51
	v_fmac_f32_e32 v20, v98, v48
	v_fmac_f32_e32 v21, v98, v49
	v_fmac_f32_e32 v22, v98, v50
	v_fmac_f32_e32 v23, v98, v51
	v_fmac_f32_e32 v24, v99, v48
	v_fmac_f32_e32 v25, v99, v49
	v_fmac_f32_e32 v26, v99, v50
	v_fmac_f32_e32 v27, v99, v51
	v_fmac_f32_e32 v28, v100, v48
	v_fmac_f32_e32 v29, v100, v49
	v_fmac_f32_e32 v30, v100, v50
	v_fmac_f32_e32 v31, v100, v51
	global_load_dwordx4 v[48:51], v11, s[10:11] nt
	s_add_u32 s10, s10, 0x18000
	s_addc_u32 s11, s11, 0
	ds_read_b32 v96, v10 offset:680
	ds_read_b32 v97, v10 offset:8872
	ds_read_b32 v98, v10 offset:17064
	ds_read_b32 v99, v10 offset:25256
	ds_read_b32 v100, v10 offset:33448
	s_waitcnt vmcnt(15) lgkmcnt(0)
	v_fmac_f32_e32 v12, v96, v52
	v_fmac_f32_e32 v13, v96, v53
	v_fmac_f32_e32 v14, v96, v54
	v_fmac_f32_e32 v15, v96, v55
	v_fmac_f32_e32 v16, v97, v52
	v_fmac_f32_e32 v17, v97, v53
	v_fmac_f32_e32 v18, v97, v54
	v_fmac_f32_e32 v19, v97, v55
	v_fmac_f32_e32 v20, v98, v52
	v_fmac_f32_e32 v21, v98, v53
	v_fmac_f32_e32 v22, v98, v54
	v_fmac_f32_e32 v23, v98, v55
	v_fmac_f32_e32 v24, v99, v52
	v_fmac_f32_e32 v25, v99, v53
	v_fmac_f32_e32 v26, v99, v54
	v_fmac_f32_e32 v27, v99, v55
	v_fmac_f32_e32 v28, v100, v52
	v_fmac_f32_e32 v29, v100, v53
	v_fmac_f32_e32 v30, v100, v54
	v_fmac_f32_e32 v31, v100, v55
	global_load_dwordx4 v[52:55], v11, s[10:11] nt
	s_add_u32 s10, s10, 0x18000
	s_addc_u32 s11, s11, 0
	ds_read_b32 v96, v10 offset:688
	ds_read_b32 v97, v10 offset:8880
	ds_read_b32 v98, v10 offset:17072
	ds_read_b32 v99, v10 offset:25264
	ds_read_b32 v100, v10 offset:33456
	s_waitcnt vmcnt(15) lgkmcnt(0)
	v_fmac_f32_e32 v12, v96, v56
	v_fmac_f32_e32 v13, v96, v57
	v_fmac_f32_e32 v14, v96, v58
	v_fmac_f32_e32 v15, v96, v59
	v_fmac_f32_e32 v16, v97, v56
	v_fmac_f32_e32 v17, v97, v57
	v_fmac_f32_e32 v18, v97, v58
	v_fmac_f32_e32 v19, v97, v59
	v_fmac_f32_e32 v20, v98, v56
	v_fmac_f32_e32 v21, v98, v57
	v_fmac_f32_e32 v22, v98, v58
	v_fmac_f32_e32 v23, v98, v59
	v_fmac_f32_e32 v24, v99, v56
	v_fmac_f32_e32 v25, v99, v57
	v_fmac_f32_e32 v26, v99, v58
	v_fmac_f32_e32 v27, v99, v59
	v_fmac_f32_e32 v28, v100, v56
	v_fmac_f32_e32 v29, v100, v57
	v_fmac_f32_e32 v30, v100, v58
	v_fmac_f32_e32 v31, v100, v59
	global_load_dwordx4 v[56:59], v11, s[10:11] nt
	s_add_u32 s10, s10, 0x18000
	s_addc_u32 s11, s11, 0
	ds_read_b32 v96, v10 offset:696
	ds_read_b32 v97, v10 offset:8888
	ds_read_b32 v98, v10 offset:17080
	ds_read_b32 v99, v10 offset:25272
	ds_read_b32 v100, v10 offset:33464
	s_waitcnt vmcnt(15) lgkmcnt(0)
	v_fmac_f32_e32 v12, v96, v60
	v_fmac_f32_e32 v13, v96, v61
	v_fmac_f32_e32 v14, v96, v62
	v_fmac_f32_e32 v15, v96, v63
	v_fmac_f32_e32 v16, v97, v60
	v_fmac_f32_e32 v17, v97, v61
	v_fmac_f32_e32 v18, v97, v62
	v_fmac_f32_e32 v19, v97, v63
	v_fmac_f32_e32 v20, v98, v60
	v_fmac_f32_e32 v21, v98, v61
	v_fmac_f32_e32 v22, v98, v62
	v_fmac_f32_e32 v23, v98, v63
	v_fmac_f32_e32 v24, v99, v60
	v_fmac_f32_e32 v25, v99, v61
	v_fmac_f32_e32 v26, v99, v62
	v_fmac_f32_e32 v27, v99, v63
	v_fmac_f32_e32 v28, v100, v60
	v_fmac_f32_e32 v29, v100, v61
	v_fmac_f32_e32 v30, v100, v62
	v_fmac_f32_e32 v31, v100, v63
	global_load_dwordx4 v[60:63], v11, s[10:11] nt
	s_add_u32 s10, s10, 0x18000
	s_addc_u32 s11, s11, 0
	ds_read_b32 v96, v10 offset:704
	ds_read_b32 v97, v10 offset:8896
	ds_read_b32 v98, v10 offset:17088
	ds_read_b32 v99, v10 offset:25280
	ds_read_b32 v100, v10 offset:33472
	s_waitcnt vmcnt(15) lgkmcnt(0)
	v_fmac_f32_e32 v12, v96, v64
	v_fmac_f32_e32 v13, v96, v65
	v_fmac_f32_e32 v14, v96, v66
	v_fmac_f32_e32 v15, v96, v67
	v_fmac_f32_e32 v16, v97, v64
	v_fmac_f32_e32 v17, v97, v65
	v_fmac_f32_e32 v18, v97, v66
	v_fmac_f32_e32 v19, v97, v67
	v_fmac_f32_e32 v20, v98, v64
	v_fmac_f32_e32 v21, v98, v65
	v_fmac_f32_e32 v22, v98, v66
	v_fmac_f32_e32 v23, v98, v67
	v_fmac_f32_e32 v24, v99, v64
	v_fmac_f32_e32 v25, v99, v65
	v_fmac_f32_e32 v26, v99, v66
	v_fmac_f32_e32 v27, v99, v67
	v_fmac_f32_e32 v28, v100, v64
	v_fmac_f32_e32 v29, v100, v65
	v_fmac_f32_e32 v30, v100, v66
	v_fmac_f32_e32 v31, v100, v67
	global_load_dwordx4 v[64:67], v11, s[10:11] nt
	s_add_u32 s10, s10, 0x18000
	s_addc_u32 s11, s11, 0
	ds_read_b32 v96, v10 offset:712
	ds_read_b32 v97, v10 offset:8904
	ds_read_b32 v98, v10 offset:17096
	ds_read_b32 v99, v10 offset:25288
	ds_read_b32 v100, v10 offset:33480
	s_waitcnt vmcnt(15) lgkmcnt(0)
	v_fmac_f32_e32 v12, v96, v68
	v_fmac_f32_e32 v13, v96, v69
	v_fmac_f32_e32 v14, v96, v70
	v_fmac_f32_e32 v15, v96, v71
	v_fmac_f32_e32 v16, v97, v68
	v_fmac_f32_e32 v17, v97, v69
	v_fmac_f32_e32 v18, v97, v70
	v_fmac_f32_e32 v19, v97, v71
	v_fmac_f32_e32 v20, v98, v68
	v_fmac_f32_e32 v21, v98, v69
	v_fmac_f32_e32 v22, v98, v70
	v_fmac_f32_e32 v23, v98, v71
	v_fmac_f32_e32 v24, v99, v68
	v_fmac_f32_e32 v25, v99, v69
	v_fmac_f32_e32 v26, v99, v70
	v_fmac_f32_e32 v27, v99, v71
	v_fmac_f32_e32 v28, v100, v68
	v_fmac_f32_e32 v29, v100, v69
	v_fmac_f32_e32 v30, v100, v70
	v_fmac_f32_e32 v31, v100, v71
	global_load_dwordx4 v[68:71], v11, s[10:11] nt
	s_add_u32 s10, s10, 0x18000
	s_addc_u32 s11, s11, 0
	ds_read_b32 v96, v10 offset:720
	ds_read_b32 v97, v10 offset:8912
	ds_read_b32 v98, v10 offset:17104
	ds_read_b32 v99, v10 offset:25296
	ds_read_b32 v100, v10 offset:33488
	s_waitcnt vmcnt(15) lgkmcnt(0)
	v_fmac_f32_e32 v12, v96, v72
	v_fmac_f32_e32 v13, v96, v73
	v_fmac_f32_e32 v14, v96, v74
	v_fmac_f32_e32 v15, v96, v75
	v_fmac_f32_e32 v16, v97, v72
	v_fmac_f32_e32 v17, v97, v73
	v_fmac_f32_e32 v18, v97, v74
	v_fmac_f32_e32 v19, v97, v75
	v_fmac_f32_e32 v20, v98, v72
	v_fmac_f32_e32 v21, v98, v73
	v_fmac_f32_e32 v22, v98, v74
	v_fmac_f32_e32 v23, v98, v75
	v_fmac_f32_e32 v24, v99, v72
	v_fmac_f32_e32 v25, v99, v73
	v_fmac_f32_e32 v26, v99, v74
	v_fmac_f32_e32 v27, v99, v75
	v_fmac_f32_e32 v28, v100, v72
	v_fmac_f32_e32 v29, v100, v73
	v_fmac_f32_e32 v30, v100, v74
	v_fmac_f32_e32 v31, v100, v75
	global_load_dwordx4 v[72:75], v11, s[10:11] nt
	s_add_u32 s10, s10, 0x18000
	s_addc_u32 s11, s11, 0
	ds_read_b32 v96, v10 offset:728
	ds_read_b32 v97, v10 offset:8920
	ds_read_b32 v98, v10 offset:17112
	ds_read_b32 v99, v10 offset:25304
	ds_read_b32 v100, v10 offset:33496
	s_waitcnt vmcnt(15) lgkmcnt(0)
	v_fmac_f32_e32 v12, v96, v76
	v_fmac_f32_e32 v13, v96, v77
	v_fmac_f32_e32 v14, v96, v78
	v_fmac_f32_e32 v15, v96, v79
	v_fmac_f32_e32 v16, v97, v76
	v_fmac_f32_e32 v17, v97, v77
	v_fmac_f32_e32 v18, v97, v78
	v_fmac_f32_e32 v19, v97, v79
	v_fmac_f32_e32 v20, v98, v76
	v_fmac_f32_e32 v21, v98, v77
	v_fmac_f32_e32 v22, v98, v78
	v_fmac_f32_e32 v23, v98, v79
	v_fmac_f32_e32 v24, v99, v76
	v_fmac_f32_e32 v25, v99, v77
	v_fmac_f32_e32 v26, v99, v78
	v_fmac_f32_e32 v27, v99, v79
	v_fmac_f32_e32 v28, v100, v76
	v_fmac_f32_e32 v29, v100, v77
	v_fmac_f32_e32 v30, v100, v78
	v_fmac_f32_e32 v31, v100, v79
	global_load_dwordx4 v[76:79], v11, s[10:11] nt
	s_add_u32 s10, s10, 0x18000
	s_addc_u32 s11, s11, 0
	ds_read_b32 v96, v10 offset:736
	ds_read_b32 v97, v10 offset:8928
	ds_read_b32 v98, v10 offset:17120
	ds_read_b32 v99, v10 offset:25312
	ds_read_b32 v100, v10 offset:33504
	s_waitcnt vmcnt(15) lgkmcnt(0)
	v_fmac_f32_e32 v12, v96, v80
	v_fmac_f32_e32 v13, v96, v81
	v_fmac_f32_e32 v14, v96, v82
	v_fmac_f32_e32 v15, v96, v83
	v_fmac_f32_e32 v16, v97, v80
	v_fmac_f32_e32 v17, v97, v81
	v_fmac_f32_e32 v18, v97, v82
	v_fmac_f32_e32 v19, v97, v83
	v_fmac_f32_e32 v20, v98, v80
	v_fmac_f32_e32 v21, v98, v81
	v_fmac_f32_e32 v22, v98, v82
	v_fmac_f32_e32 v23, v98, v83
	v_fmac_f32_e32 v24, v99, v80
	v_fmac_f32_e32 v25, v99, v81
	v_fmac_f32_e32 v26, v99, v82
	v_fmac_f32_e32 v27, v99, v83
	v_fmac_f32_e32 v28, v100, v80
	v_fmac_f32_e32 v29, v100, v81
	v_fmac_f32_e32 v30, v100, v82
	v_fmac_f32_e32 v31, v100, v83
	global_load_dwordx4 v[80:83], v11, s[10:11] nt
	s_add_u32 s10, s10, 0x18000
	s_addc_u32 s11, s11, 0
	ds_read_b32 v96, v10 offset:744
	ds_read_b32 v97, v10 offset:8936
	ds_read_b32 v98, v10 offset:17128
	ds_read_b32 v99, v10 offset:25320
	ds_read_b32 v100, v10 offset:33512
	s_waitcnt vmcnt(15) lgkmcnt(0)
	v_fmac_f32_e32 v12, v96, v84
	v_fmac_f32_e32 v13, v96, v85
	v_fmac_f32_e32 v14, v96, v86
	v_fmac_f32_e32 v15, v96, v87
	v_fmac_f32_e32 v16, v97, v84
	v_fmac_f32_e32 v17, v97, v85
	v_fmac_f32_e32 v18, v97, v86
	v_fmac_f32_e32 v19, v97, v87
	v_fmac_f32_e32 v20, v98, v84
	v_fmac_f32_e32 v21, v98, v85
	v_fmac_f32_e32 v22, v98, v86
	v_fmac_f32_e32 v23, v98, v87
	v_fmac_f32_e32 v24, v99, v84
	v_fmac_f32_e32 v25, v99, v85
	v_fmac_f32_e32 v26, v99, v86
	v_fmac_f32_e32 v27, v99, v87
	v_fmac_f32_e32 v28, v100, v84
	v_fmac_f32_e32 v29, v100, v85
	v_fmac_f32_e32 v30, v100, v86
	v_fmac_f32_e32 v31, v100, v87
	global_load_dwordx4 v[84:87], v11, s[10:11] nt
	s_add_u32 s10, s10, 0x18000
	s_addc_u32 s11, s11, 0
	ds_read_b32 v96, v10 offset:752
	ds_read_b32 v97, v10 offset:8944
	ds_read_b32 v98, v10 offset:17136
	ds_read_b32 v99, v10 offset:25328
	ds_read_b32 v100, v10 offset:33520
	s_waitcnt vmcnt(15) lgkmcnt(0)
	v_fmac_f32_e32 v12, v96, v88
	v_fmac_f32_e32 v13, v96, v89
	v_fmac_f32_e32 v14, v96, v90
	v_fmac_f32_e32 v15, v96, v91
	v_fmac_f32_e32 v16, v97, v88
	v_fmac_f32_e32 v17, v97, v89
	v_fmac_f32_e32 v18, v97, v90
	v_fmac_f32_e32 v19, v97, v91
	v_fmac_f32_e32 v20, v98, v88
	v_fmac_f32_e32 v21, v98, v89
	v_fmac_f32_e32 v22, v98, v90
	v_fmac_f32_e32 v23, v98, v91
	v_fmac_f32_e32 v24, v99, v88
	v_fmac_f32_e32 v25, v99, v89
	v_fmac_f32_e32 v26, v99, v90
	v_fmac_f32_e32 v27, v99, v91
	v_fmac_f32_e32 v28, v100, v88
	v_fmac_f32_e32 v29, v100, v89
	v_fmac_f32_e32 v30, v100, v90
	v_fmac_f32_e32 v31, v100, v91
	global_load_dwordx4 v[88:91], v11, s[10:11] nt
	s_add_u32 s10, s10, 0x18000
	s_addc_u32 s11, s11, 0
	ds_read_b32 v96, v10 offset:760
	ds_read_b32 v97, v10 offset:8952
	ds_read_b32 v98, v10 offset:17144
	ds_read_b32 v99, v10 offset:25336
	ds_read_b32 v100, v10 offset:33528
	s_waitcnt vmcnt(15) lgkmcnt(0)
	v_fmac_f32_e32 v12, v96, v92
	v_fmac_f32_e32 v13, v96, v93
	v_fmac_f32_e32 v14, v96, v94
	v_fmac_f32_e32 v15, v96, v95
	v_fmac_f32_e32 v16, v97, v92
	v_fmac_f32_e32 v17, v97, v93
	v_fmac_f32_e32 v18, v97, v94
	v_fmac_f32_e32 v19, v97, v95
	v_fmac_f32_e32 v20, v98, v92
	v_fmac_f32_e32 v21, v98, v93
	v_fmac_f32_e32 v22, v98, v94
	v_fmac_f32_e32 v23, v98, v95
	v_fmac_f32_e32 v24, v99, v92
	v_fmac_f32_e32 v25, v99, v93
	v_fmac_f32_e32 v26, v99, v94
	v_fmac_f32_e32 v27, v99, v95
	v_fmac_f32_e32 v28, v100, v92
	v_fmac_f32_e32 v29, v100, v93
	v_fmac_f32_e32 v30, v100, v94
	v_fmac_f32_e32 v31, v100, v95
	global_load_dwordx4 v[92:95], v11, s[10:11] nt
	s_add_u32 s10, s10, 0x18000
	s_addc_u32 s11, s11, 0
	ds_read_b32 v96, v10 offset:768
	ds_read_b32 v97, v10 offset:8960
	ds_read_b32 v98, v10 offset:17152
	ds_read_b32 v99, v10 offset:25344
	ds_read_b32 v100, v10 offset:33536
	s_waitcnt vmcnt(15) lgkmcnt(0)
	v_fmac_f32_e32 v12, v96, v32
	v_fmac_f32_e32 v13, v96, v33
	v_fmac_f32_e32 v14, v96, v34
	v_fmac_f32_e32 v15, v96, v35
	v_fmac_f32_e32 v16, v97, v32
	v_fmac_f32_e32 v17, v97, v33
	v_fmac_f32_e32 v18, v97, v34
	v_fmac_f32_e32 v19, v97, v35
	v_fmac_f32_e32 v20, v98, v32
	v_fmac_f32_e32 v21, v98, v33
	v_fmac_f32_e32 v22, v98, v34
	v_fmac_f32_e32 v23, v98, v35
	v_fmac_f32_e32 v24, v99, v32
	v_fmac_f32_e32 v25, v99, v33
	v_fmac_f32_e32 v26, v99, v34
	v_fmac_f32_e32 v27, v99, v35
	v_fmac_f32_e32 v28, v100, v32
	v_fmac_f32_e32 v29, v100, v33
	v_fmac_f32_e32 v30, v100, v34
	v_fmac_f32_e32 v31, v100, v35
	global_load_dwordx4 v[32:35], v11, s[10:11] nt
	s_add_u32 s10, s10, 0x18000
	s_addc_u32 s11, s11, 0
	ds_read_b32 v96, v10 offset:776
	ds_read_b32 v97, v10 offset:8968
	ds_read_b32 v98, v10 offset:17160
	ds_read_b32 v99, v10 offset:25352
	ds_read_b32 v100, v10 offset:33544
	s_waitcnt vmcnt(15) lgkmcnt(0)
	v_fmac_f32_e32 v12, v96, v36
	v_fmac_f32_e32 v13, v96, v37
	v_fmac_f32_e32 v14, v96, v38
	v_fmac_f32_e32 v15, v96, v39
	v_fmac_f32_e32 v16, v97, v36
	v_fmac_f32_e32 v17, v97, v37
	v_fmac_f32_e32 v18, v97, v38
	v_fmac_f32_e32 v19, v97, v39
	v_fmac_f32_e32 v20, v98, v36
	v_fmac_f32_e32 v21, v98, v37
	v_fmac_f32_e32 v22, v98, v38
	v_fmac_f32_e32 v23, v98, v39
	v_fmac_f32_e32 v24, v99, v36
	v_fmac_f32_e32 v25, v99, v37
	v_fmac_f32_e32 v26, v99, v38
	v_fmac_f32_e32 v27, v99, v39
	v_fmac_f32_e32 v28, v100, v36
	v_fmac_f32_e32 v29, v100, v37
	v_fmac_f32_e32 v30, v100, v38
	v_fmac_f32_e32 v31, v100, v39
	global_load_dwordx4 v[36:39], v11, s[10:11] nt
	s_add_u32 s10, s10, 0x18000
	s_addc_u32 s11, s11, 0
	ds_read_b32 v96, v10 offset:784
	ds_read_b32 v97, v10 offset:8976
	ds_read_b32 v98, v10 offset:17168
	ds_read_b32 v99, v10 offset:25360
	ds_read_b32 v100, v10 offset:33552
	s_waitcnt vmcnt(15) lgkmcnt(0)
	v_fmac_f32_e32 v12, v96, v40
	v_fmac_f32_e32 v13, v96, v41
	v_fmac_f32_e32 v14, v96, v42
	v_fmac_f32_e32 v15, v96, v43
	v_fmac_f32_e32 v16, v97, v40
	v_fmac_f32_e32 v17, v97, v41
	v_fmac_f32_e32 v18, v97, v42
	v_fmac_f32_e32 v19, v97, v43
	v_fmac_f32_e32 v20, v98, v40
	v_fmac_f32_e32 v21, v98, v41
	v_fmac_f32_e32 v22, v98, v42
	v_fmac_f32_e32 v23, v98, v43
	v_fmac_f32_e32 v24, v99, v40
	v_fmac_f32_e32 v25, v99, v41
	v_fmac_f32_e32 v26, v99, v42
	v_fmac_f32_e32 v27, v99, v43
	v_fmac_f32_e32 v28, v100, v40
	v_fmac_f32_e32 v29, v100, v41
	v_fmac_f32_e32 v30, v100, v42
	v_fmac_f32_e32 v31, v100, v43
	global_load_dwordx4 v[40:43], v11, s[10:11] nt
	s_add_u32 s10, s10, 0x18000
	s_addc_u32 s11, s11, 0
	ds_read_b32 v96, v10 offset:792
	ds_read_b32 v97, v10 offset:8984
	ds_read_b32 v98, v10 offset:17176
	ds_read_b32 v99, v10 offset:25368
	ds_read_b32 v100, v10 offset:33560
	s_waitcnt vmcnt(15) lgkmcnt(0)
	v_fmac_f32_e32 v12, v96, v44
	v_fmac_f32_e32 v13, v96, v45
	v_fmac_f32_e32 v14, v96, v46
	v_fmac_f32_e32 v15, v96, v47
	v_fmac_f32_e32 v16, v97, v44
	v_fmac_f32_e32 v17, v97, v45
	v_fmac_f32_e32 v18, v97, v46
	v_fmac_f32_e32 v19, v97, v47
	v_fmac_f32_e32 v20, v98, v44
	v_fmac_f32_e32 v21, v98, v45
	v_fmac_f32_e32 v22, v98, v46
	v_fmac_f32_e32 v23, v98, v47
	v_fmac_f32_e32 v24, v99, v44
	v_fmac_f32_e32 v25, v99, v45
	v_fmac_f32_e32 v26, v99, v46
	v_fmac_f32_e32 v27, v99, v47
	v_fmac_f32_e32 v28, v100, v44
	v_fmac_f32_e32 v29, v100, v45
	v_fmac_f32_e32 v30, v100, v46
	v_fmac_f32_e32 v31, v100, v47
	global_load_dwordx4 v[44:47], v11, s[10:11] nt
	s_add_u32 s10, s10, 0x18000
	s_addc_u32 s11, s11, 0
	ds_read_b32 v96, v10 offset:800
	ds_read_b32 v97, v10 offset:8992
	ds_read_b32 v98, v10 offset:17184
	ds_read_b32 v99, v10 offset:25376
	ds_read_b32 v100, v10 offset:33568
	s_waitcnt vmcnt(15) lgkmcnt(0)
	v_fmac_f32_e32 v12, v96, v48
	v_fmac_f32_e32 v13, v96, v49
	v_fmac_f32_e32 v14, v96, v50
	v_fmac_f32_e32 v15, v96, v51
	v_fmac_f32_e32 v16, v97, v48
	v_fmac_f32_e32 v17, v97, v49
	v_fmac_f32_e32 v18, v97, v50
	v_fmac_f32_e32 v19, v97, v51
	v_fmac_f32_e32 v20, v98, v48
	v_fmac_f32_e32 v21, v98, v49
	v_fmac_f32_e32 v22, v98, v50
	v_fmac_f32_e32 v23, v98, v51
	v_fmac_f32_e32 v24, v99, v48
	v_fmac_f32_e32 v25, v99, v49
	v_fmac_f32_e32 v26, v99, v50
	v_fmac_f32_e32 v27, v99, v51
	v_fmac_f32_e32 v28, v100, v48
	v_fmac_f32_e32 v29, v100, v49
	v_fmac_f32_e32 v30, v100, v50
	v_fmac_f32_e32 v31, v100, v51
	global_load_dwordx4 v[48:51], v11, s[10:11] nt
	s_add_u32 s10, s10, 0x18000
	s_addc_u32 s11, s11, 0
	ds_read_b32 v96, v10 offset:808
	ds_read_b32 v97, v10 offset:9000
	ds_read_b32 v98, v10 offset:17192
	ds_read_b32 v99, v10 offset:25384
	ds_read_b32 v100, v10 offset:33576
	s_waitcnt vmcnt(15) lgkmcnt(0)
	v_fmac_f32_e32 v12, v96, v52
	v_fmac_f32_e32 v13, v96, v53
	v_fmac_f32_e32 v14, v96, v54
	v_fmac_f32_e32 v15, v96, v55
	v_fmac_f32_e32 v16, v97, v52
	v_fmac_f32_e32 v17, v97, v53
	v_fmac_f32_e32 v18, v97, v54
	v_fmac_f32_e32 v19, v97, v55
	v_fmac_f32_e32 v20, v98, v52
	v_fmac_f32_e32 v21, v98, v53
	v_fmac_f32_e32 v22, v98, v54
	v_fmac_f32_e32 v23, v98, v55
	v_fmac_f32_e32 v24, v99, v52
	v_fmac_f32_e32 v25, v99, v53
	v_fmac_f32_e32 v26, v99, v54
	v_fmac_f32_e32 v27, v99, v55
	v_fmac_f32_e32 v28, v100, v52
	v_fmac_f32_e32 v29, v100, v53
	v_fmac_f32_e32 v30, v100, v54
	v_fmac_f32_e32 v31, v100, v55
	global_load_dwordx4 v[52:55], v11, s[10:11] nt
	s_add_u32 s10, s10, 0x18000
	s_addc_u32 s11, s11, 0
	ds_read_b32 v96, v10 offset:816
	ds_read_b32 v97, v10 offset:9008
	ds_read_b32 v98, v10 offset:17200
	ds_read_b32 v99, v10 offset:25392
	ds_read_b32 v100, v10 offset:33584
	s_waitcnt vmcnt(15) lgkmcnt(0)
	v_fmac_f32_e32 v12, v96, v56
	v_fmac_f32_e32 v13, v96, v57
	v_fmac_f32_e32 v14, v96, v58
	v_fmac_f32_e32 v15, v96, v59
	v_fmac_f32_e32 v16, v97, v56
	v_fmac_f32_e32 v17, v97, v57
	v_fmac_f32_e32 v18, v97, v58
	v_fmac_f32_e32 v19, v97, v59
	v_fmac_f32_e32 v20, v98, v56
	v_fmac_f32_e32 v21, v98, v57
	v_fmac_f32_e32 v22, v98, v58
	v_fmac_f32_e32 v23, v98, v59
	v_fmac_f32_e32 v24, v99, v56
	v_fmac_f32_e32 v25, v99, v57
	v_fmac_f32_e32 v26, v99, v58
	v_fmac_f32_e32 v27, v99, v59
	v_fmac_f32_e32 v28, v100, v56
	v_fmac_f32_e32 v29, v100, v57
	v_fmac_f32_e32 v30, v100, v58
	v_fmac_f32_e32 v31, v100, v59
	global_load_dwordx4 v[56:59], v11, s[10:11] nt
	s_add_u32 s10, s10, 0x18000
	s_addc_u32 s11, s11, 0
	ds_read_b32 v96, v10 offset:824
	ds_read_b32 v97, v10 offset:9016
	ds_read_b32 v98, v10 offset:17208
	ds_read_b32 v99, v10 offset:25400
	ds_read_b32 v100, v10 offset:33592
	s_waitcnt vmcnt(15) lgkmcnt(0)
	v_fmac_f32_e32 v12, v96, v60
	v_fmac_f32_e32 v13, v96, v61
	v_fmac_f32_e32 v14, v96, v62
	v_fmac_f32_e32 v15, v96, v63
	v_fmac_f32_e32 v16, v97, v60
	v_fmac_f32_e32 v17, v97, v61
	v_fmac_f32_e32 v18, v97, v62
	v_fmac_f32_e32 v19, v97, v63
	v_fmac_f32_e32 v20, v98, v60
	v_fmac_f32_e32 v21, v98, v61
	v_fmac_f32_e32 v22, v98, v62
	v_fmac_f32_e32 v23, v98, v63
	v_fmac_f32_e32 v24, v99, v60
	v_fmac_f32_e32 v25, v99, v61
	v_fmac_f32_e32 v26, v99, v62
	v_fmac_f32_e32 v27, v99, v63
	v_fmac_f32_e32 v28, v100, v60
	v_fmac_f32_e32 v29, v100, v61
	v_fmac_f32_e32 v30, v100, v62
	v_fmac_f32_e32 v31, v100, v63
	global_load_dwordx4 v[60:63], v11, s[10:11] nt
	s_add_u32 s10, s10, 0x18000
	s_addc_u32 s11, s11, 0
	ds_read_b32 v96, v10 offset:832
	ds_read_b32 v97, v10 offset:9024
	ds_read_b32 v98, v10 offset:17216
	ds_read_b32 v99, v10 offset:25408
	ds_read_b32 v100, v10 offset:33600
	s_waitcnt vmcnt(15) lgkmcnt(0)
	v_fmac_f32_e32 v12, v96, v64
	v_fmac_f32_e32 v13, v96, v65
	v_fmac_f32_e32 v14, v96, v66
	v_fmac_f32_e32 v15, v96, v67
	v_fmac_f32_e32 v16, v97, v64
	v_fmac_f32_e32 v17, v97, v65
	v_fmac_f32_e32 v18, v97, v66
	v_fmac_f32_e32 v19, v97, v67
	v_fmac_f32_e32 v20, v98, v64
	v_fmac_f32_e32 v21, v98, v65
	v_fmac_f32_e32 v22, v98, v66
	v_fmac_f32_e32 v23, v98, v67
	v_fmac_f32_e32 v24, v99, v64
	v_fmac_f32_e32 v25, v99, v65
	v_fmac_f32_e32 v26, v99, v66
	v_fmac_f32_e32 v27, v99, v67
	v_fmac_f32_e32 v28, v100, v64
	v_fmac_f32_e32 v29, v100, v65
	v_fmac_f32_e32 v30, v100, v66
	v_fmac_f32_e32 v31, v100, v67
	global_load_dwordx4 v[64:67], v11, s[10:11] nt
	s_add_u32 s10, s10, 0x18000
	s_addc_u32 s11, s11, 0
	ds_read_b32 v96, v10 offset:840
	ds_read_b32 v97, v10 offset:9032
	ds_read_b32 v98, v10 offset:17224
	ds_read_b32 v99, v10 offset:25416
	ds_read_b32 v100, v10 offset:33608
	s_waitcnt vmcnt(15) lgkmcnt(0)
	v_fmac_f32_e32 v12, v96, v68
	v_fmac_f32_e32 v13, v96, v69
	v_fmac_f32_e32 v14, v96, v70
	v_fmac_f32_e32 v15, v96, v71
	v_fmac_f32_e32 v16, v97, v68
	v_fmac_f32_e32 v17, v97, v69
	v_fmac_f32_e32 v18, v97, v70
	v_fmac_f32_e32 v19, v97, v71
	v_fmac_f32_e32 v20, v98, v68
	v_fmac_f32_e32 v21, v98, v69
	v_fmac_f32_e32 v22, v98, v70
	v_fmac_f32_e32 v23, v98, v71
	v_fmac_f32_e32 v24, v99, v68
	v_fmac_f32_e32 v25, v99, v69
	v_fmac_f32_e32 v26, v99, v70
	v_fmac_f32_e32 v27, v99, v71
	v_fmac_f32_e32 v28, v100, v68
	v_fmac_f32_e32 v29, v100, v69
	v_fmac_f32_e32 v30, v100, v70
	v_fmac_f32_e32 v31, v100, v71
	global_load_dwordx4 v[68:71], v11, s[10:11] nt
	s_add_u32 s10, s10, 0x18000
	s_addc_u32 s11, s11, 0
	ds_read_b32 v96, v10 offset:848
	ds_read_b32 v97, v10 offset:9040
	ds_read_b32 v98, v10 offset:17232
	ds_read_b32 v99, v10 offset:25424
	ds_read_b32 v100, v10 offset:33616
	s_waitcnt vmcnt(15) lgkmcnt(0)
	v_fmac_f32_e32 v12, v96, v72
	v_fmac_f32_e32 v13, v96, v73
	v_fmac_f32_e32 v14, v96, v74
	v_fmac_f32_e32 v15, v96, v75
	v_fmac_f32_e32 v16, v97, v72
	v_fmac_f32_e32 v17, v97, v73
	v_fmac_f32_e32 v18, v97, v74
	v_fmac_f32_e32 v19, v97, v75
	v_fmac_f32_e32 v20, v98, v72
	v_fmac_f32_e32 v21, v98, v73
	v_fmac_f32_e32 v22, v98, v74
	v_fmac_f32_e32 v23, v98, v75
	v_fmac_f32_e32 v24, v99, v72
	v_fmac_f32_e32 v25, v99, v73
	v_fmac_f32_e32 v26, v99, v74
	v_fmac_f32_e32 v27, v99, v75
	v_fmac_f32_e32 v28, v100, v72
	v_fmac_f32_e32 v29, v100, v73
	v_fmac_f32_e32 v30, v100, v74
	v_fmac_f32_e32 v31, v100, v75
	global_load_dwordx4 v[72:75], v11, s[10:11] nt
	s_add_u32 s10, s10, 0x18000
	s_addc_u32 s11, s11, 0
	ds_read_b32 v96, v10 offset:856
	ds_read_b32 v97, v10 offset:9048
	ds_read_b32 v98, v10 offset:17240
	ds_read_b32 v99, v10 offset:25432
	ds_read_b32 v100, v10 offset:33624
	s_waitcnt vmcnt(15) lgkmcnt(0)
	v_fmac_f32_e32 v12, v96, v76
	v_fmac_f32_e32 v13, v96, v77
	v_fmac_f32_e32 v14, v96, v78
	v_fmac_f32_e32 v15, v96, v79
	v_fmac_f32_e32 v16, v97, v76
	v_fmac_f32_e32 v17, v97, v77
	v_fmac_f32_e32 v18, v97, v78
	v_fmac_f32_e32 v19, v97, v79
	v_fmac_f32_e32 v20, v98, v76
	v_fmac_f32_e32 v21, v98, v77
	v_fmac_f32_e32 v22, v98, v78
	v_fmac_f32_e32 v23, v98, v79
	v_fmac_f32_e32 v24, v99, v76
	v_fmac_f32_e32 v25, v99, v77
	v_fmac_f32_e32 v26, v99, v78
	v_fmac_f32_e32 v27, v99, v79
	v_fmac_f32_e32 v28, v100, v76
	v_fmac_f32_e32 v29, v100, v77
	v_fmac_f32_e32 v30, v100, v78
	v_fmac_f32_e32 v31, v100, v79
	global_load_dwordx4 v[76:79], v11, s[10:11] nt
	s_add_u32 s10, s10, 0x18000
	s_addc_u32 s11, s11, 0
	ds_read_b32 v96, v10 offset:864
	ds_read_b32 v97, v10 offset:9056
	ds_read_b32 v98, v10 offset:17248
	ds_read_b32 v99, v10 offset:25440
	ds_read_b32 v100, v10 offset:33632
	s_waitcnt vmcnt(15) lgkmcnt(0)
	v_fmac_f32_e32 v12, v96, v80
	v_fmac_f32_e32 v13, v96, v81
	v_fmac_f32_e32 v14, v96, v82
	v_fmac_f32_e32 v15, v96, v83
	v_fmac_f32_e32 v16, v97, v80
	v_fmac_f32_e32 v17, v97, v81
	v_fmac_f32_e32 v18, v97, v82
	v_fmac_f32_e32 v19, v97, v83
	v_fmac_f32_e32 v20, v98, v80
	v_fmac_f32_e32 v21, v98, v81
	v_fmac_f32_e32 v22, v98, v82
	v_fmac_f32_e32 v23, v98, v83
	v_fmac_f32_e32 v24, v99, v80
	v_fmac_f32_e32 v25, v99, v81
	v_fmac_f32_e32 v26, v99, v82
	v_fmac_f32_e32 v27, v99, v83
	v_fmac_f32_e32 v28, v100, v80
	v_fmac_f32_e32 v29, v100, v81
	v_fmac_f32_e32 v30, v100, v82
	v_fmac_f32_e32 v31, v100, v83
	global_load_dwordx4 v[80:83], v11, s[10:11] nt
	s_add_u32 s10, s10, 0x18000
	s_addc_u32 s11, s11, 0
	ds_read_b32 v96, v10 offset:872
	ds_read_b32 v97, v10 offset:9064
	ds_read_b32 v98, v10 offset:17256
	ds_read_b32 v99, v10 offset:25448
	ds_read_b32 v100, v10 offset:33640
	s_waitcnt vmcnt(15) lgkmcnt(0)
	v_fmac_f32_e32 v12, v96, v84
	v_fmac_f32_e32 v13, v96, v85
	v_fmac_f32_e32 v14, v96, v86
	v_fmac_f32_e32 v15, v96, v87
	v_fmac_f32_e32 v16, v97, v84
	v_fmac_f32_e32 v17, v97, v85
	v_fmac_f32_e32 v18, v97, v86
	v_fmac_f32_e32 v19, v97, v87
	v_fmac_f32_e32 v20, v98, v84
	v_fmac_f32_e32 v21, v98, v85
	v_fmac_f32_e32 v22, v98, v86
	v_fmac_f32_e32 v23, v98, v87
	v_fmac_f32_e32 v24, v99, v84
	v_fmac_f32_e32 v25, v99, v85
	v_fmac_f32_e32 v26, v99, v86
	v_fmac_f32_e32 v27, v99, v87
	v_fmac_f32_e32 v28, v100, v84
	v_fmac_f32_e32 v29, v100, v85
	v_fmac_f32_e32 v30, v100, v86
	v_fmac_f32_e32 v31, v100, v87
	global_load_dwordx4 v[84:87], v11, s[10:11] nt
	s_add_u32 s10, s10, 0x18000
	s_addc_u32 s11, s11, 0
	ds_read_b32 v96, v10 offset:880
	ds_read_b32 v97, v10 offset:9072
	ds_read_b32 v98, v10 offset:17264
	ds_read_b32 v99, v10 offset:25456
	ds_read_b32 v100, v10 offset:33648
	s_waitcnt vmcnt(15) lgkmcnt(0)
	v_fmac_f32_e32 v12, v96, v88
	v_fmac_f32_e32 v13, v96, v89
	v_fmac_f32_e32 v14, v96, v90
	v_fmac_f32_e32 v15, v96, v91
	v_fmac_f32_e32 v16, v97, v88
	v_fmac_f32_e32 v17, v97, v89
	v_fmac_f32_e32 v18, v97, v90
	v_fmac_f32_e32 v19, v97, v91
	v_fmac_f32_e32 v20, v98, v88
	v_fmac_f32_e32 v21, v98, v89
	v_fmac_f32_e32 v22, v98, v90
	v_fmac_f32_e32 v23, v98, v91
	v_fmac_f32_e32 v24, v99, v88
	v_fmac_f32_e32 v25, v99, v89
	v_fmac_f32_e32 v26, v99, v90
	v_fmac_f32_e32 v27, v99, v91
	v_fmac_f32_e32 v28, v100, v88
	v_fmac_f32_e32 v29, v100, v89
	v_fmac_f32_e32 v30, v100, v90
	v_fmac_f32_e32 v31, v100, v91
	global_load_dwordx4 v[88:91], v11, s[10:11] nt
	s_add_u32 s10, s10, 0x18000
	s_addc_u32 s11, s11, 0
	ds_read_b32 v96, v10 offset:888
	ds_read_b32 v97, v10 offset:9080
	ds_read_b32 v98, v10 offset:17272
	ds_read_b32 v99, v10 offset:25464
	ds_read_b32 v100, v10 offset:33656
	s_waitcnt vmcnt(15) lgkmcnt(0)
	v_fmac_f32_e32 v12, v96, v92
	v_fmac_f32_e32 v13, v96, v93
	v_fmac_f32_e32 v14, v96, v94
	v_fmac_f32_e32 v15, v96, v95
	v_fmac_f32_e32 v16, v97, v92
	v_fmac_f32_e32 v17, v97, v93
	v_fmac_f32_e32 v18, v97, v94
	v_fmac_f32_e32 v19, v97, v95
	v_fmac_f32_e32 v20, v98, v92
	v_fmac_f32_e32 v21, v98, v93
	v_fmac_f32_e32 v22, v98, v94
	v_fmac_f32_e32 v23, v98, v95
	v_fmac_f32_e32 v24, v99, v92
	v_fmac_f32_e32 v25, v99, v93
	v_fmac_f32_e32 v26, v99, v94
	v_fmac_f32_e32 v27, v99, v95
	v_fmac_f32_e32 v28, v100, v92
	v_fmac_f32_e32 v29, v100, v93
	v_fmac_f32_e32 v30, v100, v94
	v_fmac_f32_e32 v31, v100, v95
	global_load_dwordx4 v[92:95], v11, s[10:11] nt
	s_add_u32 s10, s10, 0x18000
	s_addc_u32 s11, s11, 0
	ds_read_b32 v96, v10 offset:896
	ds_read_b32 v97, v10 offset:9088
	ds_read_b32 v98, v10 offset:17280
	ds_read_b32 v99, v10 offset:25472
	ds_read_b32 v100, v10 offset:33664
	s_waitcnt vmcnt(15) lgkmcnt(0)
	v_fmac_f32_e32 v12, v96, v32
	v_fmac_f32_e32 v13, v96, v33
	v_fmac_f32_e32 v14, v96, v34
	v_fmac_f32_e32 v15, v96, v35
	v_fmac_f32_e32 v16, v97, v32
	v_fmac_f32_e32 v17, v97, v33
	v_fmac_f32_e32 v18, v97, v34
	v_fmac_f32_e32 v19, v97, v35
	v_fmac_f32_e32 v20, v98, v32
	v_fmac_f32_e32 v21, v98, v33
	v_fmac_f32_e32 v22, v98, v34
	v_fmac_f32_e32 v23, v98, v35
	v_fmac_f32_e32 v24, v99, v32
	v_fmac_f32_e32 v25, v99, v33
	v_fmac_f32_e32 v26, v99, v34
	v_fmac_f32_e32 v27, v99, v35
	v_fmac_f32_e32 v28, v100, v32
	v_fmac_f32_e32 v29, v100, v33
	v_fmac_f32_e32 v30, v100, v34
	v_fmac_f32_e32 v31, v100, v35
	ds_read_b32 v96, v10 offset:904
	ds_read_b32 v97, v10 offset:9096
	ds_read_b32 v98, v10 offset:17288
	ds_read_b32 v99, v10 offset:25480
	ds_read_b32 v100, v10 offset:33672
	s_waitcnt vmcnt(14) lgkmcnt(0)
	v_fmac_f32_e32 v12, v96, v36
	v_fmac_f32_e32 v13, v96, v37
	v_fmac_f32_e32 v14, v96, v38
	v_fmac_f32_e32 v15, v96, v39
	v_fmac_f32_e32 v16, v97, v36
	v_fmac_f32_e32 v17, v97, v37
	v_fmac_f32_e32 v18, v97, v38
	v_fmac_f32_e32 v19, v97, v39
	v_fmac_f32_e32 v20, v98, v36
	v_fmac_f32_e32 v21, v98, v37
	v_fmac_f32_e32 v22, v98, v38
	v_fmac_f32_e32 v23, v98, v39
	v_fmac_f32_e32 v24, v99, v36
	v_fmac_f32_e32 v25, v99, v37
	v_fmac_f32_e32 v26, v99, v38
	v_fmac_f32_e32 v27, v99, v39
	v_fmac_f32_e32 v28, v100, v36
	v_fmac_f32_e32 v29, v100, v37
	v_fmac_f32_e32 v30, v100, v38
	v_fmac_f32_e32 v31, v100, v39
	ds_read_b32 v96, v10 offset:912
	ds_read_b32 v97, v10 offset:9104
	ds_read_b32 v98, v10 offset:17296
	ds_read_b32 v99, v10 offset:25488
	ds_read_b32 v100, v10 offset:33680
	s_waitcnt vmcnt(13) lgkmcnt(0)
	v_fmac_f32_e32 v12, v96, v40
	v_fmac_f32_e32 v13, v96, v41
	v_fmac_f32_e32 v14, v96, v42
	v_fmac_f32_e32 v15, v96, v43
	v_fmac_f32_e32 v16, v97, v40
	v_fmac_f32_e32 v17, v97, v41
	v_fmac_f32_e32 v18, v97, v42
	v_fmac_f32_e32 v19, v97, v43
	v_fmac_f32_e32 v20, v98, v40
	v_fmac_f32_e32 v21, v98, v41
	v_fmac_f32_e32 v22, v98, v42
	v_fmac_f32_e32 v23, v98, v43
	v_fmac_f32_e32 v24, v99, v40
	v_fmac_f32_e32 v25, v99, v41
	v_fmac_f32_e32 v26, v99, v42
	v_fmac_f32_e32 v27, v99, v43
	v_fmac_f32_e32 v28, v100, v40
	v_fmac_f32_e32 v29, v100, v41
	v_fmac_f32_e32 v30, v100, v42
	v_fmac_f32_e32 v31, v100, v43
	ds_read_b32 v96, v10 offset:920
	ds_read_b32 v97, v10 offset:9112
	ds_read_b32 v98, v10 offset:17304
	ds_read_b32 v99, v10 offset:25496
	ds_read_b32 v100, v10 offset:33688
	s_waitcnt vmcnt(12) lgkmcnt(0)
	v_fmac_f32_e32 v12, v96, v44
	v_fmac_f32_e32 v13, v96, v45
	v_fmac_f32_e32 v14, v96, v46
	v_fmac_f32_e32 v15, v96, v47
	v_fmac_f32_e32 v16, v97, v44
	v_fmac_f32_e32 v17, v97, v45
	v_fmac_f32_e32 v18, v97, v46
	v_fmac_f32_e32 v19, v97, v47
	v_fmac_f32_e32 v20, v98, v44
	v_fmac_f32_e32 v21, v98, v45
	v_fmac_f32_e32 v22, v98, v46
	v_fmac_f32_e32 v23, v98, v47
	v_fmac_f32_e32 v24, v99, v44
	v_fmac_f32_e32 v25, v99, v45
	v_fmac_f32_e32 v26, v99, v46
	v_fmac_f32_e32 v27, v99, v47
	v_fmac_f32_e32 v28, v100, v44
	v_fmac_f32_e32 v29, v100, v45
	v_fmac_f32_e32 v30, v100, v46
	v_fmac_f32_e32 v31, v100, v47
	ds_read_b32 v96, v10 offset:928
	ds_read_b32 v97, v10 offset:9120
	ds_read_b32 v98, v10 offset:17312
	ds_read_b32 v99, v10 offset:25504
	ds_read_b32 v100, v10 offset:33696
	s_waitcnt vmcnt(11) lgkmcnt(0)
	v_fmac_f32_e32 v12, v96, v48
	v_fmac_f32_e32 v13, v96, v49
	v_fmac_f32_e32 v14, v96, v50
	v_fmac_f32_e32 v15, v96, v51
	v_fmac_f32_e32 v16, v97, v48
	v_fmac_f32_e32 v17, v97, v49
	v_fmac_f32_e32 v18, v97, v50
	v_fmac_f32_e32 v19, v97, v51
	v_fmac_f32_e32 v20, v98, v48
	v_fmac_f32_e32 v21, v98, v49
	v_fmac_f32_e32 v22, v98, v50
	v_fmac_f32_e32 v23, v98, v51
	v_fmac_f32_e32 v24, v99, v48
	v_fmac_f32_e32 v25, v99, v49
	v_fmac_f32_e32 v26, v99, v50
	v_fmac_f32_e32 v27, v99, v51
	v_fmac_f32_e32 v28, v100, v48
	v_fmac_f32_e32 v29, v100, v49
	v_fmac_f32_e32 v30, v100, v50
	v_fmac_f32_e32 v31, v100, v51
	ds_read_b32 v96, v10 offset:936
	ds_read_b32 v97, v10 offset:9128
	ds_read_b32 v98, v10 offset:17320
	ds_read_b32 v99, v10 offset:25512
	ds_read_b32 v100, v10 offset:33704
	s_waitcnt vmcnt(10) lgkmcnt(0)
	v_fmac_f32_e32 v12, v96, v52
	v_fmac_f32_e32 v13, v96, v53
	v_fmac_f32_e32 v14, v96, v54
	v_fmac_f32_e32 v15, v96, v55
	v_fmac_f32_e32 v16, v97, v52
	v_fmac_f32_e32 v17, v97, v53
	v_fmac_f32_e32 v18, v97, v54
	v_fmac_f32_e32 v19, v97, v55
	v_fmac_f32_e32 v20, v98, v52
	v_fmac_f32_e32 v21, v98, v53
	v_fmac_f32_e32 v22, v98, v54
	v_fmac_f32_e32 v23, v98, v55
	v_fmac_f32_e32 v24, v99, v52
	v_fmac_f32_e32 v25, v99, v53
	v_fmac_f32_e32 v26, v99, v54
	v_fmac_f32_e32 v27, v99, v55
	v_fmac_f32_e32 v28, v100, v52
	v_fmac_f32_e32 v29, v100, v53
	v_fmac_f32_e32 v30, v100, v54
	v_fmac_f32_e32 v31, v100, v55
	ds_read_b32 v96, v10 offset:944
	ds_read_b32 v97, v10 offset:9136
	ds_read_b32 v98, v10 offset:17328
	ds_read_b32 v99, v10 offset:25520
	ds_read_b32 v100, v10 offset:33712
	s_waitcnt vmcnt(9) lgkmcnt(0)
	v_fmac_f32_e32 v12, v96, v56
	v_fmac_f32_e32 v13, v96, v57
	v_fmac_f32_e32 v14, v96, v58
	v_fmac_f32_e32 v15, v96, v59
	v_fmac_f32_e32 v16, v97, v56
	v_fmac_f32_e32 v17, v97, v57
	v_fmac_f32_e32 v18, v97, v58
	v_fmac_f32_e32 v19, v97, v59
	v_fmac_f32_e32 v20, v98, v56
	v_fmac_f32_e32 v21, v98, v57
	v_fmac_f32_e32 v22, v98, v58
	v_fmac_f32_e32 v23, v98, v59
	v_fmac_f32_e32 v24, v99, v56
	v_fmac_f32_e32 v25, v99, v57
	v_fmac_f32_e32 v26, v99, v58
	v_fmac_f32_e32 v27, v99, v59
	v_fmac_f32_e32 v28, v100, v56
	v_fmac_f32_e32 v29, v100, v57
	v_fmac_f32_e32 v30, v100, v58
	v_fmac_f32_e32 v31, v100, v59
	ds_read_b32 v96, v10 offset:952
	ds_read_b32 v97, v10 offset:9144
	ds_read_b32 v98, v10 offset:17336
	ds_read_b32 v99, v10 offset:25528
	ds_read_b32 v100, v10 offset:33720
	s_waitcnt vmcnt(8) lgkmcnt(0)
	v_fmac_f32_e32 v12, v96, v60
	v_fmac_f32_e32 v13, v96, v61
	v_fmac_f32_e32 v14, v96, v62
	v_fmac_f32_e32 v15, v96, v63
	v_fmac_f32_e32 v16, v97, v60
	v_fmac_f32_e32 v17, v97, v61
	v_fmac_f32_e32 v18, v97, v62
	v_fmac_f32_e32 v19, v97, v63
	v_fmac_f32_e32 v20, v98, v60
	v_fmac_f32_e32 v21, v98, v61
	v_fmac_f32_e32 v22, v98, v62
	v_fmac_f32_e32 v23, v98, v63
	v_fmac_f32_e32 v24, v99, v60
	v_fmac_f32_e32 v25, v99, v61
	v_fmac_f32_e32 v26, v99, v62
	v_fmac_f32_e32 v27, v99, v63
	v_fmac_f32_e32 v28, v100, v60
	v_fmac_f32_e32 v29, v100, v61
	v_fmac_f32_e32 v30, v100, v62
	v_fmac_f32_e32 v31, v100, v63
	ds_read_b32 v96, v10 offset:960
	ds_read_b32 v97, v10 offset:9152
	ds_read_b32 v98, v10 offset:17344
	ds_read_b32 v99, v10 offset:25536
	ds_read_b32 v100, v10 offset:33728
	s_waitcnt vmcnt(7) lgkmcnt(0)
	v_fmac_f32_e32 v12, v96, v64
	v_fmac_f32_e32 v13, v96, v65
	v_fmac_f32_e32 v14, v96, v66
	v_fmac_f32_e32 v15, v96, v67
	v_fmac_f32_e32 v16, v97, v64
	v_fmac_f32_e32 v17, v97, v65
	v_fmac_f32_e32 v18, v97, v66
	v_fmac_f32_e32 v19, v97, v67
	v_fmac_f32_e32 v20, v98, v64
	v_fmac_f32_e32 v21, v98, v65
	v_fmac_f32_e32 v22, v98, v66
	v_fmac_f32_e32 v23, v98, v67
	v_fmac_f32_e32 v24, v99, v64
	v_fmac_f32_e32 v25, v99, v65
	v_fmac_f32_e32 v26, v99, v66
	v_fmac_f32_e32 v27, v99, v67
	v_fmac_f32_e32 v28, v100, v64
	v_fmac_f32_e32 v29, v100, v65
	v_fmac_f32_e32 v30, v100, v66
	v_fmac_f32_e32 v31, v100, v67
	ds_read_b32 v96, v10 offset:968
	ds_read_b32 v97, v10 offset:9160
	ds_read_b32 v98, v10 offset:17352
	ds_read_b32 v99, v10 offset:25544
	ds_read_b32 v100, v10 offset:33736
	s_waitcnt vmcnt(6) lgkmcnt(0)
	v_fmac_f32_e32 v12, v96, v68
	v_fmac_f32_e32 v13, v96, v69
	v_fmac_f32_e32 v14, v96, v70
	v_fmac_f32_e32 v15, v96, v71
	v_fmac_f32_e32 v16, v97, v68
	v_fmac_f32_e32 v17, v97, v69
	v_fmac_f32_e32 v18, v97, v70
	v_fmac_f32_e32 v19, v97, v71
	v_fmac_f32_e32 v20, v98, v68
	v_fmac_f32_e32 v21, v98, v69
	v_fmac_f32_e32 v22, v98, v70
	v_fmac_f32_e32 v23, v98, v71
	v_fmac_f32_e32 v24, v99, v68
	v_fmac_f32_e32 v25, v99, v69
	v_fmac_f32_e32 v26, v99, v70
	v_fmac_f32_e32 v27, v99, v71
	v_fmac_f32_e32 v28, v100, v68
	v_fmac_f32_e32 v29, v100, v69
	v_fmac_f32_e32 v30, v100, v70
	v_fmac_f32_e32 v31, v100, v71
	ds_read_b32 v96, v10 offset:976
	ds_read_b32 v97, v10 offset:9168
	ds_read_b32 v98, v10 offset:17360
	ds_read_b32 v99, v10 offset:25552
	ds_read_b32 v100, v10 offset:33744
	s_waitcnt vmcnt(5) lgkmcnt(0)
	v_fmac_f32_e32 v12, v96, v72
	v_fmac_f32_e32 v13, v96, v73
	v_fmac_f32_e32 v14, v96, v74
	v_fmac_f32_e32 v15, v96, v75
	v_fmac_f32_e32 v16, v97, v72
	v_fmac_f32_e32 v17, v97, v73
	v_fmac_f32_e32 v18, v97, v74
	v_fmac_f32_e32 v19, v97, v75
	v_fmac_f32_e32 v20, v98, v72
	v_fmac_f32_e32 v21, v98, v73
	v_fmac_f32_e32 v22, v98, v74
	v_fmac_f32_e32 v23, v98, v75
	v_fmac_f32_e32 v24, v99, v72
	v_fmac_f32_e32 v25, v99, v73
	v_fmac_f32_e32 v26, v99, v74
	v_fmac_f32_e32 v27, v99, v75
	v_fmac_f32_e32 v28, v100, v72
	v_fmac_f32_e32 v29, v100, v73
	v_fmac_f32_e32 v30, v100, v74
	v_fmac_f32_e32 v31, v100, v75
	ds_read_b32 v96, v10 offset:984
	ds_read_b32 v97, v10 offset:9176
	ds_read_b32 v98, v10 offset:17368
	ds_read_b32 v99, v10 offset:25560
	ds_read_b32 v100, v10 offset:33752
	s_waitcnt vmcnt(4) lgkmcnt(0)
	v_fmac_f32_e32 v12, v96, v76
	v_fmac_f32_e32 v13, v96, v77
	v_fmac_f32_e32 v14, v96, v78
	v_fmac_f32_e32 v15, v96, v79
	v_fmac_f32_e32 v16, v97, v76
	v_fmac_f32_e32 v17, v97, v77
	v_fmac_f32_e32 v18, v97, v78
	v_fmac_f32_e32 v19, v97, v79
	v_fmac_f32_e32 v20, v98, v76
	v_fmac_f32_e32 v21, v98, v77
	v_fmac_f32_e32 v22, v98, v78
	v_fmac_f32_e32 v23, v98, v79
	v_fmac_f32_e32 v24, v99, v76
	v_fmac_f32_e32 v25, v99, v77
	v_fmac_f32_e32 v26, v99, v78
	v_fmac_f32_e32 v27, v99, v79
	v_fmac_f32_e32 v28, v100, v76
	v_fmac_f32_e32 v29, v100, v77
	v_fmac_f32_e32 v30, v100, v78
	v_fmac_f32_e32 v31, v100, v79
	ds_read_b32 v96, v10 offset:992
	ds_read_b32 v97, v10 offset:9184
	ds_read_b32 v98, v10 offset:17376
	ds_read_b32 v99, v10 offset:25568
	ds_read_b32 v100, v10 offset:33760
	s_waitcnt vmcnt(3) lgkmcnt(0)
	v_fmac_f32_e32 v12, v96, v80
	v_fmac_f32_e32 v13, v96, v81
	v_fmac_f32_e32 v14, v96, v82
	v_fmac_f32_e32 v15, v96, v83
	v_fmac_f32_e32 v16, v97, v80
	v_fmac_f32_e32 v17, v97, v81
	v_fmac_f32_e32 v18, v97, v82
	v_fmac_f32_e32 v19, v97, v83
	v_fmac_f32_e32 v20, v98, v80
	v_fmac_f32_e32 v21, v98, v81
	v_fmac_f32_e32 v22, v98, v82
	v_fmac_f32_e32 v23, v98, v83
	v_fmac_f32_e32 v24, v99, v80
	v_fmac_f32_e32 v25, v99, v81
	v_fmac_f32_e32 v26, v99, v82
	v_fmac_f32_e32 v27, v99, v83
	v_fmac_f32_e32 v28, v100, v80
	v_fmac_f32_e32 v29, v100, v81
	v_fmac_f32_e32 v30, v100, v82
	v_fmac_f32_e32 v31, v100, v83
	ds_read_b32 v96, v10 offset:1000
	ds_read_b32 v97, v10 offset:9192
	ds_read_b32 v98, v10 offset:17384
	ds_read_b32 v99, v10 offset:25576
	ds_read_b32 v100, v10 offset:33768
	s_waitcnt vmcnt(2) lgkmcnt(0)
	v_fmac_f32_e32 v12, v96, v84
	v_fmac_f32_e32 v13, v96, v85
	v_fmac_f32_e32 v14, v96, v86
	v_fmac_f32_e32 v15, v96, v87
	v_fmac_f32_e32 v16, v97, v84
	v_fmac_f32_e32 v17, v97, v85
	v_fmac_f32_e32 v18, v97, v86
	v_fmac_f32_e32 v19, v97, v87
	v_fmac_f32_e32 v20, v98, v84
	v_fmac_f32_e32 v21, v98, v85
	v_fmac_f32_e32 v22, v98, v86
	v_fmac_f32_e32 v23, v98, v87
	v_fmac_f32_e32 v24, v99, v84
	v_fmac_f32_e32 v25, v99, v85
	v_fmac_f32_e32 v26, v99, v86
	v_fmac_f32_e32 v27, v99, v87
	v_fmac_f32_e32 v28, v100, v84
	v_fmac_f32_e32 v29, v100, v85
	v_fmac_f32_e32 v30, v100, v86
	v_fmac_f32_e32 v31, v100, v87
	ds_read_b32 v96, v10 offset:1008
	ds_read_b32 v97, v10 offset:9200
	ds_read_b32 v98, v10 offset:17392
	ds_read_b32 v99, v10 offset:25584
	ds_read_b32 v100, v10 offset:33776
	s_waitcnt vmcnt(1) lgkmcnt(0)
	v_fmac_f32_e32 v12, v96, v88
	v_fmac_f32_e32 v13, v96, v89
	v_fmac_f32_e32 v14, v96, v90
	v_fmac_f32_e32 v15, v96, v91
	v_fmac_f32_e32 v16, v97, v88
	v_fmac_f32_e32 v17, v97, v89
	v_fmac_f32_e32 v18, v97, v90
	v_fmac_f32_e32 v19, v97, v91
	v_fmac_f32_e32 v20, v98, v88
	v_fmac_f32_e32 v21, v98, v89
	v_fmac_f32_e32 v22, v98, v90
	v_fmac_f32_e32 v23, v98, v91
	v_fmac_f32_e32 v24, v99, v88
	v_fmac_f32_e32 v25, v99, v89
	v_fmac_f32_e32 v26, v99, v90
	v_fmac_f32_e32 v27, v99, v91
	v_fmac_f32_e32 v28, v100, v88
	v_fmac_f32_e32 v29, v100, v89
	v_fmac_f32_e32 v30, v100, v90
	v_fmac_f32_e32 v31, v100, v91
	ds_read_b32 v96, v10 offset:1016
	ds_read_b32 v97, v10 offset:9208
	ds_read_b32 v98, v10 offset:17400
	ds_read_b32 v99, v10 offset:25592
	ds_read_b32 v100, v10 offset:33784
	s_waitcnt vmcnt(0) lgkmcnt(0)
	v_fmac_f32_e32 v12, v96, v92
	v_fmac_f32_e32 v13, v96, v93
	v_fmac_f32_e32 v14, v96, v94
	v_fmac_f32_e32 v15, v96, v95
	v_fmac_f32_e32 v16, v97, v92
	v_fmac_f32_e32 v17, v97, v93
	v_fmac_f32_e32 v18, v97, v94
	v_fmac_f32_e32 v19, v97, v95
	v_fmac_f32_e32 v20, v98, v92
	v_fmac_f32_e32 v21, v98, v93
	v_fmac_f32_e32 v22, v98, v94
	v_fmac_f32_e32 v23, v98, v95
	v_fmac_f32_e32 v24, v99, v92
	v_fmac_f32_e32 v25, v99, v93
	v_fmac_f32_e32 v26, v99, v94
	v_fmac_f32_e32 v27, v99, v95
	v_fmac_f32_e32 v28, v100, v92
	v_fmac_f32_e32 v29, v100, v93
	v_fmac_f32_e32 v30, v100, v94
	v_fmac_f32_e32 v31, v100, v95
	v_lshl_add_u32 v5, v4, 1, v2
	v_mul_u32_u24_e32 v5, 24, v5
	v_add_u32_e32 v5, v5, v3
	v_mul_u32_u24_e32 v5, 80, v5
	v_add_u32_e32 v5, 0xa000, v5
	ds_write_b128 v5, v[12:15] offset:0
	ds_write_b128 v5, v[16:19] offset:16
	ds_write_b128 v5, v[20:23] offset:32
	ds_write_b128 v5, v[24:27] offset:48
	ds_write_b128 v5, v[28:31] offset:64
	s_mov_b64 exec, s[20:21]
	s_waitcnt lgkmcnt(0)
	s_barrier
	v_cmp_gt_u32_e32 vcc, 480, v154
	s_and_saveexec_b64 s[20:21], vcc
	v_mul_u32_u24_e32 v1, 0xccd, v154
	v_lshrrev_b32_e32 v1, 16, v1
	v_mul_u32_u24_e32 v2, 20, v1
	v_sub_u32_e32 v2, v154, v2
	v_mul_u32_u24_e32 v3, 80, v1
	v_lshl_add_u32 v3, v2, 2, v3
	v_add_u32_e32 v3, 0xa000, v3
	ds_read_b32 v32, v3 offset:0
	ds_read_b32 v33, v3 offset:1920
	ds_read_b32 v34, v3 offset:3840
	ds_read_b32 v35, v3 offset:5760
	ds_read_b32 v36, v3 offset:7680
	ds_read_b32 v37, v3 offset:9600
	ds_read_b32 v38, v3 offset:11520
	ds_read_b32 v39, v3 offset:13440
	ds_read_b32 v40, v3 offset:15360
	ds_read_b32 v41, v3 offset:17280
	ds_read_b32 v42, v3 offset:19200
	ds_read_b32 v43, v3 offset:21120
	ds_read_b32 v44, v3 offset:23040
	ds_read_b32 v45, v3 offset:24960
	ds_read_b32 v46, v3 offset:26880
	ds_read_b32 v47, v3 offset:28800
	v_lshrrev_b32_e32 v4, 2, v2
	v_and_b32_e32 v5, 3, v2
	v_lshl_add_u32 v5, v1, 2, v5
	v_add_u32_e32 v5, s9, v5
	s_mul_i32 s12, s8, 12288
	v_add_u32_e32 v6, s12, v5
	v_lshlrev_b32_e32 v6, 2, v6
	global_load_dword v7, v6, s[2:3]
	s_mul_i32 s12, s8, 5
	v_add_u32_e32 v4, s12, v4
	v_mul_u32_u24_e32 v4, 12288, v4
	v_add_u32_e32 v4, v4, v5
	v_lshlrev_b32_e32 v4, 2, v4
	s_add_u32 s12, s90, 0x10400000
	s_addc_u32 s13, s91, 0
	s_waitcnt lgkmcnt(0)
	v_mov_b32_e32 v8, 0
	v_add_f32_e32 v8, v8, v32
	v_add_f32_e32 v8, v8, v33
	v_add_f32_e32 v8, v8, v34
	v_add_f32_e32 v8, v8, v35
	v_add_f32_e32 v8, v8, v36
	v_add_f32_e32 v8, v8, v37
	v_add_f32_e32 v8, v8, v38
	v_add_f32_e32 v8, v8, v39
	v_add_f32_e32 v8, v8, v40
	v_add_f32_e32 v8, v8, v41
	v_add_f32_e32 v8, v8, v42
	v_add_f32_e32 v8, v8, v43
	v_add_f32_e32 v8, v8, v44
	v_add_f32_e32 v8, v8, v45
	v_add_f32_e32 v8, v8, v46
	v_add_f32_e32 v8, v8, v47
	s_waitcnt vmcnt(0)
	v_add_f32_e32 v8, v8, v7
	global_store_dword v4, v8, s[12:13]
	s_or_b64 exec, exec, s[20:21]
	s_waitcnt vmcnt(0)
	s_barrier
	v_mov_b32_e32 v22, v154
	s_branch .LBB0_97

.Ltra_after9:
	ds_write_b32 v1, v10 offset:0
	ds_write_b32 v1, v11 offset:4
	ds_write_b32 v1, v12 offset:8
	ds_write_b32 v1, v13 offset:12
	ds_write_b32 v1, v14 offset:1056
	ds_write_b32 v1, v15 offset:1060
	ds_write_b32 v1, v16 offset:1064
	ds_write_b32 v1, v17 offset:1068
	ds_write_b32 v1, v18 offset:2112
	ds_write_b32 v1, v19 offset:2116
	ds_write_b32 v1, v20 offset:2120
	ds_write_b32 v1, v21 offset:2124
	ds_write_b32 v1, v22 offset:3168
	ds_write_b32 v1, v23 offset:3172
	ds_write_b32 v1, v24 offset:3176
	ds_write_b32 v1, v25 offset:3180
	ds_write_b32 v1, v26 offset:4224
	ds_write_b32 v1, v27 offset:4228
	ds_write_b32 v1, v28 offset:4232
	ds_write_b32 v1, v29 offset:4236
	ds_write_b32 v1, v30 offset:5280
	ds_write_b32 v1, v31 offset:5284
	ds_write_b32 v1, v32 offset:5288
	ds_write_b32 v1, v33 offset:5292
	ds_write_b32 v1, v34 offset:6336
	ds_write_b32 v1, v35 offset:6340
	ds_write_b32 v1, v36 offset:6344
	ds_write_b32 v1, v37 offset:6348
	ds_write_b32 v1, v38 offset:7392
	ds_write_b32 v1, v39 offset:7396
	ds_write_b32 v1, v40 offset:7400
	ds_write_b32 v1, v41 offset:7404
	v_mad_u32_u24 v9, v5, s22, v6
	s_lshl_b32 s46, s22, 3
	s_waitcnt lgkmcnt(0)
	ds_read_b32 v74, v2 offset:0
	ds_read_b32 v75, v2 offset:132
	ds_read_b32 v76, v2 offset:264
	ds_read_b32 v77, v2 offset:396
	ds_read_b32 v78, v2 offset:528
	ds_read_b32 v79, v2 offset:660
	ds_read_b32 v80, v2 offset:792
	ds_read_b32 v81, v2 offset:924
	ds_read_b32 v82, v2 offset:32
	ds_read_b32 v83, v2 offset:164
	ds_read_b32 v84, v2 offset:296
	ds_read_b32 v85, v2 offset:428
	ds_read_b32 v86, v2 offset:560
	ds_read_b32 v87, v2 offset:692
	ds_read_b32 v88, v2 offset:824
	ds_read_b32 v89, v2 offset:956
	s_waitcnt lgkmcnt(8)
	v_cvt_pk_bf16_f32 v106, v74, v75
	v_cvt_pk_bf16_f32 v107, v76, v77
	v_cvt_pk_bf16_f32 v108, v78, v79
	v_cvt_pk_bf16_f32 v109, v80, v81
	global_store_dwordx4 v9, v[106:109], s[18:19] nt
	s_add_u32 s18, s18, s46
	s_addc_u32 s19, s19, 0
	ds_read_b32 v90, v2 offset:64
	ds_read_b32 v91, v2 offset:196
	ds_read_b32 v92, v2 offset:328
	ds_read_b32 v93, v2 offset:460
	ds_read_b32 v94, v2 offset:592
	ds_read_b32 v95, v2 offset:724
	ds_read_b32 v96, v2 offset:856
	ds_read_b32 v97, v2 offset:988
	s_waitcnt lgkmcnt(8)
	v_cvt_pk_bf16_f32 v110, v82, v83
	v_cvt_pk_bf16_f32 v111, v84, v85
	v_cvt_pk_bf16_f32 v112, v86, v87
	v_cvt_pk_bf16_f32 v113, v88, v89
	global_store_dwordx4 v9, v[110:113], s[18:19] nt
	s_add_u32 s18, s18, s46
	s_addc_u32 s19, s19, 0
	ds_read_b32 v98, v2 offset:96
	ds_read_b32 v99, v2 offset:228
	ds_read_b32 v100, v2 offset:360
	ds_read_b32 v101, v2 offset:492
	ds_read_b32 v102, v2 offset:624
	ds_read_b32 v103, v2 offset:756
	ds_read_b32 v104, v2 offset:888
	ds_read_b32 v105, v2 offset:1020
	s_waitcnt lgkmcnt(8)
	v_cvt_pk_bf16_f32 v106, v90, v91
	v_cvt_pk_bf16_f32 v107, v92, v93
	v_cvt_pk_bf16_f32 v108, v94, v95
	v_cvt_pk_bf16_f32 v109, v96, v97
	global_store_dwordx4 v9, v[106:109], s[18:19] nt
	s_add_u32 s18, s18, s46
	s_addc_u32 s19, s19, 0
	s_waitcnt lgkmcnt(0)
	v_cvt_pk_bf16_f32 v110, v98, v99
	v_cvt_pk_bf16_f32 v111, v100, v101
	v_cvt_pk_bf16_f32 v112, v102, v103
	v_cvt_pk_bf16_f32 v113, v104, v105
	global_store_dwordx4 v9, v[110:113], s[18:19] nt
	s_cmp_eq_u32 s24, 0
	s_cbranch_scc1 .Ltra_done
	s_add_u32 s12, s12, 2048
	s_cmp_lt_u32 s12, 44544
	s_cselect_b32 s24, 1, 0
	s_cbranch_scc0 .Ltra_nonext17
	s_cmp_ge_u32 s12, 33280
	s_cselect_b32 s41, 1, 0
	s_cselect_b32 s26, 33280, 0
	s_sub_u32 s42, s12, s26
	s_cmp_ge_u32 s42, 12288
	s_cbranch_scc1 .Ltra_m20
	s_mul_i32 s43, s42, 43691
	s_lshr_b32 s43, s43, 24
	s_mul_i32 s26, s43, 384
	s_sub_u32 s44, s42, s26
	s_mov_b32 s14, s0
	s_mov_b32 s15, s1
	s_mov_b32 s36, 0xc000
	s_mov_b32 s37, 0x6000000
	s_mov_b32 s38, 0x0
	s_mov_b32 s39, 0x3000000
	s_mov_b32 s40, 0x1000
	s_branch .Ltra_dec_done19

.Ltra_after18:
	ds_write_b32 v1, v42 offset:0
	ds_write_b32 v1, v43 offset:4
	ds_write_b32 v1, v44 offset:8
	ds_write_b32 v1, v45 offset:12
	ds_write_b32 v1, v46 offset:1056
	ds_write_b32 v1, v47 offset:1060
	ds_write_b32 v1, v48 offset:1064
	ds_write_b32 v1, v49 offset:1068
	ds_write_b32 v1, v50 offset:2112
	ds_write_b32 v1, v51 offset:2116
	ds_write_b32 v1, v52 offset:2120
	ds_write_b32 v1, v53 offset:2124
	ds_write_b32 v1, v54 offset:3168
	ds_write_b32 v1, v55 offset:3172
	ds_write_b32 v1, v56 offset:3176
	ds_write_b32 v1, v57 offset:3180
	ds_write_b32 v1, v58 offset:4224
	ds_write_b32 v1, v59 offset:4228
	ds_write_b32 v1, v60 offset:4232
	ds_write_b32 v1, v61 offset:4236
	ds_write_b32 v1, v62 offset:5280
	ds_write_b32 v1, v63 offset:5284
	ds_write_b32 v1, v64 offset:5288
	ds_write_b32 v1, v65 offset:5292
	ds_write_b32 v1, v66 offset:6336
	ds_write_b32 v1, v67 offset:6340
	ds_write_b32 v1, v68 offset:6344
	ds_write_b32 v1, v69 offset:6348
	ds_write_b32 v1, v70 offset:7392
	ds_write_b32 v1, v71 offset:7396
	ds_write_b32 v1, v72 offset:7400
	ds_write_b32 v1, v73 offset:7404
	v_mad_u32_u24 v9, v5, s23, v6
	s_lshl_b32 s46, s23, 3
	s_waitcnt lgkmcnt(0)
	ds_read_b32 v74, v2 offset:0
	ds_read_b32 v75, v2 offset:132
	ds_read_b32 v76, v2 offset:264
	ds_read_b32 v77, v2 offset:396
	ds_read_b32 v78, v2 offset:528
	ds_read_b32 v79, v2 offset:660
	ds_read_b32 v80, v2 offset:792
	ds_read_b32 v81, v2 offset:924
	ds_read_b32 v82, v2 offset:32
	ds_read_b32 v83, v2 offset:164
	ds_read_b32 v84, v2 offset:296
	ds_read_b32 v85, v2 offset:428
	ds_read_b32 v86, v2 offset:560
	ds_read_b32 v87, v2 offset:692
	ds_read_b32 v88, v2 offset:824
	ds_read_b32 v89, v2 offset:956
	s_waitcnt lgkmcnt(8)
	v_cvt_pk_bf16_f32 v106, v74, v75
	v_cvt_pk_bf16_f32 v107, v76, v77
	v_cvt_pk_bf16_f32 v108, v78, v79
	v_cvt_pk_bf16_f32 v109, v80, v81
	global_store_dwordx4 v9, v[106:109], s[20:21] nt
	s_add_u32 s20, s20, s46
	s_addc_u32 s21, s21, 0
	ds_read_b32 v90, v2 offset:64
	ds_read_b32 v91, v2 offset:196
	ds_read_b32 v92, v2 offset:328
	ds_read_b32 v93, v2 offset:460
	ds_read_b32 v94, v2 offset:592
	ds_read_b32 v95, v2 offset:724
	ds_read_b32 v96, v2 offset:856
	ds_read_b32 v97, v2 offset:988
	s_waitcnt lgkmcnt(8)
	v_cvt_pk_bf16_f32 v110, v82, v83
	v_cvt_pk_bf16_f32 v111, v84, v85
	v_cvt_pk_bf16_f32 v112, v86, v87
	v_cvt_pk_bf16_f32 v113, v88, v89
	global_store_dwordx4 v9, v[110:113], s[20:21] nt
	s_add_u32 s20, s20, s46
	s_addc_u32 s21, s21, 0
	ds_read_b32 v98, v2 offset:96
	ds_read_b32 v99, v2 offset:228
	ds_read_b32 v100, v2 offset:360
	ds_read_b32 v101, v2 offset:492
	ds_read_b32 v102, v2 offset:624
	ds_read_b32 v103, v2 offset:756
	ds_read_b32 v104, v2 offset:888
	ds_read_b32 v105, v2 offset:1020
	s_waitcnt lgkmcnt(8)
	v_cvt_pk_bf16_f32 v106, v90, v91
	v_cvt_pk_bf16_f32 v107, v92, v93
	v_cvt_pk_bf16_f32 v108, v94, v95
	v_cvt_pk_bf16_f32 v109, v96, v97
	global_store_dwordx4 v9, v[106:109], s[20:21] nt
	s_add_u32 s20, s20, s46
	s_addc_u32 s21, s21, 0
	s_waitcnt lgkmcnt(0)
	v_cvt_pk_bf16_f32 v110, v98, v99
	v_cvt_pk_bf16_f32 v111, v100, v101
	v_cvt_pk_bf16_f32 v112, v102, v103
	v_cvt_pk_bf16_f32 v113, v104, v105
	global_store_dwordx4 v9, v[110:113], s[20:21] nt
	s_cmp_eq_u32 s24, 0
	s_cbranch_scc1 .Ltra_done
	s_branch .Ltra_loop

.LBB0_799:
.LBB0_800:
	s_waitcnt vmcnt(0) lgkmcnt(0)
	s_load_dwordx2 s[0:1], s[92:93], 0x68
	v_and_b32_e32 v2, 63, v154
	v_lshlrev_b32_e32 v1, 4, v2
	v_and_b32_e32 v180, 31, v2
	v_lshlrev_b32_e32 v180, 4, v180
	v_lshlrev_b32_e32 v2, 3, v2
	v_readfirstlane_b32 s10, v154
	s_lshr_b32 s10, s10, 6
	s_lshl_b32 s12, s96, 3
	s_add_u32 s10, s10, s12
	s_lshl_b32 s12, s10, 10
	s_add_u32 s2, s90, 0x24918000
	s_addc_u32 s3, s91, 0
	s_add_u32 s2, s2, s12
	s_addc_u32 s3, s3, 0
	s_add_u32 s4, s2, 0x2000000
	s_addc_u32 s5, s3, 0
	s_lshl_b32 s12, s10, 9
	s_add_u32 s8, s90, 0x13918000
	s_addc_u32 s9, s91, 0
	s_add_u32 s8, s8, s12
	s_addc_u32 s9, s9, 0
	s_lshr_b32 s12, s10, 2
	s_mul_i32 s12, s12, 24576
	s_and_b32 s13, s10, 3
	s_lshl_b32 s13, s13, 9
	s_add_u32 s12, s12, s13
	s_add_u32 s12, s12, 8192
	s_add_u32 s6, s90, 0x15918000
	s_addc_u32 s7, s91, 0
	s_add_u32 s6, s6, s12
	s_addc_u32 s7, s7, 0
	s_waitcnt lgkmcnt(0)
	global_load_dwordx4 v[4:7], v180, s[0:1]
	global_load_dwordx4 v[12:15], v1, s[2:3] nt
	global_load_dwordx4 v[76:79], v1, s[4:5] nt
	global_load_dwordx2 v[140:141], v2, s[6:7] nt
	s_add_u32 s2, s2, 0x200000
	s_addc_u32 s3, s3, 0
	s_add_u32 s4, s4, 0x200000
	s_addc_u32 s5, s5, 0
	s_add_u32 s6, s6, 0xc00000
	s_addc_u32 s7, s7, 0
	global_load_dwordx4 v[16:19], v1, s[2:3] nt
	global_load_dwordx4 v[80:83], v1, s[4:5] nt
	global_load_dwordx2 v[142:143], v2, s[6:7] nt
	s_add_u32 s2, s2, 0x200000
	s_addc_u32 s3, s3, 0
	s_add_u32 s4, s4, 0x200000
	s_addc_u32 s5, s5, 0
	s_add_u32 s6, s6, 0xc00000
	s_addc_u32 s7, s7, 0
	global_load_dwordx4 v[20:23], v1, s[2:3] nt
	global_load_dwordx4 v[84:87], v1, s[4:5] nt
	global_load_dwordx2 v[144:145], v2, s[6:7] nt
	s_add_u32 s2, s2, 0x200000
	s_addc_u32 s3, s3, 0
	s_add_u32 s4, s4, 0x200000
	s_addc_u32 s5, s5, 0
	s_add_u32 s6, s6, 0xc00000
	s_addc_u32 s7, s7, 0
	global_load_dwordx4 v[24:27], v1, s[2:3] nt
	global_load_dwordx4 v[88:91], v1, s[4:5] nt
	global_load_dwordx2 v[146:147], v2, s[6:7] nt
	s_add_u32 s2, s2, 0x200000
	s_addc_u32 s3, s3, 0
	s_add_u32 s4, s4, 0x200000
	s_addc_u32 s5, s5, 0
	s_add_u32 s6, s6, 0xc00000
	s_addc_u32 s7, s7, 0
	global_load_dwordx4 v[28:31], v1, s[2:3] nt
	global_load_dwordx4 v[92:95], v1, s[4:5] nt
	global_load_dwordx2 v[148:149], v2, s[6:7] nt
	s_add_u32 s2, s2, 0x200000
	s_addc_u32 s3, s3, 0
	s_add_u32 s4, s4, 0x200000
	s_addc_u32 s5, s5, 0
	s_add_u32 s6, s6, 0xc00000
	s_addc_u32 s7, s7, 0
	global_load_dwordx4 v[32:35], v1, s[2:3] nt
	global_load_dwordx4 v[96:99], v1, s[4:5] nt
	global_load_dwordx2 v[150:151], v2, s[6:7] nt
	s_add_u32 s2, s2, 0x200000
	s_addc_u32 s3, s3, 0
	s_add_u32 s4, s4, 0x200000
	s_addc_u32 s5, s5, 0
	s_add_u32 s6, s6, 0xc00000
	s_addc_u32 s7, s7, 0
	global_load_dwordx4 v[36:39], v1, s[2:3] nt
	global_load_dwordx4 v[100:103], v1, s[4:5] nt
	global_load_dwordx2 v[152:153], v2, s[6:7] nt
	s_add_u32 s2, s2, 0x200000
	s_addc_u32 s3, s3, 0
	s_add_u32 s4, s4, 0x200000
	s_addc_u32 s5, s5, 0
	s_add_u32 s6, s6, 0xc00000
	s_addc_u32 s7, s7, 0
	global_load_dwordx4 v[40:43], v1, s[2:3] nt
	global_load_dwordx4 v[104:107], v1, s[4:5] nt
	global_load_dwordx2 v[156:157], v2, s[6:7] nt
	s_add_u32 s2, s2, 0x200000
	s_addc_u32 s3, s3, 0
	s_add_u32 s4, s4, 0x200000
	s_addc_u32 s5, s5, 0
	s_add_u32 s6, s6, 0xc00000
	s_addc_u32 s7, s7, 0
	global_load_dwordx4 v[44:47], v1, s[2:3] nt
	global_load_dwordx4 v[108:111], v1, s[4:5] nt
	global_load_dwordx2 v[158:159], v2, s[6:7] nt
	s_add_u32 s2, s2, 0x200000
	s_addc_u32 s3, s3, 0
	s_add_u32 s4, s4, 0x200000
	s_addc_u32 s5, s5, 0
	s_add_u32 s6, s6, 0xc00000
	s_addc_u32 s7, s7, 0
	global_load_dwordx4 v[48:51], v1, s[2:3] nt
	global_load_dwordx4 v[112:115], v1, s[4:5] nt
	global_load_dwordx2 v[160:161], v2, s[6:7] nt
	s_add_u32 s2, s2, 0x200000
	s_addc_u32 s3, s3, 0
	s_add_u32 s4, s4, 0x200000
	s_addc_u32 s5, s5, 0
	s_add_u32 s6, s6, 0xc00000
	s_addc_u32 s7, s7, 0
	global_load_dwordx4 v[52:55], v1, s[2:3] nt
	global_load_dwordx4 v[116:119], v1, s[4:5] nt
	global_load_dwordx2 v[162:163], v2, s[6:7] nt
	s_add_u32 s2, s2, 0x200000
	s_addc_u32 s3, s3, 0
	s_add_u32 s4, s4, 0x200000
	s_addc_u32 s5, s5, 0
	s_add_u32 s6, s6, 0xc00000
	s_addc_u32 s7, s7, 0
	global_load_dwordx4 v[56:59], v1, s[2:3] nt
	global_load_dwordx4 v[120:123], v1, s[4:5] nt
	global_load_dwordx2 v[164:165], v2, s[6:7] nt
	s_add_u32 s2, s2, 0x200000
	s_addc_u32 s3, s3, 0
	s_add_u32 s4, s4, 0x200000
	s_addc_u32 s5, s5, 0
	s_add_u32 s6, s6, 0xc00000
	s_addc_u32 s7, s7, 0
	global_load_dwordx4 v[60:63], v1, s[2:3] nt
	global_load_dwordx4 v[124:127], v1, s[4:5] nt
	global_load_dwordx2 v[166:167], v2, s[6:7] nt
	s_add_u32 s2, s2, 0x200000
	s_addc_u32 s3, s3, 0
	s_add_u32 s4, s4, 0x200000
	s_addc_u32 s5, s5, 0
	s_add_u32 s6, s6, 0xc00000
	s_addc_u32 s7, s7, 0
	global_load_dwordx4 v[64:67], v1, s[2:3] nt
	global_load_dwordx4 v[128:131], v1, s[4:5] nt
	global_load_dwordx2 v[168:169], v2, s[6:7] nt
	s_add_u32 s2, s2, 0x200000
	s_addc_u32 s3, s3, 0
	s_add_u32 s4, s4, 0x200000
	s_addc_u32 s5, s5, 0
	s_add_u32 s6, s6, 0xc00000
	s_addc_u32 s7, s7, 0
	global_load_dwordx4 v[68:71], v1, s[2:3] nt
	global_load_dwordx4 v[132:135], v1, s[4:5] nt
	global_load_dwordx2 v[170:171], v2, s[6:7] nt
	s_add_u32 s2, s2, 0x200000
	s_addc_u32 s3, s3, 0
	s_add_u32 s4, s4, 0x200000
	s_addc_u32 s5, s5, 0
	s_add_u32 s6, s6, 0xc00000
	s_addc_u32 s7, s7, 0
	global_load_dwordx4 v[72:75], v1, s[2:3] nt
	global_load_dwordx4 v[136:139], v1, s[4:5] nt
	global_load_dwordx2 v[172:173], v2, s[6:7] nt
	v_mov_b32_e32 v8, 0xbfb8aa3b
	v_mov_b32_e32 v9, 0xbfb8aa3b
	v_mov_b32_e32 v10, 1.0
	v_mov_b32_e32 v11, 1.0
	s_mov_b32 s20, 0x3c000000
	s_mov_b32 s21, 0x358637bd
	s_waitcnt vmcnt(45)
	v_pk_add_f32 v[12:13], v[12:13], v[76:77]
	v_pk_add_f32 v[14:15], v[14:15], v[78:79]
	v_mul_f32_e32 v180, v12, v12
	v_fmac_f32_e32 v180, v13, v13
	v_fmac_f32_e32 v180, v14, v14
	v_fmac_f32_e32 v180, v15, v15
	v_lshlrev_b32_e32 v184, 16, v140
	v_and_b32_e32 v185, 0xffff0000, v140
	v_add_f32_dpp v180, v180, v180 quad_perm:[1,0,3,2] row_mask:0xf bank_mask:0xf
	v_lshlrev_b32_e32 v186, 16, v141
	v_and_b32_e32 v187, 0xffff0000, v141
	v_add_f32_dpp v180, v180, v180 quad_perm:[2,3,0,1] row_mask:0xf bank_mask:0xf
	v_pk_mul_f32 v[188:189], v[184:185], v[8:9]
	v_pk_mul_f32 v[190:191], v[186:187], v[8:9]
	v_add_f32_dpp v180, v180, v180 row_ror:4 row_mask:0xf bank_mask:0xf
	v_exp_f32_e32 v188, v188
	v_exp_f32_e32 v189, v189
	v_add_f32_dpp v180, v180, v180 row_ror:8 row_mask:0xf bank_mask:0xf
	v_exp_f32_e32 v190, v190
	v_exp_f32_e32 v191, v191
	v_mov_b32_e32 v181, v180
	v_pk_add_f32 v[188:189], v[188:189], v[10:11]
	v_pk_add_f32 v[190:191], v[190:191], v[10:11]
	v_permlane16_swap_b32_e32 v180, v181
	v_rcp_f32_e32 v188, v188
	v_rcp_f32_e32 v189, v189
	v_add_f32_e32 v180, v180, v181
	v_rcp_f32_e32 v190, v190
	v_rcp_f32_e32 v191, v191
	v_mov_b32_e32 v182, s21
	v_fmac_f32_e32 v182, s20, v180
	v_rsq_f32_e32 v182, v182
	v_pk_mul_f32 v[188:189], v[188:189], v[184:185]
	v_pk_mul_f32 v[190:191], v[190:191], v[186:187]
	v_mov_b32_e32 v183, v182
	v_pk_mul_f32 v[188:189], v[188:189], v[4:5]
	v_pk_mul_f32 v[190:191], v[190:191], v[6:7]
	v_pk_mul_f32 v[12:13], v[12:13], v[182:183]
	v_pk_mul_f32 v[14:15], v[14:15], v[182:183]
	v_pk_mul_f32 v[12:13], v[12:13], v[188:189]
	v_pk_mul_f32 v[14:15], v[14:15], v[190:191]
	v_cvt_pk_bf16_f32 v200, v12, v13
	v_cvt_pk_bf16_f32 v201, v14, v15
	global_store_dwordx2 v2, v[200:201], s[8:9]
	s_add_u32 s8, s8, 0x100000
	s_addc_u32 s9, s9, 0
	s_waitcnt vmcnt(43)
	v_pk_add_f32 v[16:17], v[16:17], v[80:81]
	v_pk_add_f32 v[18:19], v[18:19], v[82:83]
	v_mul_f32_e32 v180, v16, v16
	v_fmac_f32_e32 v180, v17, v17
	v_fmac_f32_e32 v180, v18, v18
	v_fmac_f32_e32 v180, v19, v19
	v_lshlrev_b32_e32 v184, 16, v142
	v_and_b32_e32 v185, 0xffff0000, v142
	v_add_f32_dpp v180, v180, v180 quad_perm:[1,0,3,2] row_mask:0xf bank_mask:0xf
	v_lshlrev_b32_e32 v186, 16, v143
	v_and_b32_e32 v187, 0xffff0000, v143
	v_add_f32_dpp v180, v180, v180 quad_perm:[2,3,0,1] row_mask:0xf bank_mask:0xf
	v_pk_mul_f32 v[188:189], v[184:185], v[8:9]
	v_pk_mul_f32 v[190:191], v[186:187], v[8:9]
	v_add_f32_dpp v180, v180, v180 row_ror:4 row_mask:0xf bank_mask:0xf
	v_exp_f32_e32 v188, v188
	v_exp_f32_e32 v189, v189
	v_add_f32_dpp v180, v180, v180 row_ror:8 row_mask:0xf bank_mask:0xf
	v_exp_f32_e32 v190, v190
	v_exp_f32_e32 v191, v191
	v_mov_b32_e32 v181, v180
	v_pk_add_f32 v[188:189], v[188:189], v[10:11]
	v_pk_add_f32 v[190:191], v[190:191], v[10:11]
	v_permlane16_swap_b32_e32 v180, v181
	v_rcp_f32_e32 v188, v188
	v_rcp_f32_e32 v189, v189
	v_add_f32_e32 v180, v180, v181
	v_rcp_f32_e32 v190, v190
	v_rcp_f32_e32 v191, v191
	v_mov_b32_e32 v182, s21
	v_fmac_f32_e32 v182, s20, v180
	v_rsq_f32_e32 v182, v182
	v_pk_mul_f32 v[188:189], v[188:189], v[184:185]
	v_pk_mul_f32 v[190:191], v[190:191], v[186:187]
	v_mov_b32_e32 v183, v182
	v_pk_mul_f32 v[188:189], v[188:189], v[4:5]
	v_pk_mul_f32 v[190:191], v[190:191], v[6:7]
	v_pk_mul_f32 v[16:17], v[16:17], v[182:183]
	v_pk_mul_f32 v[18:19], v[18:19], v[182:183]
	v_pk_mul_f32 v[16:17], v[16:17], v[188:189]
	v_pk_mul_f32 v[18:19], v[18:19], v[190:191]
	v_cvt_pk_bf16_f32 v202, v16, v17
	v_cvt_pk_bf16_f32 v203, v18, v19
	global_store_dwordx2 v2, v[202:203], s[8:9]
	s_add_u32 s8, s8, 0x100000
	s_addc_u32 s9, s9, 0
	s_waitcnt vmcnt(41)
	v_pk_add_f32 v[20:21], v[20:21], v[84:85]
	v_pk_add_f32 v[22:23], v[22:23], v[86:87]
	v_mul_f32_e32 v180, v20, v20
	v_fmac_f32_e32 v180, v21, v21
	v_fmac_f32_e32 v180, v22, v22
	v_fmac_f32_e32 v180, v23, v23
	v_lshlrev_b32_e32 v184, 16, v144
	v_and_b32_e32 v185, 0xffff0000, v144
	v_add_f32_dpp v180, v180, v180 quad_perm:[1,0,3,2] row_mask:0xf bank_mask:0xf
	v_lshlrev_b32_e32 v186, 16, v145
	v_and_b32_e32 v187, 0xffff0000, v145
	v_add_f32_dpp v180, v180, v180 quad_perm:[2,3,0,1] row_mask:0xf bank_mask:0xf
	v_pk_mul_f32 v[188:189], v[184:185], v[8:9]
	v_pk_mul_f32 v[190:191], v[186:187], v[8:9]
	v_add_f32_dpp v180, v180, v180 row_ror:4 row_mask:0xf bank_mask:0xf
	v_exp_f32_e32 v188, v188
	v_exp_f32_e32 v189, v189
	v_add_f32_dpp v180, v180, v180 row_ror:8 row_mask:0xf bank_mask:0xf
	v_exp_f32_e32 v190, v190
	v_exp_f32_e32 v191, v191
	v_mov_b32_e32 v181, v180
	v_pk_add_f32 v[188:189], v[188:189], v[10:11]
	v_pk_add_f32 v[190:191], v[190:191], v[10:11]
	v_permlane16_swap_b32_e32 v180, v181
	v_rcp_f32_e32 v188, v188
	v_rcp_f32_e32 v189, v189
	v_add_f32_e32 v180, v180, v181
	v_rcp_f32_e32 v190, v190
	v_rcp_f32_e32 v191, v191
	v_mov_b32_e32 v182, s21
	v_fmac_f32_e32 v182, s20, v180
	v_rsq_f32_e32 v182, v182
	v_pk_mul_f32 v[188:189], v[188:189], v[184:185]
	v_pk_mul_f32 v[190:191], v[190:191], v[186:187]
	v_mov_b32_e32 v183, v182
	v_pk_mul_f32 v[188:189], v[188:189], v[4:5]
	v_pk_mul_f32 v[190:191], v[190:191], v[6:7]
	v_pk_mul_f32 v[20:21], v[20:21], v[182:183]
	v_pk_mul_f32 v[22:23], v[22:23], v[182:183]
	v_pk_mul_f32 v[20:21], v[20:21], v[188:189]
	v_pk_mul_f32 v[22:23], v[22:23], v[190:191]
	v_cvt_pk_bf16_f32 v204, v20, v21
	v_cvt_pk_bf16_f32 v205, v22, v23
	global_store_dwordx2 v2, v[204:205], s[8:9]
	s_add_u32 s8, s8, 0x100000
	s_addc_u32 s9, s9, 0
	s_waitcnt vmcnt(39)
	v_pk_add_f32 v[24:25], v[24:25], v[88:89]
	v_pk_add_f32 v[26:27], v[26:27], v[90:91]
	v_mul_f32_e32 v180, v24, v24
	v_fmac_f32_e32 v180, v25, v25
	v_fmac_f32_e32 v180, v26, v26
	v_fmac_f32_e32 v180, v27, v27
	v_lshlrev_b32_e32 v184, 16, v146
	v_and_b32_e32 v185, 0xffff0000, v146
	v_add_f32_dpp v180, v180, v180 quad_perm:[1,0,3,2] row_mask:0xf bank_mask:0xf
	v_lshlrev_b32_e32 v186, 16, v147
	v_and_b32_e32 v187, 0xffff0000, v147
	v_add_f32_dpp v180, v180, v180 quad_perm:[2,3,0,1] row_mask:0xf bank_mask:0xf
	v_pk_mul_f32 v[188:189], v[184:185], v[8:9]
	v_pk_mul_f32 v[190:191], v[186:187], v[8:9]
	v_add_f32_dpp v180, v180, v180 row_ror:4 row_mask:0xf bank_mask:0xf
	v_exp_f32_e32 v188, v188
	v_exp_f32_e32 v189, v189
	v_add_f32_dpp v180, v180, v180 row_ror:8 row_mask:0xf bank_mask:0xf
	v_exp_f32_e32 v190, v190
	v_exp_f32_e32 v191, v191
	v_mov_b32_e32 v181, v180
	v_pk_add_f32 v[188:189], v[188:189], v[10:11]
	v_pk_add_f32 v[190:191], v[190:191], v[10:11]
	v_permlane16_swap_b32_e32 v180, v181
	v_rcp_f32_e32 v188, v188
	v_rcp_f32_e32 v189, v189
	v_add_f32_e32 v180, v180, v181
	v_rcp_f32_e32 v190, v190
	v_rcp_f32_e32 v191, v191
	v_mov_b32_e32 v182, s21
	v_fmac_f32_e32 v182, s20, v180
	v_rsq_f32_e32 v182, v182
	v_pk_mul_f32 v[188:189], v[188:189], v[184:185]
	v_pk_mul_f32 v[190:191], v[190:191], v[186:187]
	v_mov_b32_e32 v183, v182
	v_pk_mul_f32 v[188:189], v[188:189], v[4:5]
	v_pk_mul_f32 v[190:191], v[190:191], v[6:7]
	v_pk_mul_f32 v[24:25], v[24:25], v[182:183]
	v_pk_mul_f32 v[26:27], v[26:27], v[182:183]
	v_pk_mul_f32 v[24:25], v[24:25], v[188:189]
	v_pk_mul_f32 v[26:27], v[26:27], v[190:191]
	v_cvt_pk_bf16_f32 v206, v24, v25
	v_cvt_pk_bf16_f32 v207, v26, v27
	global_store_dwordx2 v2, v[206:207], s[8:9]
	s_add_u32 s8, s8, 0x100000
	s_addc_u32 s9, s9, 0
	s_waitcnt vmcnt(37)
	v_pk_add_f32 v[28:29], v[28:29], v[92:93]
	v_pk_add_f32 v[30:31], v[30:31], v[94:95]
	v_mul_f32_e32 v180, v28, v28
	v_fmac_f32_e32 v180, v29, v29
	v_fmac_f32_e32 v180, v30, v30
	v_fmac_f32_e32 v180, v31, v31
	v_lshlrev_b32_e32 v184, 16, v148
	v_and_b32_e32 v185, 0xffff0000, v148
	v_add_f32_dpp v180, v180, v180 quad_perm:[1,0,3,2] row_mask:0xf bank_mask:0xf
	v_lshlrev_b32_e32 v186, 16, v149
	v_and_b32_e32 v187, 0xffff0000, v149
	v_add_f32_dpp v180, v180, v180 quad_perm:[2,3,0,1] row_mask:0xf bank_mask:0xf
	v_pk_mul_f32 v[188:189], v[184:185], v[8:9]
	v_pk_mul_f32 v[190:191], v[186:187], v[8:9]
	v_add_f32_dpp v180, v180, v180 row_ror:4 row_mask:0xf bank_mask:0xf
	v_exp_f32_e32 v188, v188
	v_exp_f32_e32 v189, v189
	v_add_f32_dpp v180, v180, v180 row_ror:8 row_mask:0xf bank_mask:0xf
	v_exp_f32_e32 v190, v190
	v_exp_f32_e32 v191, v191
	v_mov_b32_e32 v181, v180
	v_pk_add_f32 v[188:189], v[188:189], v[10:11]
	v_pk_add_f32 v[190:191], v[190:191], v[10:11]
	v_permlane16_swap_b32_e32 v180, v181
	v_rcp_f32_e32 v188, v188
	v_rcp_f32_e32 v189, v189
	v_add_f32_e32 v180, v180, v181
	v_rcp_f32_e32 v190, v190
	v_rcp_f32_e32 v191, v191
	v_mov_b32_e32 v182, s21
	v_fmac_f32_e32 v182, s20, v180
	v_rsq_f32_e32 v182, v182
	v_pk_mul_f32 v[188:189], v[188:189], v[184:185]
	v_pk_mul_f32 v[190:191], v[190:191], v[186:187]
	v_mov_b32_e32 v183, v182
	v_pk_mul_f32 v[188:189], v[188:189], v[4:5]
	v_pk_mul_f32 v[190:191], v[190:191], v[6:7]
	v_pk_mul_f32 v[28:29], v[28:29], v[182:183]
	v_pk_mul_f32 v[30:31], v[30:31], v[182:183]
	v_pk_mul_f32 v[28:29], v[28:29], v[188:189]
	v_pk_mul_f32 v[30:31], v[30:31], v[190:191]
	v_cvt_pk_bf16_f32 v200, v28, v29
	v_cvt_pk_bf16_f32 v201, v30, v31
	global_store_dwordx2 v2, v[200:201], s[8:9]
	s_add_u32 s8, s8, 0x100000
	s_addc_u32 s9, s9, 0
	s_waitcnt vmcnt(35)
	v_pk_add_f32 v[32:33], v[32:33], v[96:97]
	v_pk_add_f32 v[34:35], v[34:35], v[98:99]
	v_mul_f32_e32 v180, v32, v32
	v_fmac_f32_e32 v180, v33, v33
	v_fmac_f32_e32 v180, v34, v34
	v_fmac_f32_e32 v180, v35, v35
	v_lshlrev_b32_e32 v184, 16, v150
	v_and_b32_e32 v185, 0xffff0000, v150
	v_add_f32_dpp v180, v180, v180 quad_perm:[1,0,3,2] row_mask:0xf bank_mask:0xf
	v_lshlrev_b32_e32 v186, 16, v151
	v_and_b32_e32 v187, 0xffff0000, v151
	v_add_f32_dpp v180, v180, v180 quad_perm:[2,3,0,1] row_mask:0xf bank_mask:0xf
	v_pk_mul_f32 v[188:189], v[184:185], v[8:9]
	v_pk_mul_f32 v[190:191], v[186:187], v[8:9]
	v_add_f32_dpp v180, v180, v180 row_ror:4 row_mask:0xf bank_mask:0xf
	v_exp_f32_e32 v188, v188
	v_exp_f32_e32 v189, v189
	v_add_f32_dpp v180, v180, v180 row_ror:8 row_mask:0xf bank_mask:0xf
	v_exp_f32_e32 v190, v190
	v_exp_f32_e32 v191, v191
	v_mov_b32_e32 v181, v180
	v_pk_add_f32 v[188:189], v[188:189], v[10:11]
	v_pk_add_f32 v[190:191], v[190:191], v[10:11]
	v_permlane16_swap_b32_e32 v180, v181
	v_rcp_f32_e32 v188, v188
	v_rcp_f32_e32 v189, v189
	v_add_f32_e32 v180, v180, v181
	v_rcp_f32_e32 v190, v190
	v_rcp_f32_e32 v191, v191
	v_mov_b32_e32 v182, s21
	v_fmac_f32_e32 v182, s20, v180
	v_rsq_f32_e32 v182, v182
	v_pk_mul_f32 v[188:189], v[188:189], v[184:185]
	v_pk_mul_f32 v[190:191], v[190:191], v[186:187]
	v_mov_b32_e32 v183, v182
	v_pk_mul_f32 v[188:189], v[188:189], v[4:5]
	v_pk_mul_f32 v[190:191], v[190:191], v[6:7]
	v_pk_mul_f32 v[32:33], v[32:33], v[182:183]
	v_pk_mul_f32 v[34:35], v[34:35], v[182:183]
	v_pk_mul_f32 v[32:33], v[32:33], v[188:189]
	v_pk_mul_f32 v[34:35], v[34:35], v[190:191]
	v_cvt_pk_bf16_f32 v202, v32, v33
	v_cvt_pk_bf16_f32 v203, v34, v35
	global_store_dwordx2 v2, v[202:203], s[8:9]
	s_add_u32 s8, s8, 0x100000
	s_addc_u32 s9, s9, 0
	s_waitcnt vmcnt(33)
	v_pk_add_f32 v[36:37], v[36:37], v[100:101]
	v_pk_add_f32 v[38:39], v[38:39], v[102:103]
	v_mul_f32_e32 v180, v36, v36
	v_fmac_f32_e32 v180, v37, v37
	v_fmac_f32_e32 v180, v38, v38
	v_fmac_f32_e32 v180, v39, v39
	v_lshlrev_b32_e32 v184, 16, v152
	v_and_b32_e32 v185, 0xffff0000, v152
	v_add_f32_dpp v180, v180, v180 quad_perm:[1,0,3,2] row_mask:0xf bank_mask:0xf
	v_lshlrev_b32_e32 v186, 16, v153
	v_and_b32_e32 v187, 0xffff0000, v153
	v_add_f32_dpp v180, v180, v180 quad_perm:[2,3,0,1] row_mask:0xf bank_mask:0xf
	v_pk_mul_f32 v[188:189], v[184:185], v[8:9]
	v_pk_mul_f32 v[190:191], v[186:187], v[8:9]
	v_add_f32_dpp v180, v180, v180 row_ror:4 row_mask:0xf bank_mask:0xf
	v_exp_f32_e32 v188, v188
	v_exp_f32_e32 v189, v189
	v_add_f32_dpp v180, v180, v180 row_ror:8 row_mask:0xf bank_mask:0xf
	v_exp_f32_e32 v190, v190
	v_exp_f32_e32 v191, v191
	v_mov_b32_e32 v181, v180
	v_pk_add_f32 v[188:189], v[188:189], v[10:11]
	v_pk_add_f32 v[190:191], v[190:191], v[10:11]
	v_permlane16_swap_b32_e32 v180, v181
	v_rcp_f32_e32 v188, v188
	v_rcp_f32_e32 v189, v189
	v_add_f32_e32 v180, v180, v181
	v_rcp_f32_e32 v190, v190
	v_rcp_f32_e32 v191, v191
	v_mov_b32_e32 v182, s21
	v_fmac_f32_e32 v182, s20, v180
	v_rsq_f32_e32 v182, v182
	v_pk_mul_f32 v[188:189], v[188:189], v[184:185]
	v_pk_mul_f32 v[190:191], v[190:191], v[186:187]
	v_mov_b32_e32 v183, v182
	v_pk_mul_f32 v[188:189], v[188:189], v[4:5]
	v_pk_mul_f32 v[190:191], v[190:191], v[6:7]
	v_pk_mul_f32 v[36:37], v[36:37], v[182:183]
	v_pk_mul_f32 v[38:39], v[38:39], v[182:183]
	v_pk_mul_f32 v[36:37], v[36:37], v[188:189]
	v_pk_mul_f32 v[38:39], v[38:39], v[190:191]
	v_cvt_pk_bf16_f32 v204, v36, v37
	v_cvt_pk_bf16_f32 v205, v38, v39
	global_store_dwordx2 v2, v[204:205], s[8:9]
	s_add_u32 s8, s8, 0x100000
	s_addc_u32 s9, s9, 0
	s_waitcnt vmcnt(31)
	v_pk_add_f32 v[40:41], v[40:41], v[104:105]
	v_pk_add_f32 v[42:43], v[42:43], v[106:107]
	v_mul_f32_e32 v180, v40, v40
	v_fmac_f32_e32 v180, v41, v41
	v_fmac_f32_e32 v180, v42, v42
	v_fmac_f32_e32 v180, v43, v43
	v_lshlrev_b32_e32 v184, 16, v156
	v_and_b32_e32 v185, 0xffff0000, v156
	v_add_f32_dpp v180, v180, v180 quad_perm:[1,0,3,2] row_mask:0xf bank_mask:0xf
	v_lshlrev_b32_e32 v186, 16, v157
	v_and_b32_e32 v187, 0xffff0000, v157
	v_add_f32_dpp v180, v180, v180 quad_perm:[2,3,0,1] row_mask:0xf bank_mask:0xf
	v_pk_mul_f32 v[188:189], v[184:185], v[8:9]
	v_pk_mul_f32 v[190:191], v[186:187], v[8:9]
	v_add_f32_dpp v180, v180, v180 row_ror:4 row_mask:0xf bank_mask:0xf
	v_exp_f32_e32 v188, v188
	v_exp_f32_e32 v189, v189
	v_add_f32_dpp v180, v180, v180 row_ror:8 row_mask:0xf bank_mask:0xf
	v_exp_f32_e32 v190, v190
	v_exp_f32_e32 v191, v191
	v_mov_b32_e32 v181, v180
	v_pk_add_f32 v[188:189], v[188:189], v[10:11]
	v_pk_add_f32 v[190:191], v[190:191], v[10:11]
	v_permlane16_swap_b32_e32 v180, v181
	v_rcp_f32_e32 v188, v188
	v_rcp_f32_e32 v189, v189
	v_add_f32_e32 v180, v180, v181
	v_rcp_f32_e32 v190, v190
	v_rcp_f32_e32 v191, v191
	v_mov_b32_e32 v182, s21
	v_fmac_f32_e32 v182, s20, v180
	v_rsq_f32_e32 v182, v182
	v_pk_mul_f32 v[188:189], v[188:189], v[184:185]
	v_pk_mul_f32 v[190:191], v[190:191], v[186:187]
	v_mov_b32_e32 v183, v182
	v_pk_mul_f32 v[188:189], v[188:189], v[4:5]
	v_pk_mul_f32 v[190:191], v[190:191], v[6:7]
	v_pk_mul_f32 v[40:41], v[40:41], v[182:183]
	v_pk_mul_f32 v[42:43], v[42:43], v[182:183]
	v_pk_mul_f32 v[40:41], v[40:41], v[188:189]
	v_pk_mul_f32 v[42:43], v[42:43], v[190:191]
	v_cvt_pk_bf16_f32 v206, v40, v41
	v_cvt_pk_bf16_f32 v207, v42, v43
	global_store_dwordx2 v2, v[206:207], s[8:9]
	s_add_u32 s8, s8, 0x100000
	s_addc_u32 s9, s9, 0
	s_waitcnt vmcnt(29)
	v_pk_add_f32 v[44:45], v[44:45], v[108:109]
	v_pk_add_f32 v[46:47], v[46:47], v[110:111]
	v_mul_f32_e32 v180, v44, v44
	v_fmac_f32_e32 v180, v45, v45
	v_fmac_f32_e32 v180, v46, v46
	v_fmac_f32_e32 v180, v47, v47
	v_lshlrev_b32_e32 v184, 16, v158
	v_and_b32_e32 v185, 0xffff0000, v158
	v_add_f32_dpp v180, v180, v180 quad_perm:[1,0,3,2] row_mask:0xf bank_mask:0xf
	v_lshlrev_b32_e32 v186, 16, v159
	v_and_b32_e32 v187, 0xffff0000, v159
	v_add_f32_dpp v180, v180, v180 quad_perm:[2,3,0,1] row_mask:0xf bank_mask:0xf
	v_pk_mul_f32 v[188:189], v[184:185], v[8:9]
	v_pk_mul_f32 v[190:191], v[186:187], v[8:9]
	v_add_f32_dpp v180, v180, v180 row_ror:4 row_mask:0xf bank_mask:0xf
	v_exp_f32_e32 v188, v188
	v_exp_f32_e32 v189, v189
	v_add_f32_dpp v180, v180, v180 row_ror:8 row_mask:0xf bank_mask:0xf
	v_exp_f32_e32 v190, v190
	v_exp_f32_e32 v191, v191
	v_mov_b32_e32 v181, v180
	v_pk_add_f32 v[188:189], v[188:189], v[10:11]
	v_pk_add_f32 v[190:191], v[190:191], v[10:11]
	v_permlane16_swap_b32_e32 v180, v181
	v_rcp_f32_e32 v188, v188
	v_rcp_f32_e32 v189, v189
	v_add_f32_e32 v180, v180, v181
	v_rcp_f32_e32 v190, v190
	v_rcp_f32_e32 v191, v191
	v_mov_b32_e32 v182, s21
	v_fmac_f32_e32 v182, s20, v180
	v_rsq_f32_e32 v182, v182
	v_pk_mul_f32 v[188:189], v[188:189], v[184:185]
	v_pk_mul_f32 v[190:191], v[190:191], v[186:187]
	v_mov_b32_e32 v183, v182
	v_pk_mul_f32 v[188:189], v[188:189], v[4:5]
	v_pk_mul_f32 v[190:191], v[190:191], v[6:7]
	v_pk_mul_f32 v[44:45], v[44:45], v[182:183]
	v_pk_mul_f32 v[46:47], v[46:47], v[182:183]
	v_pk_mul_f32 v[44:45], v[44:45], v[188:189]
	v_pk_mul_f32 v[46:47], v[46:47], v[190:191]
	v_cvt_pk_bf16_f32 v200, v44, v45
	v_cvt_pk_bf16_f32 v201, v46, v47
	global_store_dwordx2 v2, v[200:201], s[8:9]
	s_add_u32 s8, s8, 0x100000
	s_addc_u32 s9, s9, 0
	s_waitcnt vmcnt(27)
	v_pk_add_f32 v[48:49], v[48:49], v[112:113]
	v_pk_add_f32 v[50:51], v[50:51], v[114:115]
	v_mul_f32_e32 v180, v48, v48
	v_fmac_f32_e32 v180, v49, v49
	v_fmac_f32_e32 v180, v50, v50
	v_fmac_f32_e32 v180, v51, v51
	v_lshlrev_b32_e32 v184, 16, v160
	v_and_b32_e32 v185, 0xffff0000, v160
	v_add_f32_dpp v180, v180, v180 quad_perm:[1,0,3,2] row_mask:0xf bank_mask:0xf
	v_lshlrev_b32_e32 v186, 16, v161
	v_and_b32_e32 v187, 0xffff0000, v161
	v_add_f32_dpp v180, v180, v180 quad_perm:[2,3,0,1] row_mask:0xf bank_mask:0xf
	v_pk_mul_f32 v[188:189], v[184:185], v[8:9]
	v_pk_mul_f32 v[190:191], v[186:187], v[8:9]
	v_add_f32_dpp v180, v180, v180 row_ror:4 row_mask:0xf bank_mask:0xf
	v_exp_f32_e32 v188, v188
	v_exp_f32_e32 v189, v189
	v_add_f32_dpp v180, v180, v180 row_ror:8 row_mask:0xf bank_mask:0xf
	v_exp_f32_e32 v190, v190
	v_exp_f32_e32 v191, v191
	v_mov_b32_e32 v181, v180
	v_pk_add_f32 v[188:189], v[188:189], v[10:11]
	v_pk_add_f32 v[190:191], v[190:191], v[10:11]
	v_permlane16_swap_b32_e32 v180, v181
	v_rcp_f32_e32 v188, v188
	v_rcp_f32_e32 v189, v189
	v_add_f32_e32 v180, v180, v181
	v_rcp_f32_e32 v190, v190
	v_rcp_f32_e32 v191, v191
	v_mov_b32_e32 v182, s21
	v_fmac_f32_e32 v182, s20, v180
	v_rsq_f32_e32 v182, v182
	v_pk_mul_f32 v[188:189], v[188:189], v[184:185]
	v_pk_mul_f32 v[190:191], v[190:191], v[186:187]
	v_mov_b32_e32 v183, v182
	v_pk_mul_f32 v[188:189], v[188:189], v[4:5]
	v_pk_mul_f32 v[190:191], v[190:191], v[6:7]
	v_pk_mul_f32 v[48:49], v[48:49], v[182:183]
	v_pk_mul_f32 v[50:51], v[50:51], v[182:183]
	v_pk_mul_f32 v[48:49], v[48:49], v[188:189]
	v_pk_mul_f32 v[50:51], v[50:51], v[190:191]
	v_cvt_pk_bf16_f32 v202, v48, v49
	v_cvt_pk_bf16_f32 v203, v50, v51
	global_store_dwordx2 v2, v[202:203], s[8:9]
	s_add_u32 s8, s8, 0x100000
	s_addc_u32 s9, s9, 0
	s_waitcnt vmcnt(25)
	v_pk_add_f32 v[52:53], v[52:53], v[116:117]
	v_pk_add_f32 v[54:55], v[54:55], v[118:119]
	v_mul_f32_e32 v180, v52, v52
	v_fmac_f32_e32 v180, v53, v53
	v_fmac_f32_e32 v180, v54, v54
	v_fmac_f32_e32 v180, v55, v55
	v_lshlrev_b32_e32 v184, 16, v162
	v_and_b32_e32 v185, 0xffff0000, v162
	v_add_f32_dpp v180, v180, v180 quad_perm:[1,0,3,2] row_mask:0xf bank_mask:0xf
	v_lshlrev_b32_e32 v186, 16, v163
	v_and_b32_e32 v187, 0xffff0000, v163
	v_add_f32_dpp v180, v180, v180 quad_perm:[2,3,0,1] row_mask:0xf bank_mask:0xf
	v_pk_mul_f32 v[188:189], v[184:185], v[8:9]
	v_pk_mul_f32 v[190:191], v[186:187], v[8:9]
	v_add_f32_dpp v180, v180, v180 row_ror:4 row_mask:0xf bank_mask:0xf
	v_exp_f32_e32 v188, v188
	v_exp_f32_e32 v189, v189
	v_add_f32_dpp v180, v180, v180 row_ror:8 row_mask:0xf bank_mask:0xf
	v_exp_f32_e32 v190, v190
	v_exp_f32_e32 v191, v191
	v_mov_b32_e32 v181, v180
	v_pk_add_f32 v[188:189], v[188:189], v[10:11]
	v_pk_add_f32 v[190:191], v[190:191], v[10:11]
	v_permlane16_swap_b32_e32 v180, v181
	v_rcp_f32_e32 v188, v188
	v_rcp_f32_e32 v189, v189
	v_add_f32_e32 v180, v180, v181
	v_rcp_f32_e32 v190, v190
	v_rcp_f32_e32 v191, v191
	v_mov_b32_e32 v182, s21
	v_fmac_f32_e32 v182, s20, v180
	v_rsq_f32_e32 v182, v182
	v_pk_mul_f32 v[188:189], v[188:189], v[184:185]
	v_pk_mul_f32 v[190:191], v[190:191], v[186:187]
	v_mov_b32_e32 v183, v182
	v_pk_mul_f32 v[188:189], v[188:189], v[4:5]
	v_pk_mul_f32 v[190:191], v[190:191], v[6:7]
	v_pk_mul_f32 v[52:53], v[52:53], v[182:183]
	v_pk_mul_f32 v[54:55], v[54:55], v[182:183]
	v_pk_mul_f32 v[52:53], v[52:53], v[188:189]
	v_pk_mul_f32 v[54:55], v[54:55], v[190:191]
	v_cvt_pk_bf16_f32 v204, v52, v53
	v_cvt_pk_bf16_f32 v205, v54, v55
	global_store_dwordx2 v2, v[204:205], s[8:9]
	s_add_u32 s8, s8, 0x100000
	s_addc_u32 s9, s9, 0
	s_waitcnt vmcnt(23)
	v_pk_add_f32 v[56:57], v[56:57], v[120:121]
	v_pk_add_f32 v[58:59], v[58:59], v[122:123]
	v_mul_f32_e32 v180, v56, v56
	v_fmac_f32_e32 v180, v57, v57
	v_fmac_f32_e32 v180, v58, v58
	v_fmac_f32_e32 v180, v59, v59
	v_lshlrev_b32_e32 v184, 16, v164
	v_and_b32_e32 v185, 0xffff0000, v164
	v_add_f32_dpp v180, v180, v180 quad_perm:[1,0,3,2] row_mask:0xf bank_mask:0xf
	v_lshlrev_b32_e32 v186, 16, v165
	v_and_b32_e32 v187, 0xffff0000, v165
	v_add_f32_dpp v180, v180, v180 quad_perm:[2,3,0,1] row_mask:0xf bank_mask:0xf
	v_pk_mul_f32 v[188:189], v[184:185], v[8:9]
	v_pk_mul_f32 v[190:191], v[186:187], v[8:9]
	v_add_f32_dpp v180, v180, v180 row_ror:4 row_mask:0xf bank_mask:0xf
	v_exp_f32_e32 v188, v188
	v_exp_f32_e32 v189, v189
	v_add_f32_dpp v180, v180, v180 row_ror:8 row_mask:0xf bank_mask:0xf
	v_exp_f32_e32 v190, v190
	v_exp_f32_e32 v191, v191
	v_mov_b32_e32 v181, v180
	v_pk_add_f32 v[188:189], v[188:189], v[10:11]
	v_pk_add_f32 v[190:191], v[190:191], v[10:11]
	v_permlane16_swap_b32_e32 v180, v181
	v_rcp_f32_e32 v188, v188
	v_rcp_f32_e32 v189, v189
	v_add_f32_e32 v180, v180, v181
	v_rcp_f32_e32 v190, v190
	v_rcp_f32_e32 v191, v191
	v_mov_b32_e32 v182, s21
	v_fmac_f32_e32 v182, s20, v180
	v_rsq_f32_e32 v182, v182
	v_pk_mul_f32 v[188:189], v[188:189], v[184:185]
	v_pk_mul_f32 v[190:191], v[190:191], v[186:187]
	v_mov_b32_e32 v183, v182
	v_pk_mul_f32 v[188:189], v[188:189], v[4:5]
	v_pk_mul_f32 v[190:191], v[190:191], v[6:7]
	v_pk_mul_f32 v[56:57], v[56:57], v[182:183]
	v_pk_mul_f32 v[58:59], v[58:59], v[182:183]
	v_pk_mul_f32 v[56:57], v[56:57], v[188:189]
	v_pk_mul_f32 v[58:59], v[58:59], v[190:191]
	v_cvt_pk_bf16_f32 v206, v56, v57
	v_cvt_pk_bf16_f32 v207, v58, v59
	global_store_dwordx2 v2, v[206:207], s[8:9]
	s_add_u32 s8, s8, 0x100000
	s_addc_u32 s9, s9, 0
	s_waitcnt vmcnt(21)
	v_pk_add_f32 v[60:61], v[60:61], v[124:125]
	v_pk_add_f32 v[62:63], v[62:63], v[126:127]
	v_mul_f32_e32 v180, v60, v60
	v_fmac_f32_e32 v180, v61, v61
	v_fmac_f32_e32 v180, v62, v62
	v_fmac_f32_e32 v180, v63, v63
	v_lshlrev_b32_e32 v184, 16, v166
	v_and_b32_e32 v185, 0xffff0000, v166
	v_add_f32_dpp v180, v180, v180 quad_perm:[1,0,3,2] row_mask:0xf bank_mask:0xf
	v_lshlrev_b32_e32 v186, 16, v167
	v_and_b32_e32 v187, 0xffff0000, v167
	v_add_f32_dpp v180, v180, v180 quad_perm:[2,3,0,1] row_mask:0xf bank_mask:0xf
	v_pk_mul_f32 v[188:189], v[184:185], v[8:9]
	v_pk_mul_f32 v[190:191], v[186:187], v[8:9]
	v_add_f32_dpp v180, v180, v180 row_ror:4 row_mask:0xf bank_mask:0xf
	v_exp_f32_e32 v188, v188
	v_exp_f32_e32 v189, v189
	v_add_f32_dpp v180, v180, v180 row_ror:8 row_mask:0xf bank_mask:0xf
	v_exp_f32_e32 v190, v190
	v_exp_f32_e32 v191, v191
	v_mov_b32_e32 v181, v180
	v_pk_add_f32 v[188:189], v[188:189], v[10:11]
	v_pk_add_f32 v[190:191], v[190:191], v[10:11]
	v_permlane16_swap_b32_e32 v180, v181
	v_rcp_f32_e32 v188, v188
	v_rcp_f32_e32 v189, v189
	v_add_f32_e32 v180, v180, v181
	v_rcp_f32_e32 v190, v190
	v_rcp_f32_e32 v191, v191
	v_mov_b32_e32 v182, s21
	v_fmac_f32_e32 v182, s20, v180
	v_rsq_f32_e32 v182, v182
	v_pk_mul_f32 v[188:189], v[188:189], v[184:185]
	v_pk_mul_f32 v[190:191], v[190:191], v[186:187]
	v_mov_b32_e32 v183, v182
	v_pk_mul_f32 v[188:189], v[188:189], v[4:5]
	v_pk_mul_f32 v[190:191], v[190:191], v[6:7]
	v_pk_mul_f32 v[60:61], v[60:61], v[182:183]
	v_pk_mul_f32 v[62:63], v[62:63], v[182:183]
	v_pk_mul_f32 v[60:61], v[60:61], v[188:189]
	v_pk_mul_f32 v[62:63], v[62:63], v[190:191]
	v_cvt_pk_bf16_f32 v200, v60, v61
	v_cvt_pk_bf16_f32 v201, v62, v63
	global_store_dwordx2 v2, v[200:201], s[8:9]
	s_add_u32 s8, s8, 0x100000
	s_addc_u32 s9, s9, 0
	s_waitcnt vmcnt(19)
	v_pk_add_f32 v[64:65], v[64:65], v[128:129]
	v_pk_add_f32 v[66:67], v[66:67], v[130:131]
	v_mul_f32_e32 v180, v64, v64
	v_fmac_f32_e32 v180, v65, v65
	v_fmac_f32_e32 v180, v66, v66
	v_fmac_f32_e32 v180, v67, v67
	v_lshlrev_b32_e32 v184, 16, v168
	v_and_b32_e32 v185, 0xffff0000, v168
	v_add_f32_dpp v180, v180, v180 quad_perm:[1,0,3,2] row_mask:0xf bank_mask:0xf
	v_lshlrev_b32_e32 v186, 16, v169
	v_and_b32_e32 v187, 0xffff0000, v169
	v_add_f32_dpp v180, v180, v180 quad_perm:[2,3,0,1] row_mask:0xf bank_mask:0xf
	v_pk_mul_f32 v[188:189], v[184:185], v[8:9]
	v_pk_mul_f32 v[190:191], v[186:187], v[8:9]
	v_add_f32_dpp v180, v180, v180 row_ror:4 row_mask:0xf bank_mask:0xf
	v_exp_f32_e32 v188, v188
	v_exp_f32_e32 v189, v189
	v_add_f32_dpp v180, v180, v180 row_ror:8 row_mask:0xf bank_mask:0xf
	v_exp_f32_e32 v190, v190
	v_exp_f32_e32 v191, v191
	v_mov_b32_e32 v181, v180
	v_pk_add_f32 v[188:189], v[188:189], v[10:11]
	v_pk_add_f32 v[190:191], v[190:191], v[10:11]
	v_permlane16_swap_b32_e32 v180, v181
	v_rcp_f32_e32 v188, v188
	v_rcp_f32_e32 v189, v189
	v_add_f32_e32 v180, v180, v181
	v_rcp_f32_e32 v190, v190
	v_rcp_f32_e32 v191, v191
	v_mov_b32_e32 v182, s21
	v_fmac_f32_e32 v182, s20, v180
	v_rsq_f32_e32 v182, v182
	v_pk_mul_f32 v[188:189], v[188:189], v[184:185]
	v_pk_mul_f32 v[190:191], v[190:191], v[186:187]
	v_mov_b32_e32 v183, v182
	v_pk_mul_f32 v[188:189], v[188:189], v[4:5]
	v_pk_mul_f32 v[190:191], v[190:191], v[6:7]
	v_pk_mul_f32 v[64:65], v[64:65], v[182:183]
	v_pk_mul_f32 v[66:67], v[66:67], v[182:183]
	v_pk_mul_f32 v[64:65], v[64:65], v[188:189]
	v_pk_mul_f32 v[66:67], v[66:67], v[190:191]
	v_cvt_pk_bf16_f32 v202, v64, v65
	v_cvt_pk_bf16_f32 v203, v66, v67
	global_store_dwordx2 v2, v[202:203], s[8:9]
	s_add_u32 s8, s8, 0x100000
	s_addc_u32 s9, s9, 0
	s_waitcnt vmcnt(17)
	v_pk_add_f32 v[68:69], v[68:69], v[132:133]
	v_pk_add_f32 v[70:71], v[70:71], v[134:135]
	v_mul_f32_e32 v180, v68, v68
	v_fmac_f32_e32 v180, v69, v69
	v_fmac_f32_e32 v180, v70, v70
	v_fmac_f32_e32 v180, v71, v71
	v_lshlrev_b32_e32 v184, 16, v170
	v_and_b32_e32 v185, 0xffff0000, v170
	v_add_f32_dpp v180, v180, v180 quad_perm:[1,0,3,2] row_mask:0xf bank_mask:0xf
	v_lshlrev_b32_e32 v186, 16, v171
	v_and_b32_e32 v187, 0xffff0000, v171
	v_add_f32_dpp v180, v180, v180 quad_perm:[2,3,0,1] row_mask:0xf bank_mask:0xf
	v_pk_mul_f32 v[188:189], v[184:185], v[8:9]
	v_pk_mul_f32 v[190:191], v[186:187], v[8:9]
	v_add_f32_dpp v180, v180, v180 row_ror:4 row_mask:0xf bank_mask:0xf
	v_exp_f32_e32 v188, v188
	v_exp_f32_e32 v189, v189
	v_add_f32_dpp v180, v180, v180 row_ror:8 row_mask:0xf bank_mask:0xf
	v_exp_f32_e32 v190, v190
	v_exp_f32_e32 v191, v191
	v_mov_b32_e32 v181, v180
	v_pk_add_f32 v[188:189], v[188:189], v[10:11]
	v_pk_add_f32 v[190:191], v[190:191], v[10:11]
	v_permlane16_swap_b32_e32 v180, v181
	v_rcp_f32_e32 v188, v188
	v_rcp_f32_e32 v189, v189
	v_add_f32_e32 v180, v180, v181
	v_rcp_f32_e32 v190, v190
	v_rcp_f32_e32 v191, v191
	v_mov_b32_e32 v182, s21
	v_fmac_f32_e32 v182, s20, v180
	v_rsq_f32_e32 v182, v182
	v_pk_mul_f32 v[188:189], v[188:189], v[184:185]
	v_pk_mul_f32 v[190:191], v[190:191], v[186:187]
	v_mov_b32_e32 v183, v182
	v_pk_mul_f32 v[188:189], v[188:189], v[4:5]
	v_pk_mul_f32 v[190:191], v[190:191], v[6:7]
	v_pk_mul_f32 v[68:69], v[68:69], v[182:183]
	v_pk_mul_f32 v[70:71], v[70:71], v[182:183]
	v_pk_mul_f32 v[68:69], v[68:69], v[188:189]
	v_pk_mul_f32 v[70:71], v[70:71], v[190:191]
	v_cvt_pk_bf16_f32 v204, v68, v69
	v_cvt_pk_bf16_f32 v205, v70, v71
	global_store_dwordx2 v2, v[204:205], s[8:9]
	s_add_u32 s8, s8, 0x100000
	s_addc_u32 s9, s9, 0
	s_waitcnt vmcnt(15)
	v_pk_add_f32 v[72:73], v[72:73], v[136:137]
	v_pk_add_f32 v[74:75], v[74:75], v[138:139]
	v_mul_f32_e32 v180, v72, v72
	v_fmac_f32_e32 v180, v73, v73
	v_fmac_f32_e32 v180, v74, v74
	v_fmac_f32_e32 v180, v75, v75
	v_lshlrev_b32_e32 v184, 16, v172
	v_and_b32_e32 v185, 0xffff0000, v172
	v_add_f32_dpp v180, v180, v180 quad_perm:[1,0,3,2] row_mask:0xf bank_mask:0xf
	v_lshlrev_b32_e32 v186, 16, v173
	v_and_b32_e32 v187, 0xffff0000, v173
	v_add_f32_dpp v180, v180, v180 quad_perm:[2,3,0,1] row_mask:0xf bank_mask:0xf
	v_pk_mul_f32 v[188:189], v[184:185], v[8:9]
	v_pk_mul_f32 v[190:191], v[186:187], v[8:9]
	v_add_f32_dpp v180, v180, v180 row_ror:4 row_mask:0xf bank_mask:0xf
	v_exp_f32_e32 v188, v188
	v_exp_f32_e32 v189, v189
	v_add_f32_dpp v180, v180, v180 row_ror:8 row_mask:0xf bank_mask:0xf
	v_exp_f32_e32 v190, v190
	v_exp_f32_e32 v191, v191
	v_mov_b32_e32 v181, v180
	v_pk_add_f32 v[188:189], v[188:189], v[10:11]
	v_pk_add_f32 v[190:191], v[190:191], v[10:11]
	v_permlane16_swap_b32_e32 v180, v181
	v_rcp_f32_e32 v188, v188
	v_rcp_f32_e32 v189, v189
	v_add_f32_e32 v180, v180, v181
	v_rcp_f32_e32 v190, v190
	v_rcp_f32_e32 v191, v191
	v_mov_b32_e32 v182, s21
	v_fmac_f32_e32 v182, s20, v180
	v_rsq_f32_e32 v182, v182
	v_pk_mul_f32 v[188:189], v[188:189], v[184:185]
	v_pk_mul_f32 v[190:191], v[190:191], v[186:187]
	v_mov_b32_e32 v183, v182
	v_pk_mul_f32 v[188:189], v[188:189], v[4:5]
	v_pk_mul_f32 v[190:191], v[190:191], v[6:7]
	v_pk_mul_f32 v[72:73], v[72:73], v[182:183]
	v_pk_mul_f32 v[74:75], v[74:75], v[182:183]
	v_pk_mul_f32 v[72:73], v[72:73], v[188:189]
	v_pk_mul_f32 v[74:75], v[74:75], v[190:191]
	v_cvt_pk_bf16_f32 v206, v72, v73
	v_cvt_pk_bf16_f32 v207, v74, v75
	global_store_dwordx2 v2, v[206:207], s[8:9]
	s_waitcnt vmcnt(0)
	s_branch .LBB0_804

.Ltrs_after9:
	ds_write_b32 v1, v10 offset:0
	ds_write_b32 v1, v11 offset:4
	ds_write_b32 v1, v12 offset:8
	ds_write_b32 v1, v13 offset:12
	ds_write_b32 v1, v14 offset:1056
	ds_write_b32 v1, v15 offset:1060
	ds_write_b32 v1, v16 offset:1064
	ds_write_b32 v1, v17 offset:1068
	ds_write_b32 v1, v18 offset:2112
	ds_write_b32 v1, v19 offset:2116
	ds_write_b32 v1, v20 offset:2120
	ds_write_b32 v1, v21 offset:2124
	ds_write_b32 v1, v22 offset:3168
	ds_write_b32 v1, v23 offset:3172
	ds_write_b32 v1, v24 offset:3176
	ds_write_b32 v1, v25 offset:3180
	ds_write_b32 v1, v26 offset:4224
	ds_write_b32 v1, v27 offset:4228
	ds_write_b32 v1, v28 offset:4232
	ds_write_b32 v1, v29 offset:4236
	ds_write_b32 v1, v30 offset:5280
	ds_write_b32 v1, v31 offset:5284
	ds_write_b32 v1, v32 offset:5288
	ds_write_b32 v1, v33 offset:5292
	ds_write_b32 v1, v34 offset:6336
	ds_write_b32 v1, v35 offset:6340
	ds_write_b32 v1, v36 offset:6344
	ds_write_b32 v1, v37 offset:6348
	ds_write_b32 v1, v38 offset:7392
	ds_write_b32 v1, v39 offset:7396
	ds_write_b32 v1, v40 offset:7400
	ds_write_b32 v1, v41 offset:7404
	v_mad_u32_u24 v9, v5, s22, v6
	s_lshl_b32 s46, s22, 3
	s_waitcnt lgkmcnt(0)
	ds_read_b32 v74, v2 offset:0
	ds_read_b32 v75, v2 offset:132
	ds_read_b32 v76, v2 offset:264
	ds_read_b32 v77, v2 offset:396
	ds_read_b32 v78, v2 offset:528
	ds_read_b32 v79, v2 offset:660
	ds_read_b32 v80, v2 offset:792
	ds_read_b32 v81, v2 offset:924
	ds_read_b32 v82, v2 offset:32
	ds_read_b32 v83, v2 offset:164
	ds_read_b32 v84, v2 offset:296
	ds_read_b32 v85, v2 offset:428
	ds_read_b32 v86, v2 offset:560
	ds_read_b32 v87, v2 offset:692
	ds_read_b32 v88, v2 offset:824
	ds_read_b32 v89, v2 offset:956
	s_waitcnt lgkmcnt(8)
	v_cvt_pk_bf16_f32 v106, v74, v75
	v_cvt_pk_bf16_f32 v107, v76, v77
	v_cvt_pk_bf16_f32 v108, v78, v79
	v_cvt_pk_bf16_f32 v109, v80, v81
	global_store_dwordx4 v9, v[106:109], s[18:19] nt
	s_add_u32 s18, s18, s46
	s_addc_u32 s19, s19, 0
	ds_read_b32 v90, v2 offset:64
	ds_read_b32 v91, v2 offset:196
	ds_read_b32 v92, v2 offset:328
	ds_read_b32 v93, v2 offset:460
	ds_read_b32 v94, v2 offset:592
	ds_read_b32 v95, v2 offset:724
	ds_read_b32 v96, v2 offset:856
	ds_read_b32 v97, v2 offset:988
	s_waitcnt lgkmcnt(8)
	v_cvt_pk_bf16_f32 v110, v82, v83
	v_cvt_pk_bf16_f32 v111, v84, v85
	v_cvt_pk_bf16_f32 v112, v86, v87
	v_cvt_pk_bf16_f32 v113, v88, v89
	global_store_dwordx4 v9, v[110:113], s[18:19] nt
	s_add_u32 s18, s18, s46
	s_addc_u32 s19, s19, 0
	ds_read_b32 v98, v2 offset:96
	ds_read_b32 v99, v2 offset:228
	ds_read_b32 v100, v2 offset:360
	ds_read_b32 v101, v2 offset:492
	ds_read_b32 v102, v2 offset:624
	ds_read_b32 v103, v2 offset:756
	ds_read_b32 v104, v2 offset:888
	ds_read_b32 v105, v2 offset:1020
	s_waitcnt lgkmcnt(8)
	v_cvt_pk_bf16_f32 v106, v90, v91
	v_cvt_pk_bf16_f32 v107, v92, v93
	v_cvt_pk_bf16_f32 v108, v94, v95
	v_cvt_pk_bf16_f32 v109, v96, v97
	global_store_dwordx4 v9, v[106:109], s[18:19] nt
	s_add_u32 s18, s18, s46
	s_addc_u32 s19, s19, 0
	s_waitcnt lgkmcnt(0)
	v_cvt_pk_bf16_f32 v110, v98, v99
	v_cvt_pk_bf16_f32 v111, v100, v101
	v_cvt_pk_bf16_f32 v112, v102, v103
	v_cvt_pk_bf16_f32 v113, v104, v105
	global_store_dwordx4 v9, v[110:113], s[18:19] nt
	s_cmp_eq_u32 s24, 0
	s_cbranch_scc1 .Ltrs_done
	s_add_u32 s12, s12, 1024
	s_cmp_lt_u32 s12, 60928
	s_cselect_b32 s24, 1, 0
	s_cbranch_scc0 .Ltrs_nonext17
	s_cmp_ge_u32 s12, 33280
	s_cselect_b32 s41, 1, 0
	s_cselect_b32 s26, 33280, 0
	s_sub_u32 s42, s12, s26
	s_cmp_ge_u32 s42, 12288
	s_cbranch_scc1 .Ltrs_m20
	s_mul_i32 s43, s42, 43691
	s_lshr_b32 s43, s43, 24
	s_mul_i32 s26, s43, 384
	s_sub_u32 s44, s42, s26
	s_mov_b32 s14, s0
	s_mov_b32 s15, s1
	s_mov_b32 s36, 0xc000
	s_mov_b32 s37, 0x6000000
	s_mov_b32 s38, 0x0
	s_mov_b32 s39, 0x3000000
	s_mov_b32 s40, 0x1000
	s_branch .Ltrs_dec_done19

.LBB0_2040:
.LBB0_2041:
	s_waitcnt vmcnt(0) lgkmcnt(0)
	s_load_dwordx2 s[0:1], s[92:93], 0x68
	v_and_b32_e32 v2, 63, v154
	v_lshlrev_b32_e32 v1, 4, v2
	v_and_b32_e32 v180, 31, v2
	v_lshlrev_b32_e32 v180, 4, v180
	v_lshlrev_b32_e32 v2, 3, v2
	v_readfirstlane_b32 s10, v154
	s_lshr_b32 s10, s10, 6
	s_lshl_b32 s12, s96, 3
	s_add_u32 s10, s10, s12
	s_lshl_b32 s12, s10, 10
	s_add_u32 s2, s90, 0x24918000
	s_addc_u32 s3, s91, 0
	s_add_u32 s2, s2, s12
	s_addc_u32 s3, s3, 0
	s_add_u32 s4, s2, 0x2000000
	s_addc_u32 s5, s3, 0
	s_lshl_b32 s12, s10, 9
	s_add_u32 s8, s90, 0x13918000
	s_addc_u32 s9, s91, 0
	s_add_u32 s8, s8, s12
	s_addc_u32 s9, s9, 0
	s_lshr_b32 s12, s10, 2
	s_mul_i32 s12, s12, 24576
	s_and_b32 s13, s10, 3
	s_lshl_b32 s13, s13, 9
	s_add_u32 s12, s12, s13
	s_add_u32 s12, s12, 8192
	s_add_u32 s6, s90, 0x15918000
	s_addc_u32 s7, s91, 0
	s_add_u32 s6, s6, s12
	s_addc_u32 s7, s7, 0
	s_waitcnt lgkmcnt(0)
	s_add_u32 s0, s0, 512
	s_addc_u32 s1, s1, 0
	global_load_dwordx4 v[4:7], v180, s[0:1]
	global_load_dwordx4 v[12:15], v1, s[2:3] nt
	global_load_dwordx4 v[76:79], v1, s[4:5] nt
	global_load_dwordx2 v[140:141], v2, s[6:7] nt
	s_add_u32 s2, s2, 0x200000
	s_addc_u32 s3, s3, 0
	s_add_u32 s4, s4, 0x200000
	s_addc_u32 s5, s5, 0
	s_add_u32 s6, s6, 0xc00000
	s_addc_u32 s7, s7, 0
	global_load_dwordx4 v[16:19], v1, s[2:3] nt
	global_load_dwordx4 v[80:83], v1, s[4:5] nt
	global_load_dwordx2 v[142:143], v2, s[6:7] nt
	s_add_u32 s2, s2, 0x200000
	s_addc_u32 s3, s3, 0
	s_add_u32 s4, s4, 0x200000
	s_addc_u32 s5, s5, 0
	s_add_u32 s6, s6, 0xc00000
	s_addc_u32 s7, s7, 0
	global_load_dwordx4 v[20:23], v1, s[2:3] nt
	global_load_dwordx4 v[84:87], v1, s[4:5] nt
	global_load_dwordx2 v[144:145], v2, s[6:7] nt
	s_add_u32 s2, s2, 0x200000
	s_addc_u32 s3, s3, 0
	s_add_u32 s4, s4, 0x200000
	s_addc_u32 s5, s5, 0
	s_add_u32 s6, s6, 0xc00000
	s_addc_u32 s7, s7, 0
	global_load_dwordx4 v[24:27], v1, s[2:3] nt
	global_load_dwordx4 v[88:91], v1, s[4:5] nt
	global_load_dwordx2 v[146:147], v2, s[6:7] nt
	s_add_u32 s2, s2, 0x200000
	s_addc_u32 s3, s3, 0
	s_add_u32 s4, s4, 0x200000
	s_addc_u32 s5, s5, 0
	s_add_u32 s6, s6, 0xc00000
	s_addc_u32 s7, s7, 0
	global_load_dwordx4 v[28:31], v1, s[2:3] nt
	global_load_dwordx4 v[92:95], v1, s[4:5] nt
	global_load_dwordx2 v[148:149], v2, s[6:7] nt
	s_add_u32 s2, s2, 0x200000
	s_addc_u32 s3, s3, 0
	s_add_u32 s4, s4, 0x200000
	s_addc_u32 s5, s5, 0
	s_add_u32 s6, s6, 0xc00000
	s_addc_u32 s7, s7, 0
	global_load_dwordx4 v[32:35], v1, s[2:3] nt
	global_load_dwordx4 v[96:99], v1, s[4:5] nt
	global_load_dwordx2 v[150:151], v2, s[6:7] nt
	s_add_u32 s2, s2, 0x200000
	s_addc_u32 s3, s3, 0
	s_add_u32 s4, s4, 0x200000
	s_addc_u32 s5, s5, 0
	s_add_u32 s6, s6, 0xc00000
	s_addc_u32 s7, s7, 0
	global_load_dwordx4 v[36:39], v1, s[2:3] nt
	global_load_dwordx4 v[100:103], v1, s[4:5] nt
	global_load_dwordx2 v[152:153], v2, s[6:7] nt
	s_add_u32 s2, s2, 0x200000
	s_addc_u32 s3, s3, 0
	s_add_u32 s4, s4, 0x200000
	s_addc_u32 s5, s5, 0
	s_add_u32 s6, s6, 0xc00000
	s_addc_u32 s7, s7, 0
	global_load_dwordx4 v[40:43], v1, s[2:3] nt
	global_load_dwordx4 v[104:107], v1, s[4:5] nt
	global_load_dwordx2 v[156:157], v2, s[6:7] nt
	s_add_u32 s2, s2, 0x200000
	s_addc_u32 s3, s3, 0
	s_add_u32 s4, s4, 0x200000
	s_addc_u32 s5, s5, 0
	s_add_u32 s6, s6, 0xc00000
	s_addc_u32 s7, s7, 0
	global_load_dwordx4 v[44:47], v1, s[2:3] nt
	global_load_dwordx4 v[108:111], v1, s[4:5] nt
	global_load_dwordx2 v[158:159], v2, s[6:7] nt
	s_add_u32 s2, s2, 0x200000
	s_addc_u32 s3, s3, 0
	s_add_u32 s4, s4, 0x200000
	s_addc_u32 s5, s5, 0
	s_add_u32 s6, s6, 0xc00000
	s_addc_u32 s7, s7, 0
	global_load_dwordx4 v[48:51], v1, s[2:3] nt
	global_load_dwordx4 v[112:115], v1, s[4:5] nt
	global_load_dwordx2 v[160:161], v2, s[6:7] nt
	s_add_u32 s2, s2, 0x200000
	s_addc_u32 s3, s3, 0
	s_add_u32 s4, s4, 0x200000
	s_addc_u32 s5, s5, 0
	s_add_u32 s6, s6, 0xc00000
	s_addc_u32 s7, s7, 0
	global_load_dwordx4 v[52:55], v1, s[2:3] nt
	global_load_dwordx4 v[116:119], v1, s[4:5] nt
	global_load_dwordx2 v[162:163], v2, s[6:7] nt
	s_add_u32 s2, s2, 0x200000
	s_addc_u32 s3, s3, 0
	s_add_u32 s4, s4, 0x200000
	s_addc_u32 s5, s5, 0
	s_add_u32 s6, s6, 0xc00000
	s_addc_u32 s7, s7, 0
	global_load_dwordx4 v[56:59], v1, s[2:3] nt
	global_load_dwordx4 v[120:123], v1, s[4:5] nt
	global_load_dwordx2 v[164:165], v2, s[6:7] nt
	s_add_u32 s2, s2, 0x200000
	s_addc_u32 s3, s3, 0
	s_add_u32 s4, s4, 0x200000
	s_addc_u32 s5, s5, 0
	s_add_u32 s6, s6, 0xc00000
	s_addc_u32 s7, s7, 0
	global_load_dwordx4 v[60:63], v1, s[2:3] nt
	global_load_dwordx4 v[124:127], v1, s[4:5] nt
	global_load_dwordx2 v[166:167], v2, s[6:7] nt
	s_add_u32 s2, s2, 0x200000
	s_addc_u32 s3, s3, 0
	s_add_u32 s4, s4, 0x200000
	s_addc_u32 s5, s5, 0
	s_add_u32 s6, s6, 0xc00000
	s_addc_u32 s7, s7, 0
	global_load_dwordx4 v[64:67], v1, s[2:3] nt
	global_load_dwordx4 v[128:131], v1, s[4:5] nt
	global_load_dwordx2 v[168:169], v2, s[6:7] nt
	s_add_u32 s2, s2, 0x200000
	s_addc_u32 s3, s3, 0
	s_add_u32 s4, s4, 0x200000
	s_addc_u32 s5, s5, 0
	s_add_u32 s6, s6, 0xc00000
	s_addc_u32 s7, s7, 0
	global_load_dwordx4 v[68:71], v1, s[2:3] nt
	global_load_dwordx4 v[132:135], v1, s[4:5] nt
	global_load_dwordx2 v[170:171], v2, s[6:7] nt
	s_add_u32 s2, s2, 0x200000
	s_addc_u32 s3, s3, 0
	s_add_u32 s4, s4, 0x200000
	s_addc_u32 s5, s5, 0
	s_add_u32 s6, s6, 0xc00000
	s_addc_u32 s7, s7, 0
	global_load_dwordx4 v[72:75], v1, s[2:3] nt
	global_load_dwordx4 v[136:139], v1, s[4:5] nt
	global_load_dwordx2 v[172:173], v2, s[6:7] nt
	v_mov_b32_e32 v8, 0xbfb8aa3b
	v_mov_b32_e32 v9, 0xbfb8aa3b
	v_mov_b32_e32 v10, 1.0
	v_mov_b32_e32 v11, 1.0
	s_mov_b32 s20, 0x3c000000
	s_mov_b32 s21, 0x358637bd
	s_waitcnt vmcnt(45)
	v_pk_add_f32 v[12:13], v[12:13], v[76:77]
	v_pk_add_f32 v[14:15], v[14:15], v[78:79]
	v_mul_f32_e32 v180, v12, v12
	v_fmac_f32_e32 v180, v13, v13
	v_fmac_f32_e32 v180, v14, v14
	v_fmac_f32_e32 v180, v15, v15
	v_lshlrev_b32_e32 v184, 16, v140
	v_and_b32_e32 v185, 0xffff0000, v140
	v_add_f32_dpp v180, v180, v180 quad_perm:[1,0,3,2] row_mask:0xf bank_mask:0xf
	v_lshlrev_b32_e32 v186, 16, v141
	v_and_b32_e32 v187, 0xffff0000, v141
	v_add_f32_dpp v180, v180, v180 quad_perm:[2,3,0,1] row_mask:0xf bank_mask:0xf
	v_pk_mul_f32 v[188:189], v[184:185], v[8:9]
	v_pk_mul_f32 v[190:191], v[186:187], v[8:9]
	v_add_f32_dpp v180, v180, v180 row_ror:4 row_mask:0xf bank_mask:0xf
	v_exp_f32_e32 v188, v188
	v_exp_f32_e32 v189, v189
	v_add_f32_dpp v180, v180, v180 row_ror:8 row_mask:0xf bank_mask:0xf
	v_exp_f32_e32 v190, v190
	v_exp_f32_e32 v191, v191
	v_mov_b32_e32 v181, v180
	v_pk_add_f32 v[188:189], v[188:189], v[10:11]
	v_pk_add_f32 v[190:191], v[190:191], v[10:11]
	v_permlane16_swap_b32_e32 v180, v181
	v_rcp_f32_e32 v188, v188
	v_rcp_f32_e32 v189, v189
	v_add_f32_e32 v180, v180, v181
	v_rcp_f32_e32 v190, v190
	v_rcp_f32_e32 v191, v191
	v_mov_b32_e32 v182, s21
	v_fmac_f32_e32 v182, s20, v180
	v_rsq_f32_e32 v182, v182
	v_pk_mul_f32 v[188:189], v[188:189], v[184:185]
	v_pk_mul_f32 v[190:191], v[190:191], v[186:187]
	v_mov_b32_e32 v183, v182
	v_pk_mul_f32 v[188:189], v[188:189], v[4:5]
	v_pk_mul_f32 v[190:191], v[190:191], v[6:7]
	v_pk_mul_f32 v[12:13], v[12:13], v[182:183]
	v_pk_mul_f32 v[14:15], v[14:15], v[182:183]
	v_pk_mul_f32 v[12:13], v[12:13], v[188:189]
	v_pk_mul_f32 v[14:15], v[14:15], v[190:191]
	v_cvt_pk_bf16_f32 v200, v12, v13
	v_cvt_pk_bf16_f32 v201, v14, v15
	global_store_dwordx2 v2, v[200:201], s[8:9]
	s_add_u32 s8, s8, 0x100000
	s_addc_u32 s9, s9, 0
	s_waitcnt vmcnt(43)
	v_pk_add_f32 v[16:17], v[16:17], v[80:81]
	v_pk_add_f32 v[18:19], v[18:19], v[82:83]
	v_mul_f32_e32 v180, v16, v16
	v_fmac_f32_e32 v180, v17, v17
	v_fmac_f32_e32 v180, v18, v18
	v_fmac_f32_e32 v180, v19, v19
	v_lshlrev_b32_e32 v184, 16, v142
	v_and_b32_e32 v185, 0xffff0000, v142
	v_add_f32_dpp v180, v180, v180 quad_perm:[1,0,3,2] row_mask:0xf bank_mask:0xf
	v_lshlrev_b32_e32 v186, 16, v143
	v_and_b32_e32 v187, 0xffff0000, v143
	v_add_f32_dpp v180, v180, v180 quad_perm:[2,3,0,1] row_mask:0xf bank_mask:0xf
	v_pk_mul_f32 v[188:189], v[184:185], v[8:9]
	v_pk_mul_f32 v[190:191], v[186:187], v[8:9]
	v_add_f32_dpp v180, v180, v180 row_ror:4 row_mask:0xf bank_mask:0xf
	v_exp_f32_e32 v188, v188
	v_exp_f32_e32 v189, v189
	v_add_f32_dpp v180, v180, v180 row_ror:8 row_mask:0xf bank_mask:0xf
	v_exp_f32_e32 v190, v190
	v_exp_f32_e32 v191, v191
	v_mov_b32_e32 v181, v180
	v_pk_add_f32 v[188:189], v[188:189], v[10:11]
	v_pk_add_f32 v[190:191], v[190:191], v[10:11]
	v_permlane16_swap_b32_e32 v180, v181
	v_rcp_f32_e32 v188, v188
	v_rcp_f32_e32 v189, v189
	v_add_f32_e32 v180, v180, v181
	v_rcp_f32_e32 v190, v190
	v_rcp_f32_e32 v191, v191
	v_mov_b32_e32 v182, s21
	v_fmac_f32_e32 v182, s20, v180
	v_rsq_f32_e32 v182, v182
	v_pk_mul_f32 v[188:189], v[188:189], v[184:185]
	v_pk_mul_f32 v[190:191], v[190:191], v[186:187]
	v_mov_b32_e32 v183, v182
	v_pk_mul_f32 v[188:189], v[188:189], v[4:5]
	v_pk_mul_f32 v[190:191], v[190:191], v[6:7]
	v_pk_mul_f32 v[16:17], v[16:17], v[182:183]
	v_pk_mul_f32 v[18:19], v[18:19], v[182:183]
	v_pk_mul_f32 v[16:17], v[16:17], v[188:189]
	v_pk_mul_f32 v[18:19], v[18:19], v[190:191]
	v_cvt_pk_bf16_f32 v202, v16, v17
	v_cvt_pk_bf16_f32 v203, v18, v19
	global_store_dwordx2 v2, v[202:203], s[8:9]
	s_add_u32 s8, s8, 0x100000
	s_addc_u32 s9, s9, 0
	s_waitcnt vmcnt(41)
	v_pk_add_f32 v[20:21], v[20:21], v[84:85]
	v_pk_add_f32 v[22:23], v[22:23], v[86:87]
	v_mul_f32_e32 v180, v20, v20
	v_fmac_f32_e32 v180, v21, v21
	v_fmac_f32_e32 v180, v22, v22
	v_fmac_f32_e32 v180, v23, v23
	v_lshlrev_b32_e32 v184, 16, v144
	v_and_b32_e32 v185, 0xffff0000, v144
	v_add_f32_dpp v180, v180, v180 quad_perm:[1,0,3,2] row_mask:0xf bank_mask:0xf
	v_lshlrev_b32_e32 v186, 16, v145
	v_and_b32_e32 v187, 0xffff0000, v145
	v_add_f32_dpp v180, v180, v180 quad_perm:[2,3,0,1] row_mask:0xf bank_mask:0xf
	v_pk_mul_f32 v[188:189], v[184:185], v[8:9]
	v_pk_mul_f32 v[190:191], v[186:187], v[8:9]
	v_add_f32_dpp v180, v180, v180 row_ror:4 row_mask:0xf bank_mask:0xf
	v_exp_f32_e32 v188, v188
	v_exp_f32_e32 v189, v189
	v_add_f32_dpp v180, v180, v180 row_ror:8 row_mask:0xf bank_mask:0xf
	v_exp_f32_e32 v190, v190
	v_exp_f32_e32 v191, v191
	v_mov_b32_e32 v181, v180
	v_pk_add_f32 v[188:189], v[188:189], v[10:11]
	v_pk_add_f32 v[190:191], v[190:191], v[10:11]
	v_permlane16_swap_b32_e32 v180, v181
	v_rcp_f32_e32 v188, v188
	v_rcp_f32_e32 v189, v189
	v_add_f32_e32 v180, v180, v181
	v_rcp_f32_e32 v190, v190
	v_rcp_f32_e32 v191, v191
	v_mov_b32_e32 v182, s21
	v_fmac_f32_e32 v182, s20, v180
	v_rsq_f32_e32 v182, v182
	v_pk_mul_f32 v[188:189], v[188:189], v[184:185]
	v_pk_mul_f32 v[190:191], v[190:191], v[186:187]
	v_mov_b32_e32 v183, v182
	v_pk_mul_f32 v[188:189], v[188:189], v[4:5]
	v_pk_mul_f32 v[190:191], v[190:191], v[6:7]
	v_pk_mul_f32 v[20:21], v[20:21], v[182:183]
	v_pk_mul_f32 v[22:23], v[22:23], v[182:183]
	v_pk_mul_f32 v[20:21], v[20:21], v[188:189]
	v_pk_mul_f32 v[22:23], v[22:23], v[190:191]
	v_cvt_pk_bf16_f32 v204, v20, v21
	v_cvt_pk_bf16_f32 v205, v22, v23
	global_store_dwordx2 v2, v[204:205], s[8:9]
	s_add_u32 s8, s8, 0x100000
	s_addc_u32 s9, s9, 0
	s_waitcnt vmcnt(39)
	v_pk_add_f32 v[24:25], v[24:25], v[88:89]
	v_pk_add_f32 v[26:27], v[26:27], v[90:91]
	v_mul_f32_e32 v180, v24, v24
	v_fmac_f32_e32 v180, v25, v25
	v_fmac_f32_e32 v180, v26, v26
	v_fmac_f32_e32 v180, v27, v27
	v_lshlrev_b32_e32 v184, 16, v146
	v_and_b32_e32 v185, 0xffff0000, v146
	v_add_f32_dpp v180, v180, v180 quad_perm:[1,0,3,2] row_mask:0xf bank_mask:0xf
	v_lshlrev_b32_e32 v186, 16, v147
	v_and_b32_e32 v187, 0xffff0000, v147
	v_add_f32_dpp v180, v180, v180 quad_perm:[2,3,0,1] row_mask:0xf bank_mask:0xf
	v_pk_mul_f32 v[188:189], v[184:185], v[8:9]
	v_pk_mul_f32 v[190:191], v[186:187], v[8:9]
	v_add_f32_dpp v180, v180, v180 row_ror:4 row_mask:0xf bank_mask:0xf
	v_exp_f32_e32 v188, v188
	v_exp_f32_e32 v189, v189
	v_add_f32_dpp v180, v180, v180 row_ror:8 row_mask:0xf bank_mask:0xf
	v_exp_f32_e32 v190, v190
	v_exp_f32_e32 v191, v191
	v_mov_b32_e32 v181, v180
	v_pk_add_f32 v[188:189], v[188:189], v[10:11]
	v_pk_add_f32 v[190:191], v[190:191], v[10:11]
	v_permlane16_swap_b32_e32 v180, v181
	v_rcp_f32_e32 v188, v188
	v_rcp_f32_e32 v189, v189
	v_add_f32_e32 v180, v180, v181
	v_rcp_f32_e32 v190, v190
	v_rcp_f32_e32 v191, v191
	v_mov_b32_e32 v182, s21
	v_fmac_f32_e32 v182, s20, v180
	v_rsq_f32_e32 v182, v182
	v_pk_mul_f32 v[188:189], v[188:189], v[184:185]
	v_pk_mul_f32 v[190:191], v[190:191], v[186:187]
	v_mov_b32_e32 v183, v182
	v_pk_mul_f32 v[188:189], v[188:189], v[4:5]
	v_pk_mul_f32 v[190:191], v[190:191], v[6:7]
	v_pk_mul_f32 v[24:25], v[24:25], v[182:183]
	v_pk_mul_f32 v[26:27], v[26:27], v[182:183]
	v_pk_mul_f32 v[24:25], v[24:25], v[188:189]
	v_pk_mul_f32 v[26:27], v[26:27], v[190:191]
	v_cvt_pk_bf16_f32 v206, v24, v25
	v_cvt_pk_bf16_f32 v207, v26, v27
	global_store_dwordx2 v2, v[206:207], s[8:9]
	s_add_u32 s8, s8, 0x100000
	s_addc_u32 s9, s9, 0
	s_waitcnt vmcnt(37)
	v_pk_add_f32 v[28:29], v[28:29], v[92:93]
	v_pk_add_f32 v[30:31], v[30:31], v[94:95]
	v_mul_f32_e32 v180, v28, v28
	v_fmac_f32_e32 v180, v29, v29
	v_fmac_f32_e32 v180, v30, v30
	v_fmac_f32_e32 v180, v31, v31
	v_lshlrev_b32_e32 v184, 16, v148
	v_and_b32_e32 v185, 0xffff0000, v148
	v_add_f32_dpp v180, v180, v180 quad_perm:[1,0,3,2] row_mask:0xf bank_mask:0xf
	v_lshlrev_b32_e32 v186, 16, v149
	v_and_b32_e32 v187, 0xffff0000, v149
	v_add_f32_dpp v180, v180, v180 quad_perm:[2,3,0,1] row_mask:0xf bank_mask:0xf
	v_pk_mul_f32 v[188:189], v[184:185], v[8:9]
	v_pk_mul_f32 v[190:191], v[186:187], v[8:9]
	v_add_f32_dpp v180, v180, v180 row_ror:4 row_mask:0xf bank_mask:0xf
	v_exp_f32_e32 v188, v188
	v_exp_f32_e32 v189, v189
	v_add_f32_dpp v180, v180, v180 row_ror:8 row_mask:0xf bank_mask:0xf
	v_exp_f32_e32 v190, v190
	v_exp_f32_e32 v191, v191
	v_mov_b32_e32 v181, v180
	v_pk_add_f32 v[188:189], v[188:189], v[10:11]
	v_pk_add_f32 v[190:191], v[190:191], v[10:11]
	v_permlane16_swap_b32_e32 v180, v181
	v_rcp_f32_e32 v188, v188
	v_rcp_f32_e32 v189, v189
	v_add_f32_e32 v180, v180, v181
	v_rcp_f32_e32 v190, v190
	v_rcp_f32_e32 v191, v191
	v_mov_b32_e32 v182, s21
	v_fmac_f32_e32 v182, s20, v180
	v_rsq_f32_e32 v182, v182
	v_pk_mul_f32 v[188:189], v[188:189], v[184:185]
	v_pk_mul_f32 v[190:191], v[190:191], v[186:187]
	v_mov_b32_e32 v183, v182
	v_pk_mul_f32 v[188:189], v[188:189], v[4:5]
	v_pk_mul_f32 v[190:191], v[190:191], v[6:7]
	v_pk_mul_f32 v[28:29], v[28:29], v[182:183]
	v_pk_mul_f32 v[30:31], v[30:31], v[182:183]
	v_pk_mul_f32 v[28:29], v[28:29], v[188:189]
	v_pk_mul_f32 v[30:31], v[30:31], v[190:191]
	v_cvt_pk_bf16_f32 v200, v28, v29
	v_cvt_pk_bf16_f32 v201, v30, v31
	global_store_dwordx2 v2, v[200:201], s[8:9]
	s_add_u32 s8, s8, 0x100000
	s_addc_u32 s9, s9, 0
	s_waitcnt vmcnt(35)
	v_pk_add_f32 v[32:33], v[32:33], v[96:97]
	v_pk_add_f32 v[34:35], v[34:35], v[98:99]
	v_mul_f32_e32 v180, v32, v32
	v_fmac_f32_e32 v180, v33, v33
	v_fmac_f32_e32 v180, v34, v34
	v_fmac_f32_e32 v180, v35, v35
	v_lshlrev_b32_e32 v184, 16, v150
	v_and_b32_e32 v185, 0xffff0000, v150
	v_add_f32_dpp v180, v180, v180 quad_perm:[1,0,3,2] row_mask:0xf bank_mask:0xf
	v_lshlrev_b32_e32 v186, 16, v151
	v_and_b32_e32 v187, 0xffff0000, v151
	v_add_f32_dpp v180, v180, v180 quad_perm:[2,3,0,1] row_mask:0xf bank_mask:0xf
	v_pk_mul_f32 v[188:189], v[184:185], v[8:9]
	v_pk_mul_f32 v[190:191], v[186:187], v[8:9]
	v_add_f32_dpp v180, v180, v180 row_ror:4 row_mask:0xf bank_mask:0xf
	v_exp_f32_e32 v188, v188
	v_exp_f32_e32 v189, v189
	v_add_f32_dpp v180, v180, v180 row_ror:8 row_mask:0xf bank_mask:0xf
	v_exp_f32_e32 v190, v190
	v_exp_f32_e32 v191, v191
	v_mov_b32_e32 v181, v180
	v_pk_add_f32 v[188:189], v[188:189], v[10:11]
	v_pk_add_f32 v[190:191], v[190:191], v[10:11]
	v_permlane16_swap_b32_e32 v180, v181
	v_rcp_f32_e32 v188, v188
	v_rcp_f32_e32 v189, v189
	v_add_f32_e32 v180, v180, v181
	v_rcp_f32_e32 v190, v190
	v_rcp_f32_e32 v191, v191
	v_mov_b32_e32 v182, s21
	v_fmac_f32_e32 v182, s20, v180
	v_rsq_f32_e32 v182, v182
	v_pk_mul_f32 v[188:189], v[188:189], v[184:185]
	v_pk_mul_f32 v[190:191], v[190:191], v[186:187]
	v_mov_b32_e32 v183, v182
	v_pk_mul_f32 v[188:189], v[188:189], v[4:5]
	v_pk_mul_f32 v[190:191], v[190:191], v[6:7]
	v_pk_mul_f32 v[32:33], v[32:33], v[182:183]
	v_pk_mul_f32 v[34:35], v[34:35], v[182:183]
	v_pk_mul_f32 v[32:33], v[32:33], v[188:189]
	v_pk_mul_f32 v[34:35], v[34:35], v[190:191]
	v_cvt_pk_bf16_f32 v202, v32, v33
	v_cvt_pk_bf16_f32 v203, v34, v35
	global_store_dwordx2 v2, v[202:203], s[8:9]
	s_add_u32 s8, s8, 0x100000
	s_addc_u32 s9, s9, 0
	s_waitcnt vmcnt(33)
	v_pk_add_f32 v[36:37], v[36:37], v[100:101]
	v_pk_add_f32 v[38:39], v[38:39], v[102:103]
	v_mul_f32_e32 v180, v36, v36
	v_fmac_f32_e32 v180, v37, v37
	v_fmac_f32_e32 v180, v38, v38
	v_fmac_f32_e32 v180, v39, v39
	v_lshlrev_b32_e32 v184, 16, v152
	v_and_b32_e32 v185, 0xffff0000, v152
	v_add_f32_dpp v180, v180, v180 quad_perm:[1,0,3,2] row_mask:0xf bank_mask:0xf
	v_lshlrev_b32_e32 v186, 16, v153
	v_and_b32_e32 v187, 0xffff0000, v153
	v_add_f32_dpp v180, v180, v180 quad_perm:[2,3,0,1] row_mask:0xf bank_mask:0xf
	v_pk_mul_f32 v[188:189], v[184:185], v[8:9]
	v_pk_mul_f32 v[190:191], v[186:187], v[8:9]
	v_add_f32_dpp v180, v180, v180 row_ror:4 row_mask:0xf bank_mask:0xf
	v_exp_f32_e32 v188, v188
	v_exp_f32_e32 v189, v189
	v_add_f32_dpp v180, v180, v180 row_ror:8 row_mask:0xf bank_mask:0xf
	v_exp_f32_e32 v190, v190
	v_exp_f32_e32 v191, v191
	v_mov_b32_e32 v181, v180
	v_pk_add_f32 v[188:189], v[188:189], v[10:11]
	v_pk_add_f32 v[190:191], v[190:191], v[10:11]
	v_permlane16_swap_b32_e32 v180, v181
	v_rcp_f32_e32 v188, v188
	v_rcp_f32_e32 v189, v189
	v_add_f32_e32 v180, v180, v181
	v_rcp_f32_e32 v190, v190
	v_rcp_f32_e32 v191, v191
	v_mov_b32_e32 v182, s21
	v_fmac_f32_e32 v182, s20, v180
	v_rsq_f32_e32 v182, v182
	v_pk_mul_f32 v[188:189], v[188:189], v[184:185]
	v_pk_mul_f32 v[190:191], v[190:191], v[186:187]
	v_mov_b32_e32 v183, v182
	v_pk_mul_f32 v[188:189], v[188:189], v[4:5]
	v_pk_mul_f32 v[190:191], v[190:191], v[6:7]
	v_pk_mul_f32 v[36:37], v[36:37], v[182:183]
	v_pk_mul_f32 v[38:39], v[38:39], v[182:183]
	v_pk_mul_f32 v[36:37], v[36:37], v[188:189]
	v_pk_mul_f32 v[38:39], v[38:39], v[190:191]
	v_cvt_pk_bf16_f32 v204, v36, v37
	v_cvt_pk_bf16_f32 v205, v38, v39
	global_store_dwordx2 v2, v[204:205], s[8:9]
	s_add_u32 s8, s8, 0x100000
	s_addc_u32 s9, s9, 0
	s_waitcnt vmcnt(31)
	v_pk_add_f32 v[40:41], v[40:41], v[104:105]
	v_pk_add_f32 v[42:43], v[42:43], v[106:107]
	v_mul_f32_e32 v180, v40, v40
	v_fmac_f32_e32 v180, v41, v41
	v_fmac_f32_e32 v180, v42, v42
	v_fmac_f32_e32 v180, v43, v43
	v_lshlrev_b32_e32 v184, 16, v156
	v_and_b32_e32 v185, 0xffff0000, v156
	v_add_f32_dpp v180, v180, v180 quad_perm:[1,0,3,2] row_mask:0xf bank_mask:0xf
	v_lshlrev_b32_e32 v186, 16, v157
	v_and_b32_e32 v187, 0xffff0000, v157
	v_add_f32_dpp v180, v180, v180 quad_perm:[2,3,0,1] row_mask:0xf bank_mask:0xf
	v_pk_mul_f32 v[188:189], v[184:185], v[8:9]
	v_pk_mul_f32 v[190:191], v[186:187], v[8:9]
	v_add_f32_dpp v180, v180, v180 row_ror:4 row_mask:0xf bank_mask:0xf
	v_exp_f32_e32 v188, v188
	v_exp_f32_e32 v189, v189
	v_add_f32_dpp v180, v180, v180 row_ror:8 row_mask:0xf bank_mask:0xf
	v_exp_f32_e32 v190, v190
	v_exp_f32_e32 v191, v191
	v_mov_b32_e32 v181, v180
	v_pk_add_f32 v[188:189], v[188:189], v[10:11]
	v_pk_add_f32 v[190:191], v[190:191], v[10:11]
	v_permlane16_swap_b32_e32 v180, v181
	v_rcp_f32_e32 v188, v188
	v_rcp_f32_e32 v189, v189
	v_add_f32_e32 v180, v180, v181
	v_rcp_f32_e32 v190, v190
	v_rcp_f32_e32 v191, v191
	v_mov_b32_e32 v182, s21
	v_fmac_f32_e32 v182, s20, v180
	v_rsq_f32_e32 v182, v182
	v_pk_mul_f32 v[188:189], v[188:189], v[184:185]
	v_pk_mul_f32 v[190:191], v[190:191], v[186:187]
	v_mov_b32_e32 v183, v182
	v_pk_mul_f32 v[188:189], v[188:189], v[4:5]
	v_pk_mul_f32 v[190:191], v[190:191], v[6:7]
	v_pk_mul_f32 v[40:41], v[40:41], v[182:183]
	v_pk_mul_f32 v[42:43], v[42:43], v[182:183]
	v_pk_mul_f32 v[40:41], v[40:41], v[188:189]
	v_pk_mul_f32 v[42:43], v[42:43], v[190:191]
	v_cvt_pk_bf16_f32 v206, v40, v41
	v_cvt_pk_bf16_f32 v207, v42, v43
	global_store_dwordx2 v2, v[206:207], s[8:9]
	s_add_u32 s8, s8, 0x100000
	s_addc_u32 s9, s9, 0
	s_waitcnt vmcnt(29)
	v_pk_add_f32 v[44:45], v[44:45], v[108:109]
	v_pk_add_f32 v[46:47], v[46:47], v[110:111]
	v_mul_f32_e32 v180, v44, v44
	v_fmac_f32_e32 v180, v45, v45
	v_fmac_f32_e32 v180, v46, v46
	v_fmac_f32_e32 v180, v47, v47
	v_lshlrev_b32_e32 v184, 16, v158
	v_and_b32_e32 v185, 0xffff0000, v158
	v_add_f32_dpp v180, v180, v180 quad_perm:[1,0,3,2] row_mask:0xf bank_mask:0xf
	v_lshlrev_b32_e32 v186, 16, v159
	v_and_b32_e32 v187, 0xffff0000, v159
	v_add_f32_dpp v180, v180, v180 quad_perm:[2,3,0,1] row_mask:0xf bank_mask:0xf
	v_pk_mul_f32 v[188:189], v[184:185], v[8:9]
	v_pk_mul_f32 v[190:191], v[186:187], v[8:9]
	v_add_f32_dpp v180, v180, v180 row_ror:4 row_mask:0xf bank_mask:0xf
	v_exp_f32_e32 v188, v188
	v_exp_f32_e32 v189, v189
	v_add_f32_dpp v180, v180, v180 row_ror:8 row_mask:0xf bank_mask:0xf
	v_exp_f32_e32 v190, v190
	v_exp_f32_e32 v191, v191
	v_mov_b32_e32 v181, v180
	v_pk_add_f32 v[188:189], v[188:189], v[10:11]
	v_pk_add_f32 v[190:191], v[190:191], v[10:11]
	v_permlane16_swap_b32_e32 v180, v181
	v_rcp_f32_e32 v188, v188
	v_rcp_f32_e32 v189, v189
	v_add_f32_e32 v180, v180, v181
	v_rcp_f32_e32 v190, v190
	v_rcp_f32_e32 v191, v191
	v_mov_b32_e32 v182, s21
	v_fmac_f32_e32 v182, s20, v180
	v_rsq_f32_e32 v182, v182
	v_pk_mul_f32 v[188:189], v[188:189], v[184:185]
	v_pk_mul_f32 v[190:191], v[190:191], v[186:187]
	v_mov_b32_e32 v183, v182
	v_pk_mul_f32 v[188:189], v[188:189], v[4:5]
	v_pk_mul_f32 v[190:191], v[190:191], v[6:7]
	v_pk_mul_f32 v[44:45], v[44:45], v[182:183]
	v_pk_mul_f32 v[46:47], v[46:47], v[182:183]
	v_pk_mul_f32 v[44:45], v[44:45], v[188:189]
	v_pk_mul_f32 v[46:47], v[46:47], v[190:191]
	v_cvt_pk_bf16_f32 v200, v44, v45
	v_cvt_pk_bf16_f32 v201, v46, v47
	global_store_dwordx2 v2, v[200:201], s[8:9]
	s_add_u32 s8, s8, 0x100000
	s_addc_u32 s9, s9, 0
	s_waitcnt vmcnt(27)
	v_pk_add_f32 v[48:49], v[48:49], v[112:113]
	v_pk_add_f32 v[50:51], v[50:51], v[114:115]
	v_mul_f32_e32 v180, v48, v48
	v_fmac_f32_e32 v180, v49, v49
	v_fmac_f32_e32 v180, v50, v50
	v_fmac_f32_e32 v180, v51, v51
	v_lshlrev_b32_e32 v184, 16, v160
	v_and_b32_e32 v185, 0xffff0000, v160
	v_add_f32_dpp v180, v180, v180 quad_perm:[1,0,3,2] row_mask:0xf bank_mask:0xf
	v_lshlrev_b32_e32 v186, 16, v161
	v_and_b32_e32 v187, 0xffff0000, v161
	v_add_f32_dpp v180, v180, v180 quad_perm:[2,3,0,1] row_mask:0xf bank_mask:0xf
	v_pk_mul_f32 v[188:189], v[184:185], v[8:9]
	v_pk_mul_f32 v[190:191], v[186:187], v[8:9]
	v_add_f32_dpp v180, v180, v180 row_ror:4 row_mask:0xf bank_mask:0xf
	v_exp_f32_e32 v188, v188
	v_exp_f32_e32 v189, v189
	v_add_f32_dpp v180, v180, v180 row_ror:8 row_mask:0xf bank_mask:0xf
	v_exp_f32_e32 v190, v190
	v_exp_f32_e32 v191, v191
	v_mov_b32_e32 v181, v180
	v_pk_add_f32 v[188:189], v[188:189], v[10:11]
	v_pk_add_f32 v[190:191], v[190:191], v[10:11]
	v_permlane16_swap_b32_e32 v180, v181
	v_rcp_f32_e32 v188, v188
	v_rcp_f32_e32 v189, v189
	v_add_f32_e32 v180, v180, v181
	v_rcp_f32_e32 v190, v190
	v_rcp_f32_e32 v191, v191
	v_mov_b32_e32 v182, s21
	v_fmac_f32_e32 v182, s20, v180
	v_rsq_f32_e32 v182, v182
	v_pk_mul_f32 v[188:189], v[188:189], v[184:185]
	v_pk_mul_f32 v[190:191], v[190:191], v[186:187]
	v_mov_b32_e32 v183, v182
	v_pk_mul_f32 v[188:189], v[188:189], v[4:5]
	v_pk_mul_f32 v[190:191], v[190:191], v[6:7]
	v_pk_mul_f32 v[48:49], v[48:49], v[182:183]
	v_pk_mul_f32 v[50:51], v[50:51], v[182:183]
	v_pk_mul_f32 v[48:49], v[48:49], v[188:189]
	v_pk_mul_f32 v[50:51], v[50:51], v[190:191]
	v_cvt_pk_bf16_f32 v202, v48, v49
	v_cvt_pk_bf16_f32 v203, v50, v51
	global_store_dwordx2 v2, v[202:203], s[8:9]
	s_add_u32 s8, s8, 0x100000
	s_addc_u32 s9, s9, 0
	s_waitcnt vmcnt(25)
	v_pk_add_f32 v[52:53], v[52:53], v[116:117]
	v_pk_add_f32 v[54:55], v[54:55], v[118:119]
	v_mul_f32_e32 v180, v52, v52
	v_fmac_f32_e32 v180, v53, v53
	v_fmac_f32_e32 v180, v54, v54
	v_fmac_f32_e32 v180, v55, v55
	v_lshlrev_b32_e32 v184, 16, v162
	v_and_b32_e32 v185, 0xffff0000, v162
	v_add_f32_dpp v180, v180, v180 quad_perm:[1,0,3,2] row_mask:0xf bank_mask:0xf
	v_lshlrev_b32_e32 v186, 16, v163
	v_and_b32_e32 v187, 0xffff0000, v163
	v_add_f32_dpp v180, v180, v180 quad_perm:[2,3,0,1] row_mask:0xf bank_mask:0xf
	v_pk_mul_f32 v[188:189], v[184:185], v[8:9]
	v_pk_mul_f32 v[190:191], v[186:187], v[8:9]
	v_add_f32_dpp v180, v180, v180 row_ror:4 row_mask:0xf bank_mask:0xf
	v_exp_f32_e32 v188, v188
	v_exp_f32_e32 v189, v189
	v_add_f32_dpp v180, v180, v180 row_ror:8 row_mask:0xf bank_mask:0xf
	v_exp_f32_e32 v190, v190
	v_exp_f32_e32 v191, v191
	v_mov_b32_e32 v181, v180
	v_pk_add_f32 v[188:189], v[188:189], v[10:11]
	v_pk_add_f32 v[190:191], v[190:191], v[10:11]
	v_permlane16_swap_b32_e32 v180, v181
	v_rcp_f32_e32 v188, v188
	v_rcp_f32_e32 v189, v189
	v_add_f32_e32 v180, v180, v181
	v_rcp_f32_e32 v190, v190
	v_rcp_f32_e32 v191, v191
	v_mov_b32_e32 v182, s21
	v_fmac_f32_e32 v182, s20, v180
	v_rsq_f32_e32 v182, v182
	v_pk_mul_f32 v[188:189], v[188:189], v[184:185]
	v_pk_mul_f32 v[190:191], v[190:191], v[186:187]
	v_mov_b32_e32 v183, v182
	v_pk_mul_f32 v[188:189], v[188:189], v[4:5]
	v_pk_mul_f32 v[190:191], v[190:191], v[6:7]
	v_pk_mul_f32 v[52:53], v[52:53], v[182:183]
	v_pk_mul_f32 v[54:55], v[54:55], v[182:183]
	v_pk_mul_f32 v[52:53], v[52:53], v[188:189]
	v_pk_mul_f32 v[54:55], v[54:55], v[190:191]
	v_cvt_pk_bf16_f32 v204, v52, v53
	v_cvt_pk_bf16_f32 v205, v54, v55
	global_store_dwordx2 v2, v[204:205], s[8:9]
	s_add_u32 s8, s8, 0x100000
	s_addc_u32 s9, s9, 0
	s_waitcnt vmcnt(23)
	v_pk_add_f32 v[56:57], v[56:57], v[120:121]
	v_pk_add_f32 v[58:59], v[58:59], v[122:123]
	v_mul_f32_e32 v180, v56, v56
	v_fmac_f32_e32 v180, v57, v57
	v_fmac_f32_e32 v180, v58, v58
	v_fmac_f32_e32 v180, v59, v59
	v_lshlrev_b32_e32 v184, 16, v164
	v_and_b32_e32 v185, 0xffff0000, v164
	v_add_f32_dpp v180, v180, v180 quad_perm:[1,0,3,2] row_mask:0xf bank_mask:0xf
	v_lshlrev_b32_e32 v186, 16, v165
	v_and_b32_e32 v187, 0xffff0000, v165
	v_add_f32_dpp v180, v180, v180 quad_perm:[2,3,0,1] row_mask:0xf bank_mask:0xf
	v_pk_mul_f32 v[188:189], v[184:185], v[8:9]
	v_pk_mul_f32 v[190:191], v[186:187], v[8:9]
	v_add_f32_dpp v180, v180, v180 row_ror:4 row_mask:0xf bank_mask:0xf
	v_exp_f32_e32 v188, v188
	v_exp_f32_e32 v189, v189
	v_add_f32_dpp v180, v180, v180 row_ror:8 row_mask:0xf bank_mask:0xf
	v_exp_f32_e32 v190, v190
	v_exp_f32_e32 v191, v191
	v_mov_b32_e32 v181, v180
	v_pk_add_f32 v[188:189], v[188:189], v[10:11]
	v_pk_add_f32 v[190:191], v[190:191], v[10:11]
	v_permlane16_swap_b32_e32 v180, v181
	v_rcp_f32_e32 v188, v188
	v_rcp_f32_e32 v189, v189
	v_add_f32_e32 v180, v180, v181
	v_rcp_f32_e32 v190, v190
	v_rcp_f32_e32 v191, v191
	v_mov_b32_e32 v182, s21
	v_fmac_f32_e32 v182, s20, v180
	v_rsq_f32_e32 v182, v182
	v_pk_mul_f32 v[188:189], v[188:189], v[184:185]
	v_pk_mul_f32 v[190:191], v[190:191], v[186:187]
	v_mov_b32_e32 v183, v182
	v_pk_mul_f32 v[188:189], v[188:189], v[4:5]
	v_pk_mul_f32 v[190:191], v[190:191], v[6:7]
	v_pk_mul_f32 v[56:57], v[56:57], v[182:183]
	v_pk_mul_f32 v[58:59], v[58:59], v[182:183]
	v_pk_mul_f32 v[56:57], v[56:57], v[188:189]
	v_pk_mul_f32 v[58:59], v[58:59], v[190:191]
	v_cvt_pk_bf16_f32 v206, v56, v57
	v_cvt_pk_bf16_f32 v207, v58, v59
	global_store_dwordx2 v2, v[206:207], s[8:9]
	s_add_u32 s8, s8, 0x100000
	s_addc_u32 s9, s9, 0
	s_waitcnt vmcnt(21)
	v_pk_add_f32 v[60:61], v[60:61], v[124:125]
	v_pk_add_f32 v[62:63], v[62:63], v[126:127]
	v_mul_f32_e32 v180, v60, v60
	v_fmac_f32_e32 v180, v61, v61
	v_fmac_f32_e32 v180, v62, v62
	v_fmac_f32_e32 v180, v63, v63
	v_lshlrev_b32_e32 v184, 16, v166
	v_and_b32_e32 v185, 0xffff0000, v166
	v_add_f32_dpp v180, v180, v180 quad_perm:[1,0,3,2] row_mask:0xf bank_mask:0xf
	v_lshlrev_b32_e32 v186, 16, v167
	v_and_b32_e32 v187, 0xffff0000, v167
	v_add_f32_dpp v180, v180, v180 quad_perm:[2,3,0,1] row_mask:0xf bank_mask:0xf
	v_pk_mul_f32 v[188:189], v[184:185], v[8:9]
	v_pk_mul_f32 v[190:191], v[186:187], v[8:9]
	v_add_f32_dpp v180, v180, v180 row_ror:4 row_mask:0xf bank_mask:0xf
	v_exp_f32_e32 v188, v188
	v_exp_f32_e32 v189, v189
	v_add_f32_dpp v180, v180, v180 row_ror:8 row_mask:0xf bank_mask:0xf
	v_exp_f32_e32 v190, v190
	v_exp_f32_e32 v191, v191
	v_mov_b32_e32 v181, v180
	v_pk_add_f32 v[188:189], v[188:189], v[10:11]
	v_pk_add_f32 v[190:191], v[190:191], v[10:11]
	v_permlane16_swap_b32_e32 v180, v181
	v_rcp_f32_e32 v188, v188
	v_rcp_f32_e32 v189, v189
	v_add_f32_e32 v180, v180, v181
	v_rcp_f32_e32 v190, v190
	v_rcp_f32_e32 v191, v191
	v_mov_b32_e32 v182, s21
	v_fmac_f32_e32 v182, s20, v180
	v_rsq_f32_e32 v182, v182
	v_pk_mul_f32 v[188:189], v[188:189], v[184:185]
	v_pk_mul_f32 v[190:191], v[190:191], v[186:187]
	v_mov_b32_e32 v183, v182
	v_pk_mul_f32 v[188:189], v[188:189], v[4:5]
	v_pk_mul_f32 v[190:191], v[190:191], v[6:7]
	v_pk_mul_f32 v[60:61], v[60:61], v[182:183]
	v_pk_mul_f32 v[62:63], v[62:63], v[182:183]
	v_pk_mul_f32 v[60:61], v[60:61], v[188:189]
	v_pk_mul_f32 v[62:63], v[62:63], v[190:191]
	v_cvt_pk_bf16_f32 v200, v60, v61
	v_cvt_pk_bf16_f32 v201, v62, v63
	global_store_dwordx2 v2, v[200:201], s[8:9]
	s_add_u32 s8, s8, 0x100000
	s_addc_u32 s9, s9, 0
	s_waitcnt vmcnt(19)
	v_pk_add_f32 v[64:65], v[64:65], v[128:129]
	v_pk_add_f32 v[66:67], v[66:67], v[130:131]
	v_mul_f32_e32 v180, v64, v64
	v_fmac_f32_e32 v180, v65, v65
	v_fmac_f32_e32 v180, v66, v66
	v_fmac_f32_e32 v180, v67, v67
	v_lshlrev_b32_e32 v184, 16, v168
	v_and_b32_e32 v185, 0xffff0000, v168
	v_add_f32_dpp v180, v180, v180 quad_perm:[1,0,3,2] row_mask:0xf bank_mask:0xf
	v_lshlrev_b32_e32 v186, 16, v169
	v_and_b32_e32 v187, 0xffff0000, v169
	v_add_f32_dpp v180, v180, v180 quad_perm:[2,3,0,1] row_mask:0xf bank_mask:0xf
	v_pk_mul_f32 v[188:189], v[184:185], v[8:9]
	v_pk_mul_f32 v[190:191], v[186:187], v[8:9]
	v_add_f32_dpp v180, v180, v180 row_ror:4 row_mask:0xf bank_mask:0xf
	v_exp_f32_e32 v188, v188
	v_exp_f32_e32 v189, v189
	v_add_f32_dpp v180, v180, v180 row_ror:8 row_mask:0xf bank_mask:0xf
	v_exp_f32_e32 v190, v190
	v_exp_f32_e32 v191, v191
	v_mov_b32_e32 v181, v180
	v_pk_add_f32 v[188:189], v[188:189], v[10:11]
	v_pk_add_f32 v[190:191], v[190:191], v[10:11]
	v_permlane16_swap_b32_e32 v180, v181
	v_rcp_f32_e32 v188, v188
	v_rcp_f32_e32 v189, v189
	v_add_f32_e32 v180, v180, v181
	v_rcp_f32_e32 v190, v190
	v_rcp_f32_e32 v191, v191
	v_mov_b32_e32 v182, s21
	v_fmac_f32_e32 v182, s20, v180
	v_rsq_f32_e32 v182, v182
	v_pk_mul_f32 v[188:189], v[188:189], v[184:185]
	v_pk_mul_f32 v[190:191], v[190:191], v[186:187]
	v_mov_b32_e32 v183, v182
	v_pk_mul_f32 v[188:189], v[188:189], v[4:5]
	v_pk_mul_f32 v[190:191], v[190:191], v[6:7]
	v_pk_mul_f32 v[64:65], v[64:65], v[182:183]
	v_pk_mul_f32 v[66:67], v[66:67], v[182:183]
	v_pk_mul_f32 v[64:65], v[64:65], v[188:189]
	v_pk_mul_f32 v[66:67], v[66:67], v[190:191]
	v_cvt_pk_bf16_f32 v202, v64, v65
	v_cvt_pk_bf16_f32 v203, v66, v67
	global_store_dwordx2 v2, v[202:203], s[8:9]
	s_add_u32 s8, s8, 0x100000
	s_addc_u32 s9, s9, 0
	s_waitcnt vmcnt(17)
	v_pk_add_f32 v[68:69], v[68:69], v[132:133]
	v_pk_add_f32 v[70:71], v[70:71], v[134:135]
	v_mul_f32_e32 v180, v68, v68
	v_fmac_f32_e32 v180, v69, v69
	v_fmac_f32_e32 v180, v70, v70
	v_fmac_f32_e32 v180, v71, v71
	v_lshlrev_b32_e32 v184, 16, v170
	v_and_b32_e32 v185, 0xffff0000, v170
	v_add_f32_dpp v180, v180, v180 quad_perm:[1,0,3,2] row_mask:0xf bank_mask:0xf
	v_lshlrev_b32_e32 v186, 16, v171
	v_and_b32_e32 v187, 0xffff0000, v171
	v_add_f32_dpp v180, v180, v180 quad_perm:[2,3,0,1] row_mask:0xf bank_mask:0xf
	v_pk_mul_f32 v[188:189], v[184:185], v[8:9]
	v_pk_mul_f32 v[190:191], v[186:187], v[8:9]
	v_add_f32_dpp v180, v180, v180 row_ror:4 row_mask:0xf bank_mask:0xf
	v_exp_f32_e32 v188, v188
	v_exp_f32_e32 v189, v189
	v_add_f32_dpp v180, v180, v180 row_ror:8 row_mask:0xf bank_mask:0xf
	v_exp_f32_e32 v190, v190
	v_exp_f32_e32 v191, v191
	v_mov_b32_e32 v181, v180
	v_pk_add_f32 v[188:189], v[188:189], v[10:11]
	v_pk_add_f32 v[190:191], v[190:191], v[10:11]
	v_permlane16_swap_b32_e32 v180, v181
	v_rcp_f32_e32 v188, v188
	v_rcp_f32_e32 v189, v189
	v_add_f32_e32 v180, v180, v181
	v_rcp_f32_e32 v190, v190
	v_rcp_f32_e32 v191, v191
	v_mov_b32_e32 v182, s21
	v_fmac_f32_e32 v182, s20, v180
	v_rsq_f32_e32 v182, v182
	v_pk_mul_f32 v[188:189], v[188:189], v[184:185]
	v_pk_mul_f32 v[190:191], v[190:191], v[186:187]
	v_mov_b32_e32 v183, v182
	v_pk_mul_f32 v[188:189], v[188:189], v[4:5]
	v_pk_mul_f32 v[190:191], v[190:191], v[6:7]
	v_pk_mul_f32 v[68:69], v[68:69], v[182:183]
	v_pk_mul_f32 v[70:71], v[70:71], v[182:183]
	v_pk_mul_f32 v[68:69], v[68:69], v[188:189]
	v_pk_mul_f32 v[70:71], v[70:71], v[190:191]
	v_cvt_pk_bf16_f32 v204, v68, v69
	v_cvt_pk_bf16_f32 v205, v70, v71
	global_store_dwordx2 v2, v[204:205], s[8:9]
	s_add_u32 s8, s8, 0x100000
	s_addc_u32 s9, s9, 0
	s_waitcnt vmcnt(15)
	v_pk_add_f32 v[72:73], v[72:73], v[136:137]
	v_pk_add_f32 v[74:75], v[74:75], v[138:139]
	v_mul_f32_e32 v180, v72, v72
	v_fmac_f32_e32 v180, v73, v73
	v_fmac_f32_e32 v180, v74, v74
	v_fmac_f32_e32 v180, v75, v75
	v_lshlrev_b32_e32 v184, 16, v172
	v_and_b32_e32 v185, 0xffff0000, v172
	v_add_f32_dpp v180, v180, v180 quad_perm:[1,0,3,2] row_mask:0xf bank_mask:0xf
	v_lshlrev_b32_e32 v186, 16, v173
	v_and_b32_e32 v187, 0xffff0000, v173
	v_add_f32_dpp v180, v180, v180 quad_perm:[2,3,0,1] row_mask:0xf bank_mask:0xf
	v_pk_mul_f32 v[188:189], v[184:185], v[8:9]
	v_pk_mul_f32 v[190:191], v[186:187], v[8:9]
	v_add_f32_dpp v180, v180, v180 row_ror:4 row_mask:0xf bank_mask:0xf
	v_exp_f32_e32 v188, v188
	v_exp_f32_e32 v189, v189
	v_add_f32_dpp v180, v180, v180 row_ror:8 row_mask:0xf bank_mask:0xf
	v_exp_f32_e32 v190, v190
	v_exp_f32_e32 v191, v191
	v_mov_b32_e32 v181, v180
	v_pk_add_f32 v[188:189], v[188:189], v[10:11]
	v_pk_add_f32 v[190:191], v[190:191], v[10:11]
	v_permlane16_swap_b32_e32 v180, v181
	v_rcp_f32_e32 v188, v188
	v_rcp_f32_e32 v189, v189
	v_add_f32_e32 v180, v180, v181
	v_rcp_f32_e32 v190, v190
	v_rcp_f32_e32 v191, v191
	v_mov_b32_e32 v182, s21
	v_fmac_f32_e32 v182, s20, v180
	v_rsq_f32_e32 v182, v182
	v_pk_mul_f32 v[188:189], v[188:189], v[184:185]
	v_pk_mul_f32 v[190:191], v[190:191], v[186:187]
	v_mov_b32_e32 v183, v182
	v_pk_mul_f32 v[188:189], v[188:189], v[4:5]
	v_pk_mul_f32 v[190:191], v[190:191], v[6:7]
	v_pk_mul_f32 v[72:73], v[72:73], v[182:183]
	v_pk_mul_f32 v[74:75], v[74:75], v[182:183]
	v_pk_mul_f32 v[72:73], v[72:73], v[188:189]
	v_pk_mul_f32 v[74:75], v[74:75], v[190:191]
	v_cvt_pk_bf16_f32 v206, v72, v73
	v_cvt_pk_bf16_f32 v207, v74, v75
	global_store_dwordx2 v2, v[206:207], s[8:9]
	s_waitcnt vmcnt(0)
	s_branch .LBB0_2045

.Ltrt_after9:
	ds_write_b32 v1, v10 offset:0
	ds_write_b32 v1, v11 offset:4
	ds_write_b32 v1, v12 offset:8
	ds_write_b32 v1, v13 offset:12
	ds_write_b32 v1, v14 offset:1056
	ds_write_b32 v1, v15 offset:1060
	ds_write_b32 v1, v16 offset:1064
	ds_write_b32 v1, v17 offset:1068
	ds_write_b32 v1, v18 offset:2112
	ds_write_b32 v1, v19 offset:2116
	ds_write_b32 v1, v20 offset:2120
	ds_write_b32 v1, v21 offset:2124
	ds_write_b32 v1, v22 offset:3168
	ds_write_b32 v1, v23 offset:3172
	ds_write_b32 v1, v24 offset:3176
	ds_write_b32 v1, v25 offset:3180
	ds_write_b32 v1, v26 offset:4224
	ds_write_b32 v1, v27 offset:4228
	ds_write_b32 v1, v28 offset:4232
	ds_write_b32 v1, v29 offset:4236
	ds_write_b32 v1, v30 offset:5280
	ds_write_b32 v1, v31 offset:5284
	ds_write_b32 v1, v32 offset:5288
	ds_write_b32 v1, v33 offset:5292
	ds_write_b32 v1, v34 offset:6336
	ds_write_b32 v1, v35 offset:6340
	ds_write_b32 v1, v36 offset:6344
	ds_write_b32 v1, v37 offset:6348
	ds_write_b32 v1, v38 offset:7392
	ds_write_b32 v1, v39 offset:7396
	ds_write_b32 v1, v40 offset:7400
	ds_write_b32 v1, v41 offset:7404
	v_mad_u32_u24 v9, v5, s22, v6
	s_lshl_b32 s46, s22, 3
	s_waitcnt lgkmcnt(0)
	ds_read_b32 v74, v2 offset:0
	ds_read_b32 v75, v2 offset:132
	ds_read_b32 v76, v2 offset:264
	ds_read_b32 v77, v2 offset:396
	ds_read_b32 v78, v2 offset:528
	ds_read_b32 v79, v2 offset:660
	ds_read_b32 v80, v2 offset:792
	ds_read_b32 v81, v2 offset:924
	ds_read_b32 v82, v2 offset:32
	ds_read_b32 v83, v2 offset:164
	ds_read_b32 v84, v2 offset:296
	ds_read_b32 v85, v2 offset:428
	ds_read_b32 v86, v2 offset:560
	ds_read_b32 v87, v2 offset:692
	ds_read_b32 v88, v2 offset:824
	ds_read_b32 v89, v2 offset:956
	s_waitcnt lgkmcnt(8)
	v_cvt_pk_bf16_f32 v106, v74, v75
	v_cvt_pk_bf16_f32 v107, v76, v77
	v_cvt_pk_bf16_f32 v108, v78, v79
	v_cvt_pk_bf16_f32 v109, v80, v81
	global_store_dwordx4 v9, v[106:109], s[18:19] nt
	s_add_u32 s18, s18, s46
	s_addc_u32 s19, s19, 0
	ds_read_b32 v90, v2 offset:64
	ds_read_b32 v91, v2 offset:196
	ds_read_b32 v92, v2 offset:328
	ds_read_b32 v93, v2 offset:460
	ds_read_b32 v94, v2 offset:592
	ds_read_b32 v95, v2 offset:724
	ds_read_b32 v96, v2 offset:856
	ds_read_b32 v97, v2 offset:988
	s_waitcnt lgkmcnt(8)
	v_cvt_pk_bf16_f32 v110, v82, v83
	v_cvt_pk_bf16_f32 v111, v84, v85
	v_cvt_pk_bf16_f32 v112, v86, v87
	v_cvt_pk_bf16_f32 v113, v88, v89
	global_store_dwordx4 v9, v[110:113], s[18:19] nt
	s_add_u32 s18, s18, s46
	s_addc_u32 s19, s19, 0
	ds_read_b32 v98, v2 offset:96
	ds_read_b32 v99, v2 offset:228
	ds_read_b32 v100, v2 offset:360
	ds_read_b32 v101, v2 offset:492
	ds_read_b32 v102, v2 offset:624
	ds_read_b32 v103, v2 offset:756
	ds_read_b32 v104, v2 offset:888
	ds_read_b32 v105, v2 offset:1020
	s_waitcnt lgkmcnt(8)
	v_cvt_pk_bf16_f32 v106, v90, v91
	v_cvt_pk_bf16_f32 v107, v92, v93
	v_cvt_pk_bf16_f32 v108, v94, v95
	v_cvt_pk_bf16_f32 v109, v96, v97
	global_store_dwordx4 v9, v[106:109], s[18:19] nt
	s_add_u32 s18, s18, s46
	s_addc_u32 s19, s19, 0
	s_waitcnt lgkmcnt(0)
	v_cvt_pk_bf16_f32 v110, v98, v99
	v_cvt_pk_bf16_f32 v111, v100, v101
	v_cvt_pk_bf16_f32 v112, v102, v103
	v_cvt_pk_bf16_f32 v113, v104, v105
	global_store_dwordx4 v9, v[110:113], s[18:19] nt
	s_cmp_eq_u32 s24, 0
	s_cbranch_scc1 .Ltrt_done
	s_add_u32 s12, s12, 1024
	s_cmp_lt_u32 s12, 66560
	s_cselect_b32 s24, 1, 0
	s_cbranch_scc0 .Ltrt_nonext17
	s_cmp_ge_u32 s12, 33280
	s_cselect_b32 s41, 1, 0
	s_cselect_b32 s26, 33280, 0
	s_sub_u32 s42, s12, s26
	s_cmp_ge_u32 s42, 12288
	s_cbranch_scc1 .Ltrt_m20
	s_mul_i32 s43, s42, 43691
	s_lshr_b32 s43, s43, 24
	s_mul_i32 s26, s43, 384
	s_sub_u32 s44, s42, s26
	s_mov_b32 s14, s0
	s_mov_b32 s15, s1
	s_mov_b32 s36, 0xc000
	s_mov_b32 s37, 0x6000000
	s_mov_b32 s38, 0x0
	s_mov_b32 s39, 0x3000000
	s_mov_b32 s40, 0x1000
	s_branch .Ltrt_dec_done19
